# lever 1 waitcnt placement: GEMM phases drop the satisfied lgkmcnt(0) that follows each pre-MFMA barrier (36 sites)
# speedup vs baseline: 1.0059x; 1.0059x over previous
; #define PG8_STAGE(bufoff, gbase, voff) do { _Pragma("unroll") for (int _i = 0; _i < 2; ++_i) \
;         __builtin_amdgcn_global_load_lds((const unsigned*)((const char*)(gbase) + (voff)[_i]), (PG8_LAS unsigned*)(lds + (bufoff) + ldsw + _i * 8192), 16, 0, 0); } while (0)
; #define PG8_LDA(dst, b, h) do { _Pragma("unroll") for (int m = 0; m < 4; ++m) _Pragma("unroll") for (int k = 0; k < 2; ++k) dst[m][k] = *(const PG8_LAS bf16x8*)(lds + PG8_SA(b, h) + aoff + m * 2048 + k * 1024); } while (0)
; #define PG8_LDB(dst, b, h) do { _Pragma("unroll") for (int n = 0; n < 2; ++n) _Pragma("unroll") for (int k = 0; k < 2; ++k) dst[n][k] = *(const PG8_LAS bf16x8*)(lds + PG8_SB(b, h) + boff + n * 2048 + k * 1024); } while (0)
; #define PG8_MMA(ai, bj, At, Bt) do { __builtin_amdgcn_s_setprio(1); _Pragma("unroll") for (int m = 0; m < 4; ++m) _Pragma("unroll") for (int n = 0; n < 2; ++n) _Pragma("unroll") for (int k = 0; k < 2; ++k) \
;         acc[ai][bj][m][n] = __builtin_amdgcn_mfma_f32_16x16x32_bf16(Bt[n][k], At[m][k], acc[ai][bj][m][n], 0, 0, 0); __builtin_amdgcn_s_setprio(0); } while (0)
; #define PG8_WAIT_V(n) asm volatile("s_waitcnt vmcnt(" #n ")" ::: "memory")
; #define PG8_WAIT_L(n) asm volatile("s_waitcnt lgkmcnt(" #n ")" ::: "memory")
; #define PG8_BAR __builtin_amdgcn_s_barrier()
; #define PG8_SCHED __builtin_amdgcn_sched_barrier(0)
; template <class Epi, class Sched, bool ALIGN_EPI = false, bool SP2 = false>
; __device__ __forceinline__ void gemm_phase(PG8_LAS unsigned char* lds, const Gemm g, const Sched& S, const Epi& E) {
;     ...
;             PG8_LDB(B0, 0, 0); PG8_LDB(B1, 0, 1); PG8_SCHED; PG8_LDA(At, 0, 0); PG8_STAGE(PG8_SA(1, 1), a1 + hstepA, voffA);
;             PG8_WAIT_V(8); PG8_WAIT_L(0); PG8_BAR; PG8_MMA(0, 0, At, B0); PG8_MMA(0, 1, At, B1); PG8_BAR; PG8_SCHED;
;             PG8_LDA(At, 0, 1); PG8_STAGE(PG8_SB(0, 0), b2, voffB); PG8_STAGE(PG8_SB(0, 1), b2 + hstepB, voffB); PG8_STAGE(PG8_SA(0, 0), a2, voffA);
;             PG8_WAIT_V(8); PG8_WAIT_L(0); PG8_BAR; PG8_MMA(1, 0, At, B0); PG8_MMA(1, 1, At, B1); PG8_BAR; PG8_SCHED;
.LBB0_135:
	s_add_u32 s22, s20, 0xfffc0080
	s_addc_u32 s23, s21, -1
	s_add_i32 s28, 0, 0x10000
	s_cmp_eq_u32 s53, 12
	s_cselect_b32 s25, s12, s23
	s_cselect_b32 s24, s14, s22
	v_add_u32_e32 v138, s28, v141
	s_cselect_b32 s23, s15, s45
	s_cselect_b32 s22, s38, s43
	s_add_i32 s29, 0, 0x14000
	ds_read_b128 v[144:147], v138
	ds_read_b128 v[148:151], v138 offset:1024
	ds_read_b128 v[152:155], v138 offset:2048
	ds_read_b128 v[156:159], v138 offset:3072
	v_add_u32_e32 v138, s29, v141
	ds_read_b128 v[160:163], v138
	ds_read_b128 v[164:167], v138 offset:1024
	ds_read_b128 v[168:171], v138 offset:2048
	ds_read_b128 v[172:175], v138 offset:3072
	s_add_i32 m0, s26, 0xc000
	ds_read_b128 v[176:179], v143
	ds_read_b128 v[180:183], v143 offset:1024
	ds_read_b128 v[184:187], v143 offset:2048
	ds_read_b128 v[188:191], v143 offset:3072
	ds_read_b128 v[192:195], v143 offset:4096
	ds_read_b128 v[196:199], v143 offset:5120
	ds_read_b128 v[200:203], v143 offset:6144
	ds_read_b128 v[204:207], v143 offset:7168
	global_load_lds_dwordx4 v134, s[20:21]
	s_add_i32 m0, s26, 0xe000
	s_nop 0
	global_load_lds_dwordx4 v136, s[20:21]
	s_waitcnt vmcnt(8)
	s_waitcnt lgkmcnt(0)
	s_barrier
	v_mfma_f32_16x16x32_bf16 v[124:127], v[144:147], v[176:179], v[124:127]
	v_mfma_f32_16x16x32_bf16 v[120:123], v[152:155], v[176:179], v[120:123]
	v_mfma_f32_16x16x32_bf16 v[108:111], v[144:147], v[184:187], v[108:111]
	v_mfma_f32_16x16x32_bf16 v[104:107], v[152:155], v[184:187], v[104:107]
	v_mfma_f32_16x16x32_bf16 v[92:95], v[144:147], v[192:195], v[92:95]
	v_mfma_f32_16x16x32_bf16 v[88:91], v[152:155], v[192:195], v[88:91]
	v_mfma_f32_16x16x32_bf16 v[76:79], v[144:147], v[200:203], v[76:79]
	v_mfma_f32_16x16x32_bf16 v[72:75], v[152:155], v[200:203], v[72:75]
	v_mfma_f32_16x16x32_bf16 v[124:127], v[148:151], v[180:183], v[124:127]
	v_mfma_f32_16x16x32_bf16 v[120:123], v[156:159], v[180:183], v[120:123]
	v_mfma_f32_16x16x32_bf16 v[108:111], v[148:151], v[188:191], v[108:111]
	v_mfma_f32_16x16x32_bf16 v[104:107], v[156:159], v[188:191], v[104:107]
	v_mfma_f32_16x16x32_bf16 v[92:95], v[148:151], v[196:199], v[92:95]
	v_mfma_f32_16x16x32_bf16 v[88:91], v[156:159], v[196:199], v[88:91]
	v_mfma_f32_16x16x32_bf16 v[76:79], v[148:151], v[204:207], v[76:79]
	v_mfma_f32_16x16x32_bf16 v[72:75], v[156:159], v[204:207], v[72:75]
	v_mfma_f32_16x16x32_bf16 v[116:119], v[160:163], v[176:179], v[116:119]
	v_mfma_f32_16x16x32_bf16 v[112:115], v[168:171], v[176:179], v[112:115]
	v_mfma_f32_16x16x32_bf16 v[100:103], v[160:163], v[184:187], v[100:103]
	v_mfma_f32_16x16x32_bf16 v[96:99], v[168:171], v[184:187], v[96:99]
	v_mfma_f32_16x16x32_bf16 v[84:87], v[160:163], v[192:195], v[84:87]
	v_mfma_f32_16x16x32_bf16 v[80:83], v[168:171], v[192:195], v[80:83]
	v_mfma_f32_16x16x32_bf16 v[68:71], v[160:163], v[200:203], v[68:71]
	v_mfma_f32_16x16x32_bf16 v[64:67], v[168:171], v[200:203], v[64:67]
	v_mfma_f32_16x16x32_bf16 v[116:119], v[164:167], v[180:183], v[116:119]
	v_mfma_f32_16x16x32_bf16 v[112:115], v[172:175], v[180:183], v[112:115]
	v_mfma_f32_16x16x32_bf16 v[100:103], v[164:167], v[188:191], v[100:103]
	v_mfma_f32_16x16x32_bf16 v[96:99], v[172:175], v[188:191], v[96:99]
	v_mfma_f32_16x16x32_bf16 v[84:87], v[164:167], v[196:199], v[84:87]
	v_mfma_f32_16x16x32_bf16 v[80:83], v[172:175], v[196:199], v[80:83]
	v_mfma_f32_16x16x32_bf16 v[68:71], v[164:167], v[204:207], v[68:71]
	v_mfma_f32_16x16x32_bf16 v[64:67], v[172:175], v[204:207], v[64:67]
	s_barrier
	s_add_i32 s28, s28, s18
	v_lshl_add_u64 v[138:139], s[22:23], 0, v[208:209]
	s_mov_b32 m0, s28
	ds_read_b128 v[176:179], v143 offset:16384
	ds_read_b128 v[180:183], v143 offset:17408
	ds_read_b128 v[184:187], v143 offset:18432
	ds_read_b128 v[188:191], v143 offset:19456
	ds_read_b128 v[192:195], v143 offset:20480
	ds_read_b128 v[196:199], v143 offset:21504
	ds_read_b128 v[200:203], v143 offset:22528
	ds_read_b128 v[204:207], v143 offset:23552
	global_load_lds_dwordx4 v208, s[22:23]
	s_add_i32 m0, s28, 0x2000
	s_add_u32 s54, s22, 0x40000
	v_lshl_add_u64 v[210:211], s[22:23], 0, v[128:129]
	s_addc_u32 s55, s23, 0
	s_add_i32 s28, s29, s18
	global_load_lds_dwordx4 v128, s[22:23]
	s_mov_b32 m0, s28
	v_lshl_add_u64 v[222:223], s[24:25], 0, v[130:131]
	global_load_lds_dwordx4 v208, s[54:55]
	s_add_i32 m0, s28, 0x2000
	s_nop 0
	global_load_lds_dwordx4 v128, s[54:55]
	v_lshl_add_u64 v[212:213], s[24:25], 0, v[132:133]
	s_mov_b32 m0, s26
	s_nop 0
	global_load_lds_dwordx4 v132, s[24:25]
	s_mov_b32 m0, s34
	s_nop 0
	global_load_lds_dwordx4 v130, s[24:25]
	s_waitcnt vmcnt(8)
	s_waitcnt lgkmcnt(0)
	s_barrier
; #define PG8_STAGE(bufoff, gbase, voff) do { _Pragma("unroll") for (int _i = 0; _i < 2; ++_i) \
;         __builtin_amdgcn_global_load_lds((const unsigned*)((const char*)(gbase) + (voff)[_i]), (PG8_LAS unsigned*)(lds + (bufoff) + ldsw + _i * 8192), 16, 0, 0); } while (0)
; #define PG8_LDA(dst, b, h) do { _Pragma("unroll") for (int m = 0; m < 4; ++m) _Pragma("unroll") for (int k = 0; k < 2; ++k) dst[m][k] = *(const PG8_LAS bf16x8*)(lds + PG8_SA(b, h) + aoff + m * 2048 + k * 1024); } while (0)
; #define PG8_LDB(dst, b, h) do { _Pragma("unroll") for (int n = 0; n < 2; ++n) _Pragma("unroll") for (int k = 0; k < 2; ++k) dst[n][k] = *(const PG8_LAS bf16x8*)(lds + PG8_SB(b, h) + boff + n * 2048 + k * 1024); } while (0)
; #define PG8_MMA(ai, bj, At, Bt) do { __builtin_amdgcn_s_setprio(1); _Pragma("unroll") for (int m = 0; m < 4; ++m) _Pragma("unroll") for (int n = 0; n < 2; ++n) _Pragma("unroll") for (int k = 0; k < 2; ++k) \
;         acc[ai][bj][m][n] = __builtin_amdgcn_mfma_f32_16x16x32_bf16(Bt[n][k], At[m][k], acc[ai][bj][m][n], 0, 0, 0); __builtin_amdgcn_s_setprio(0); } while (0)
; #define PG8_WAIT_V(n) asm volatile("s_waitcnt vmcnt(" #n ")" ::: "memory")
; #define PG8_WAIT_L(n) asm volatile("s_waitcnt lgkmcnt(" #n ")" ::: "memory")
; #define PG8_BAR __builtin_amdgcn_s_barrier()
; #define PG8_SCHED __builtin_amdgcn_sched_barrier(0)
; template <class Epi, class Sched, bool ALIGN_EPI = false, bool SP2 = false>
; __device__ __forceinline__ void gemm_phase(PG8_LAS unsigned char* lds, const Gemm g, const Sched& S, const Epi& E) {
;     ...
;             PG8_WAIT_V(8); PG8_WAIT_L(0); PG8_BAR; PG8_MMA(1, 0, At, B0); PG8_MMA(1, 1, At, B1); PG8_BAR; PG8_SCHED;
;             PG8_LDB(B0, 1, 0); PG8_LDB(B1, 1, 1); PG8_SCHED; PG8_LDA(At, 1, 0); PG8_STAGE(PG8_SA(0, 1), a2 + hstepA, voffA);
;             PG8_WAIT_V(8); PG8_WAIT_L(0); PG8_BAR; PG8_MMA(0, 0, At, B0); PG8_MMA(0, 1, At, B1); PG8_BAR; PG8_SCHED;
;             PG8_LDA(At, 1, 1); PG8_STAGE(PG8_SB(1, 0), b3, voffB); PG8_STAGE(PG8_SB(1, 1), b3 + hstepB, voffB); PG8_STAGE(PG8_SA(1, 0), a3, voffA);
;             PG8_WAIT_V(8); PG8_WAIT_L(0); PG8_BAR; PG8_MMA(1, 0, At, B0); PG8_MMA(1, 1, At, B1); PG8_BAR; PG8_SCHED;
	v_mfma_f32_16x16x32_bf16 v[60:63], v[144:147], v[176:179], v[60:63]
	v_mfma_f32_16x16x32_bf16 v[56:59], v[152:155], v[176:179], v[56:59]
	v_mfma_f32_16x16x32_bf16 v[44:47], v[144:147], v[184:187], v[44:47]
	v_mfma_f32_16x16x32_bf16 v[40:43], v[152:155], v[184:187], v[40:43]
	v_mfma_f32_16x16x32_bf16 v[28:31], v[144:147], v[192:195], v[28:31]
	v_mfma_f32_16x16x32_bf16 v[24:27], v[152:155], v[192:195], v[24:27]
	v_mfma_f32_16x16x32_bf16 v[12:15], v[144:147], v[200:203], v[12:15]
	v_mfma_f32_16x16x32_bf16 v[8:11], v[152:155], v[200:203], v[8:11]
	v_mfma_f32_16x16x32_bf16 v[60:63], v[148:151], v[180:183], v[60:63]
	v_mfma_f32_16x16x32_bf16 v[56:59], v[156:159], v[180:183], v[56:59]
	v_mfma_f32_16x16x32_bf16 v[44:47], v[148:151], v[188:191], v[44:47]
	v_mfma_f32_16x16x32_bf16 v[40:43], v[156:159], v[188:191], v[40:43]
	v_mfma_f32_16x16x32_bf16 v[28:31], v[148:151], v[196:199], v[28:31]
	v_mfma_f32_16x16x32_bf16 v[24:27], v[156:159], v[196:199], v[24:27]
	v_mfma_f32_16x16x32_bf16 v[12:15], v[148:151], v[204:207], v[12:15]
	v_mfma_f32_16x16x32_bf16 v[8:11], v[156:159], v[204:207], v[8:11]
	v_mfma_f32_16x16x32_bf16 v[52:55], v[160:163], v[176:179], v[52:55]
	v_mfma_f32_16x16x32_bf16 v[48:51], v[168:171], v[176:179], v[48:51]
	v_mfma_f32_16x16x32_bf16 v[36:39], v[160:163], v[184:187], v[36:39]
	v_mfma_f32_16x16x32_bf16 v[32:35], v[168:171], v[184:187], v[32:35]
	v_mfma_f32_16x16x32_bf16 v[20:23], v[160:163], v[192:195], v[20:23]
	v_mfma_f32_16x16x32_bf16 v[16:19], v[168:171], v[192:195], v[16:19]
	v_mfma_f32_16x16x32_bf16 v[4:7], v[160:163], v[200:203], v[4:7]
	v_mfma_f32_16x16x32_bf16 v[0:3], v[168:171], v[200:203], v[0:3]
	v_mfma_f32_16x16x32_bf16 v[52:55], v[164:167], v[180:183], v[52:55]
	v_mfma_f32_16x16x32_bf16 v[48:51], v[172:175], v[180:183], v[48:51]
	v_mfma_f32_16x16x32_bf16 v[36:39], v[164:167], v[188:191], v[36:39]
	v_mfma_f32_16x16x32_bf16 v[32:35], v[172:175], v[188:191], v[32:35]
	v_mfma_f32_16x16x32_bf16 v[20:23], v[164:167], v[196:199], v[20:23]
	v_mfma_f32_16x16x32_bf16 v[16:19], v[172:175], v[196:199], v[16:19]
	v_mfma_f32_16x16x32_bf16 v[4:7], v[164:167], v[204:207], v[4:7]
	v_mfma_f32_16x16x32_bf16 v[0:3], v[172:175], v[204:207], v[0:3]
	s_barrier
	s_add_i32 s28, 0, 0x18000
	s_add_i32 s29, 0, 0x1c000
	v_add_u32_e32 v156, s28, v141
	v_add_u32_e32 v172, s29, v141
	ds_read_b128 v[144:147], v156
	ds_read_b128 v[148:151], v156 offset:1024
	ds_read_b128 v[152:155], v156 offset:2048
	ds_read_b128 v[156:159], v156 offset:3072
	ds_read_b128 v[160:163], v172
	ds_read_b128 v[164:167], v172 offset:1024
	ds_read_b128 v[168:171], v172 offset:2048
	ds_read_b128 v[172:175], v172 offset:3072
	s_add_u32 s24, s24, 0x40000
	s_addc_u32 s25, s25, 0
	s_mov_b32 m0, s35
	ds_read_b128 v[176:179], v143 offset:32768
	ds_read_b128 v[180:183], v143 offset:33792
	ds_read_b128 v[184:187], v143 offset:34816
	ds_read_b128 v[188:191], v143 offset:35840
	ds_read_b128 v[192:195], v143 offset:36864
	ds_read_b128 v[196:199], v143 offset:37888
	ds_read_b128 v[200:203], v143 offset:38912
	ds_read_b128 v[204:207], v143 offset:39936
	global_load_lds_dwordx4 v132, s[24:25]
	v_lshl_add_u64 v[224:225], s[24:25], 0, v[130:131]
	s_mov_b32 m0, s39
	s_nop 0
	global_load_lds_dwordx4 v130, s[24:25]
	s_waitcnt vmcnt(8)
	s_waitcnt lgkmcnt(0)
	s_barrier
	v_mfma_f32_16x16x32_bf16 v[124:127], v[144:147], v[176:179], v[124:127]
	v_mfma_f32_16x16x32_bf16 v[120:123], v[152:155], v[176:179], v[120:123]
	v_mfma_f32_16x16x32_bf16 v[108:111], v[144:147], v[184:187], v[108:111]
	v_mfma_f32_16x16x32_bf16 v[104:107], v[152:155], v[184:187], v[104:107]
	v_mfma_f32_16x16x32_bf16 v[92:95], v[144:147], v[192:195], v[92:95]
	v_mfma_f32_16x16x32_bf16 v[88:91], v[152:155], v[192:195], v[88:91]
	v_mfma_f32_16x16x32_bf16 v[76:79], v[144:147], v[200:203], v[76:79]
	v_mfma_f32_16x16x32_bf16 v[72:75], v[152:155], v[200:203], v[72:75]
	v_mfma_f32_16x16x32_bf16 v[124:127], v[148:151], v[180:183], v[124:127]
	v_mfma_f32_16x16x32_bf16 v[120:123], v[156:159], v[180:183], v[120:123]
	v_mfma_f32_16x16x32_bf16 v[108:111], v[148:151], v[188:191], v[108:111]
	v_mfma_f32_16x16x32_bf16 v[104:107], v[156:159], v[188:191], v[104:107]
	v_mfma_f32_16x16x32_bf16 v[92:95], v[148:151], v[196:199], v[92:95]
	v_mfma_f32_16x16x32_bf16 v[88:91], v[156:159], v[196:199], v[88:91]
	v_mfma_f32_16x16x32_bf16 v[76:79], v[148:151], v[204:207], v[76:79]
	v_mfma_f32_16x16x32_bf16 v[72:75], v[156:159], v[204:207], v[72:75]
	v_mfma_f32_16x16x32_bf16 v[116:119], v[160:163], v[176:179], v[116:119]
	v_mfma_f32_16x16x32_bf16 v[112:115], v[168:171], v[176:179], v[112:115]
	v_mfma_f32_16x16x32_bf16 v[100:103], v[160:163], v[184:187], v[100:103]
	v_mfma_f32_16x16x32_bf16 v[96:99], v[168:171], v[184:187], v[96:99]
	v_mfma_f32_16x16x32_bf16 v[84:87], v[160:163], v[192:195], v[84:87]
	v_mfma_f32_16x16x32_bf16 v[80:83], v[168:171], v[192:195], v[80:83]
	v_mfma_f32_16x16x32_bf16 v[68:71], v[160:163], v[200:203], v[68:71]
	v_mfma_f32_16x16x32_bf16 v[64:67], v[168:171], v[200:203], v[64:67]
	v_mfma_f32_16x16x32_bf16 v[116:119], v[164:167], v[180:183], v[116:119]
	v_mfma_f32_16x16x32_bf16 v[112:115], v[172:175], v[180:183], v[112:115]
	v_mfma_f32_16x16x32_bf16 v[100:103], v[164:167], v[188:191], v[100:103]
	v_mfma_f32_16x16x32_bf16 v[96:99], v[172:175], v[188:191], v[96:99]
	v_mfma_f32_16x16x32_bf16 v[84:87], v[164:167], v[196:199], v[84:87]
	v_mfma_f32_16x16x32_bf16 v[80:83], v[172:175], v[196:199], v[80:83]
	v_mfma_f32_16x16x32_bf16 v[68:71], v[164:167], v[204:207], v[68:71]
	v_mfma_f32_16x16x32_bf16 v[64:67], v[172:175], v[204:207], v[64:67]
	s_barrier
; #define PG8_STAGE(bufoff, gbase, voff) do { _Pragma("unroll") for (int _i = 0; _i < 2; ++_i) \
;         __builtin_amdgcn_global_load_lds((const unsigned*)((const char*)(gbase) + (voff)[_i]), (PG8_LAS unsigned*)(lds + (bufoff) + ldsw + _i * 8192), 16, 0, 0); } while (0)
; #define PG8_LDA(dst, b, h) do { _Pragma("unroll") for (int m = 0; m < 4; ++m) _Pragma("unroll") for (int k = 0; k < 2; ++k) dst[m][k] = *(const PG8_LAS bf16x8*)(lds + PG8_SA(b, h) + aoff + m * 2048 + k * 1024); } while (0)
; #define PG8_MMA(ai, bj, At, Bt) do { __builtin_amdgcn_s_setprio(1); _Pragma("unroll") for (int m = 0; m < 4; ++m) _Pragma("unroll") for (int n = 0; n < 2; ++n) _Pragma("unroll") for (int k = 0; k < 2; ++k) \
;         acc[ai][bj][m][n] = __builtin_amdgcn_mfma_f32_16x16x32_bf16(Bt[n][k], At[m][k], acc[ai][bj][m][n], 0, 0, 0); __builtin_amdgcn_s_setprio(0); } while (0)
; #define PG8_WAIT_V(n) asm volatile("s_waitcnt vmcnt(" #n ")" ::: "memory")
; #define PG8_WAIT_L(n) asm volatile("s_waitcnt lgkmcnt(" #n ")" ::: "memory")
; #define PG8_BAR __builtin_amdgcn_s_barrier()
; #define PG8_SCHED __builtin_amdgcn_sched_barrier(0)
; template <class Epi, class Sched, bool ALIGN_EPI = false, bool SP2 = false>
; __device__ __forceinline__ void gemm_phase(PG8_LAS unsigned char* lds, const Gemm g, const Sched& S, const Epi& E) {
;     ...
;             PG8_LDA(At, 1, 1); PG8_STAGE(PG8_SB(1, 0), b3, voffB); PG8_STAGE(PG8_SB(1, 1), b3 + hstepB, voffB); PG8_STAGE(PG8_SA(1, 0), a3, voffA);
;             PG8_WAIT_V(8); PG8_WAIT_L(0); PG8_BAR; PG8_MMA(1, 0, At, B0); PG8_MMA(1, 1, At, B1); PG8_BAR; PG8_SCHED;
;     ...
;         if constexpr (ALIGN_EPI) { if (wr == 0) PG8_BAR; }
	s_add_i32 s24, s28, s18
	v_lshl_add_u64 v[138:139], v[138:139], 0, s[10:11]
	s_mov_b32 m0, s24
	ds_read_b128 v[176:179], v143 offset:49152
	ds_read_b128 v[180:183], v143 offset:50176
	ds_read_b128 v[184:187], v143 offset:51200
	ds_read_b128 v[188:191], v143 offset:52224
	ds_read_b128 v[192:195], v143 offset:53248
	ds_read_b128 v[196:199], v143 offset:54272
	ds_read_b128 v[200:203], v143 offset:55296
	ds_read_b128 v[204:207], v143 offset:56320
	global_load_lds_dwordx4 v[138:139], off
	s_add_i32 m0, s24, 0x2000
	s_add_u32 s22, s22, 0x40080
	v_lshl_add_u64 v[138:139], v[210:211], 0, s[10:11]
	s_addc_u32 s23, s23, 0
	s_add_i32 s24, s29, s18
	global_load_lds_dwordx4 v[138:139], off
	s_mov_b32 m0, s24
	s_nop 0
	global_load_lds_dwordx4 v208, s[22:23]
	s_add_i32 m0, s24, 0x2000
	s_nop 0
	global_load_lds_dwordx4 v128, s[22:23]
	v_lshl_add_u64 v[138:139], v[212:213], 0, s[10:11]
	s_mov_b32 m0, s50
	s_nop 0
	global_load_lds_dwordx4 v[138:139], off
	v_lshl_add_u64 v[138:139], v[222:223], 0, s[10:11]
	s_mov_b32 m0, s51
	s_nop 0
	global_load_lds_dwordx4 v[138:139], off
	s_waitcnt vmcnt(8)
	s_waitcnt lgkmcnt(0)
	s_barrier
	v_mfma_f32_16x16x32_bf16 v[60:63], v[144:147], v[176:179], v[60:63]
	v_mfma_f32_16x16x32_bf16 v[56:59], v[152:155], v[176:179], v[56:59]
	v_mfma_f32_16x16x32_bf16 v[44:47], v[144:147], v[184:187], v[44:47]
	v_mfma_f32_16x16x32_bf16 v[40:43], v[152:155], v[184:187], v[40:43]
	v_mfma_f32_16x16x32_bf16 v[28:31], v[144:147], v[192:195], v[28:31]
	v_mfma_f32_16x16x32_bf16 v[24:27], v[152:155], v[192:195], v[24:27]
	v_mfma_f32_16x16x32_bf16 v[12:15], v[144:147], v[200:203], v[12:15]
	v_mfma_f32_16x16x32_bf16 v[8:11], v[152:155], v[200:203], v[8:11]
	v_mfma_f32_16x16x32_bf16 v[60:63], v[148:151], v[180:183], v[60:63]
	v_mfma_f32_16x16x32_bf16 v[56:59], v[156:159], v[180:183], v[56:59]
	v_mfma_f32_16x16x32_bf16 v[44:47], v[148:151], v[188:191], v[44:47]
	v_mfma_f32_16x16x32_bf16 v[40:43], v[156:159], v[188:191], v[40:43]
	v_mfma_f32_16x16x32_bf16 v[28:31], v[148:151], v[196:199], v[28:31]
	v_mfma_f32_16x16x32_bf16 v[24:27], v[156:159], v[196:199], v[24:27]
	v_mfma_f32_16x16x32_bf16 v[12:15], v[148:151], v[204:207], v[12:15]
	v_mfma_f32_16x16x32_bf16 v[8:11], v[156:159], v[204:207], v[8:11]
	v_mfma_f32_16x16x32_bf16 v[52:55], v[160:163], v[176:179], v[52:55]
	v_mfma_f32_16x16x32_bf16 v[48:51], v[168:171], v[176:179], v[48:51]
	v_mfma_f32_16x16x32_bf16 v[36:39], v[160:163], v[184:187], v[36:39]
	v_mfma_f32_16x16x32_bf16 v[32:35], v[168:171], v[184:187], v[32:35]
	v_mfma_f32_16x16x32_bf16 v[20:23], v[160:163], v[192:195], v[20:23]
	v_mfma_f32_16x16x32_bf16 v[16:19], v[168:171], v[192:195], v[16:19]
	v_mfma_f32_16x16x32_bf16 v[4:7], v[160:163], v[200:203], v[4:7]
	v_mfma_f32_16x16x32_bf16 v[0:3], v[168:171], v[200:203], v[0:3]
	v_mfma_f32_16x16x32_bf16 v[52:55], v[164:167], v[180:183], v[52:55]
	v_mfma_f32_16x16x32_bf16 v[48:51], v[172:175], v[180:183], v[48:51]
	v_mfma_f32_16x16x32_bf16 v[36:39], v[164:167], v[188:191], v[36:39]
	v_mfma_f32_16x16x32_bf16 v[32:35], v[172:175], v[188:191], v[32:35]
	v_mfma_f32_16x16x32_bf16 v[20:23], v[164:167], v[196:199], v[20:23]
	v_mfma_f32_16x16x32_bf16 v[16:19], v[172:175], v[196:199], v[16:19]
	v_mfma_f32_16x16x32_bf16 v[4:7], v[164:167], v[204:207], v[4:7]
	v_mfma_f32_16x16x32_bf16 v[0:3], v[172:175], v[204:207], v[0:3]
	s_barrier
	s_add_i32 s53, s53, 2
	s_add_u32 s20, s20, 0x100
	s_addc_u32 s21, s21, 0
	s_add_u32 s43, s43, 0x100
	s_addc_u32 s45, s45, 0
	s_cmp_gt_u32 s53, 13
	s_cbranch_scc0 .LBB0_135
	s_and_b64 vcc, exec, s[6:7]
	s_cbranch_vccz .LBB0_138
	s_barrier

; #define PG8_STAGE(bufoff, gbase, voff) do { _Pragma("unroll") for (int _i = 0; _i < 2; ++_i) \
;         __builtin_amdgcn_global_load_lds((const unsigned*)((const char*)(gbase) + (voff)[_i]), (PG8_LAS unsigned*)(lds + (bufoff) + ldsw + _i * 8192), 16, 0, 0); } while (0)
; #define PG8_LDA(dst, b, h) do { _Pragma("unroll") for (int m = 0; m < 4; ++m) _Pragma("unroll") for (int k = 0; k < 2; ++k) dst[m][k] = *(const PG8_LAS bf16x8*)(lds + PG8_SA(b, h) + aoff + m * 2048 + k * 1024); } while (0)
; #define PG8_LDB(dst, b, h) do { _Pragma("unroll") for (int n = 0; n < 2; ++n) _Pragma("unroll") for (int k = 0; k < 2; ++k) dst[n][k] = *(const PG8_LAS bf16x8*)(lds + PG8_SB(b, h) + boff + n * 2048 + k * 1024); } while (0)
; #define PG8_WAIT_V(n) asm volatile("s_waitcnt vmcnt(" #n ")" ::: "memory")
; #define PG8_WAIT_L(n) asm volatile("s_waitcnt lgkmcnt(" #n ")" ::: "memory")
; #define PG8_BAR __builtin_amdgcn_s_barrier()
; #define PG8_SCHED __builtin_amdgcn_sched_barrier(0)
; template <class Epi, class Sched, bool ALIGN_EPI = false, bool SP2 = false>
; __device__ __forceinline__ void gemm_phase(PG8_LAS unsigned char* lds, const Gemm g, const Sched& S, const Epi& E) {
;     ...
;         const char* nA = has_next ? (const char*)g.A + (size_t)nxt.pm * tstepA : cA; const char* nB = has_next ? (const char*)g.Bt + (size_t)nxt.pn * tstepB : cB;
;         for (int t = 0; t < nt; t += 2) {
;             const bool last = (t == nt - 2);
;             const char* a1 = cA + (size_t)(t + 1) * kstep;
;             const char* a2 = last ? nA : cA + (size_t)(t + 2) * kstep; const char* b2 = last ? nB : cB + (size_t)(t + 2) * kstep;
;             const char* a3 = a2 + kstep; const char* b3 = b2 + kstep;
;             if (last && has_next) S.a_ready(nxt);
;             if constexpr (SP2) {
;             PG8_LDB(B0, 0, 0); PG8_LDB(B1, 0, 1); PG8_SCHED; PG8_LDA(At, 0, 0); PG8_STAGE(PG8_SA(1, 1), a1 + hstepA, voffA);
;             PG8_WAIT_V(8); PG8_WAIT_L(0); PG8_BAR; PG8_MMA(0, 0, At, B0); PG8_MMA(0, 1, At, B1); PG8_BAR; PG8_SCHED;
;             PG8_LDA(At, 0, 1); PG8_STAGE(PG8_SB(0, 0), b2, voffB); PG8_STAGE(PG8_SB(0, 1), b2 + hstepB, voffB); PG8_STAGE(PG8_SA(0, 0), a2, voffA);
;             PG8_WAIT_V(8); PG8_WAIT_L(0); PG8_BAR; PG8_MMA(1, 0, At, B0); PG8_MMA(1, 1, At, B1); PG8_BAR; PG8_SCHED;
.LBB0_215:
	s_add_u32 s20, s0, 0x100
	s_addc_u32 s21, s1, 0
	s_add_i32 s28, 0, 0x10000
	s_cmp_eq_u32 s51, 40
	s_cselect_b32 s25, s5, s21
	s_cselect_b32 s24, s4, s20
	v_add_u32_e32 v138, s28, v141
	s_cselect_b32 s23, s45, s15
	s_cselect_b32 s22, s44, s14
	s_add_i32 s29, 0, 0x14000
	ds_read_b128 v[134:137], v138
	ds_read_b128 v[144:147], v138 offset:1024
	ds_read_b128 v[148:151], v138 offset:2048
	ds_read_b128 v[152:155], v138 offset:3072
	v_add_u32_e32 v138, s29, v141
	ds_read_b128 v[156:159], v138
	ds_read_b128 v[160:163], v138 offset:1024
	ds_read_b128 v[164:167], v138 offset:2048
	ds_read_b128 v[168:171], v138 offset:3072
	v_lshl_add_u64 v[138:139], s[0:1], 0, v[130:131]
	s_add_i32 m0, s26, 0xc000
	ds_read_b128 v[172:175], v143
	ds_read_b128 v[176:179], v143 offset:1024
	ds_read_b128 v[180:183], v143 offset:2048
	ds_read_b128 v[184:187], v143 offset:3072
	ds_read_b128 v[188:191], v143 offset:4096
	ds_read_b128 v[192:195], v143 offset:5120
	ds_read_b128 v[196:199], v143 offset:6144
	ds_read_b128 v[200:203], v143 offset:7168
	global_load_lds_dwordx4 v[138:139], off
	v_lshl_add_u64 v[138:139], s[0:1], 0, v[132:133]
	s_add_i32 m0, s26, 0xe000
	s_nop 0
	global_load_lds_dwordx4 v[138:139], off
	s_waitcnt vmcnt(8)
	s_waitcnt lgkmcnt(0)
	s_barrier
	v_mfma_f32_16x16x32_bf16 v[124:127], v[134:137], v[172:175], v[124:127]
	v_mfma_f32_16x16x32_bf16 v[120:123], v[148:151], v[172:175], v[120:123]
	v_mfma_f32_16x16x32_bf16 v[116:119], v[134:137], v[180:183], v[116:119]
	v_mfma_f32_16x16x32_bf16 v[112:115], v[148:151], v[180:183], v[112:115]
	v_mfma_f32_16x16x32_bf16 v[108:111], v[134:137], v[188:191], v[108:111]
	v_mfma_f32_16x16x32_bf16 v[100:103], v[148:151], v[188:191], v[100:103]
	v_mfma_f32_16x16x32_bf16 v[92:95], v[134:137], v[196:199], v[92:95]
	v_mfma_f32_16x16x32_bf16 v[80:83], v[148:151], v[196:199], v[80:83]
	v_mfma_f32_16x16x32_bf16 v[124:127], v[144:147], v[176:179], v[124:127]
	v_mfma_f32_16x16x32_bf16 v[120:123], v[152:155], v[176:179], v[120:123]
	v_mfma_f32_16x16x32_bf16 v[116:119], v[144:147], v[184:187], v[116:119]
	v_mfma_f32_16x16x32_bf16 v[112:115], v[152:155], v[184:187], v[112:115]
	v_mfma_f32_16x16x32_bf16 v[108:111], v[144:147], v[192:195], v[108:111]
	v_mfma_f32_16x16x32_bf16 v[100:103], v[152:155], v[192:195], v[100:103]
	v_mfma_f32_16x16x32_bf16 v[92:95], v[144:147], v[200:203], v[92:95]
	v_mfma_f32_16x16x32_bf16 v[80:83], v[152:155], v[200:203], v[80:83]
	v_mfma_f32_16x16x32_bf16 v[104:107], v[156:159], v[172:175], v[104:107]
	v_mfma_f32_16x16x32_bf16 v[96:99], v[164:167], v[172:175], v[96:99]
	v_mfma_f32_16x16x32_bf16 v[88:91], v[156:159], v[180:183], v[88:91]
	v_mfma_f32_16x16x32_bf16 v[84:87], v[164:167], v[180:183], v[84:87]
	v_mfma_f32_16x16x32_bf16 v[76:79], v[156:159], v[188:191], v[76:79]
	v_mfma_f32_16x16x32_bf16 v[72:75], v[164:167], v[188:191], v[72:75]
	v_mfma_f32_16x16x32_bf16 v[68:71], v[156:159], v[196:199], v[68:71]
	v_mfma_f32_16x16x32_bf16 v[64:67], v[164:167], v[196:199], v[64:67]
	v_mfma_f32_16x16x32_bf16 v[104:107], v[160:163], v[176:179], v[104:107]
	v_mfma_f32_16x16x32_bf16 v[96:99], v[168:171], v[176:179], v[96:99]
	v_mfma_f32_16x16x32_bf16 v[88:91], v[160:163], v[184:187], v[88:91]
	v_mfma_f32_16x16x32_bf16 v[84:87], v[168:171], v[184:187], v[84:87]
	v_mfma_f32_16x16x32_bf16 v[76:79], v[160:163], v[192:195], v[76:79]
	v_mfma_f32_16x16x32_bf16 v[72:75], v[168:171], v[192:195], v[72:75]
	v_mfma_f32_16x16x32_bf16 v[68:71], v[160:163], v[200:203], v[68:71]
	v_mfma_f32_16x16x32_bf16 v[64:67], v[168:171], v[200:203], v[64:67]
	s_barrier
	s_add_i32 s0, s28, s19
	v_lshl_add_u64 v[138:139], s[22:23], 0, v[208:209]
	s_mov_b32 m0, s0
	ds_read_b128 v[172:175], v143 offset:16384
	ds_read_b128 v[176:179], v143 offset:17408
	ds_read_b128 v[180:183], v143 offset:18432
	ds_read_b128 v[184:187], v143 offset:19456
	ds_read_b128 v[188:191], v143 offset:20480
	ds_read_b128 v[192:195], v143 offset:21504
	ds_read_b128 v[196:199], v143 offset:22528
	ds_read_b128 v[200:203], v143 offset:23552
	global_load_lds_dwordx4 v208, s[22:23]
	s_add_i32 m0, s0, 0x2000
	s_add_u32 s0, s22, 0xb0000
	v_lshl_add_u64 v[204:205], s[22:23], 0, v[128:129]
	s_addc_u32 s1, s23, 0
	s_add_i32 s28, s29, s19
	global_load_lds_dwordx4 v128, s[22:23]
	s_mov_b32 m0, s28
	v_lshl_add_u64 v[210:211], s[24:25], 0, v[128:129]
	global_load_lds_dwordx4 v208, s[0:1]
	s_add_i32 m0, s28, 0x2000
	s_nop 0
	global_load_lds_dwordx4 v128, s[0:1]
	v_lshl_add_u64 v[206:207], s[24:25], 0, v[208:209]
	s_mov_b32 m0, s26
	s_nop 0
	global_load_lds_dwordx4 v208, s[24:25]
	s_mov_b32 m0, s34
	s_nop 0
	global_load_lds_dwordx4 v128, s[24:25]
	s_waitcnt vmcnt(8)
	s_waitcnt lgkmcnt(0)
	s_barrier
; #define PG8_STAGE(bufoff, gbase, voff) do { _Pragma("unroll") for (int _i = 0; _i < 2; ++_i) \
;         __builtin_amdgcn_global_load_lds((const unsigned*)((const char*)(gbase) + (voff)[_i]), (PG8_LAS unsigned*)(lds + (bufoff) + ldsw + _i * 8192), 16, 0, 0); } while (0)
; #define PG8_LDA(dst, b, h) do { _Pragma("unroll") for (int m = 0; m < 4; ++m) _Pragma("unroll") for (int k = 0; k < 2; ++k) dst[m][k] = *(const PG8_LAS bf16x8*)(lds + PG8_SA(b, h) + aoff + m * 2048 + k * 1024); } while (0)
; #define PG8_LDB(dst, b, h) do { _Pragma("unroll") for (int n = 0; n < 2; ++n) _Pragma("unroll") for (int k = 0; k < 2; ++k) dst[n][k] = *(const PG8_LAS bf16x8*)(lds + PG8_SB(b, h) + boff + n * 2048 + k * 1024); } while (0)
; #define PG8_MMA(ai, bj, At, Bt) do { __builtin_amdgcn_s_setprio(1); _Pragma("unroll") for (int m = 0; m < 4; ++m) _Pragma("unroll") for (int n = 0; n < 2; ++n) _Pragma("unroll") for (int k = 0; k < 2; ++k) \
;         acc[ai][bj][m][n] = __builtin_amdgcn_mfma_f32_16x16x32_bf16(Bt[n][k], At[m][k], acc[ai][bj][m][n], 0, 0, 0); __builtin_amdgcn_s_setprio(0); } while (0)
; #define PG8_WAIT_V(n) asm volatile("s_waitcnt vmcnt(" #n ")" ::: "memory")
; #define PG8_WAIT_L(n) asm volatile("s_waitcnt lgkmcnt(" #n ")" ::: "memory")
; #define PG8_BAR __builtin_amdgcn_s_barrier()
; #define PG8_SCHED __builtin_amdgcn_sched_barrier(0)
; template <class Epi, class Sched, bool ALIGN_EPI = false, bool SP2 = false>
; __device__ __forceinline__ void gemm_phase(PG8_LAS unsigned char* lds, const Gemm g, const Sched& S, const Epi& E) {
;     ...
;             PG8_WAIT_V(8); PG8_WAIT_L(0); PG8_BAR; PG8_MMA(1, 0, At, B0); PG8_MMA(1, 1, At, B1); PG8_BAR; PG8_SCHED;
;             PG8_LDB(B0, 1, 0); PG8_LDB(B1, 1, 1); PG8_SCHED; PG8_LDA(At, 1, 0); PG8_STAGE(PG8_SA(0, 1), a2 + hstepA, voffA);
;             PG8_WAIT_V(8); PG8_WAIT_L(0); PG8_BAR; PG8_MMA(0, 0, At, B0); PG8_MMA(0, 1, At, B1); PG8_BAR; PG8_SCHED;
	v_mfma_f32_16x16x32_bf16 v[60:63], v[134:137], v[172:175], v[60:63]
	v_mfma_f32_16x16x32_bf16 v[56:59], v[148:151], v[172:175], v[56:59]
	v_mfma_f32_16x16x32_bf16 v[52:55], v[134:137], v[180:183], v[52:55]
	v_mfma_f32_16x16x32_bf16 v[48:51], v[148:151], v[180:183], v[48:51]
	v_mfma_f32_16x16x32_bf16 v[44:47], v[134:137], v[188:191], v[44:47]
	v_mfma_f32_16x16x32_bf16 v[32:35], v[148:151], v[188:191], v[32:35]
	v_mfma_f32_16x16x32_bf16 v[16:19], v[134:137], v[196:199], v[16:19]
	v_mfma_f32_16x16x32_bf16 v[8:11], v[148:151], v[196:199], v[8:11]
	v_mfma_f32_16x16x32_bf16 v[60:63], v[144:147], v[176:179], v[60:63]
	v_mfma_f32_16x16x32_bf16 v[56:59], v[152:155], v[176:179], v[56:59]
	v_mfma_f32_16x16x32_bf16 v[52:55], v[144:147], v[184:187], v[52:55]
	v_mfma_f32_16x16x32_bf16 v[48:51], v[152:155], v[184:187], v[48:51]
	v_mfma_f32_16x16x32_bf16 v[44:47], v[144:147], v[192:195], v[44:47]
	v_mfma_f32_16x16x32_bf16 v[32:35], v[152:155], v[192:195], v[32:35]
	v_mfma_f32_16x16x32_bf16 v[16:19], v[144:147], v[200:203], v[16:19]
	v_mfma_f32_16x16x32_bf16 v[8:11], v[152:155], v[200:203], v[8:11]
	v_mfma_f32_16x16x32_bf16 v[40:43], v[156:159], v[172:175], v[40:43]
	v_mfma_f32_16x16x32_bf16 v[36:39], v[164:167], v[172:175], v[36:39]
	v_mfma_f32_16x16x32_bf16 v[28:31], v[156:159], v[180:183], v[28:31]
	v_mfma_f32_16x16x32_bf16 v[24:27], v[164:167], v[180:183], v[24:27]
	v_mfma_f32_16x16x32_bf16 v[20:23], v[156:159], v[188:191], v[20:23]
	v_mfma_f32_16x16x32_bf16 v[12:15], v[164:167], v[188:191], v[12:15]
	v_mfma_f32_16x16x32_bf16 v[4:7], v[156:159], v[196:199], v[4:7]
	v_mfma_f32_16x16x32_bf16 v[0:3], v[164:167], v[196:199], v[0:3]
	v_mfma_f32_16x16x32_bf16 v[40:43], v[160:163], v[176:179], v[40:43]
	v_mfma_f32_16x16x32_bf16 v[36:39], v[168:171], v[176:179], v[36:39]
	v_mfma_f32_16x16x32_bf16 v[28:31], v[160:163], v[184:187], v[28:31]
	v_mfma_f32_16x16x32_bf16 v[24:27], v[168:171], v[184:187], v[24:27]
	v_mfma_f32_16x16x32_bf16 v[20:23], v[160:163], v[192:195], v[20:23]
	v_mfma_f32_16x16x32_bf16 v[12:15], v[168:171], v[192:195], v[12:15]
	v_mfma_f32_16x16x32_bf16 v[4:7], v[160:163], v[200:203], v[4:7]
	v_mfma_f32_16x16x32_bf16 v[0:3], v[168:171], v[200:203], v[0:3]
	s_barrier
	s_add_i32 s28, 0, 0x18000
	s_add_i32 s29, 0, 0x1c000
	v_add_u32_e32 v152, s28, v141
	v_add_u32_e32 v168, s29, v141
	ds_read_b128 v[134:137], v152
	ds_read_b128 v[144:147], v152 offset:1024
	ds_read_b128 v[148:151], v152 offset:2048
	ds_read_b128 v[152:155], v152 offset:3072
	ds_read_b128 v[156:159], v168
	ds_read_b128 v[160:163], v168 offset:1024
	ds_read_b128 v[164:167], v168 offset:2048
	ds_read_b128 v[168:171], v168 offset:3072
	s_add_u32 s0, s24, 0xb0000
	s_addc_u32 s1, s25, 0
	s_mov_b32 m0, s35
	ds_read_b128 v[172:175], v143 offset:32768
	ds_read_b128 v[176:179], v143 offset:33792
	ds_read_b128 v[180:183], v143 offset:34816
	ds_read_b128 v[184:187], v143 offset:35840
	ds_read_b128 v[188:191], v143 offset:36864
	ds_read_b128 v[192:195], v143 offset:37888
	ds_read_b128 v[196:199], v143 offset:38912
	ds_read_b128 v[200:203], v143 offset:39936
	global_load_lds_dwordx4 v208, s[0:1]
	s_mov_b32 m0, s39
	s_nop 0
	global_load_lds_dwordx4 v128, s[0:1]
	s_waitcnt vmcnt(8)
	s_waitcnt lgkmcnt(0)
	s_barrier
	v_mfma_f32_16x16x32_bf16 v[124:127], v[134:137], v[172:175], v[124:127]
	v_mfma_f32_16x16x32_bf16 v[120:123], v[148:151], v[172:175], v[120:123]
	v_mfma_f32_16x16x32_bf16 v[116:119], v[134:137], v[180:183], v[116:119]
	v_mfma_f32_16x16x32_bf16 v[112:115], v[148:151], v[180:183], v[112:115]
	v_mfma_f32_16x16x32_bf16 v[108:111], v[134:137], v[188:191], v[108:111]
	v_mfma_f32_16x16x32_bf16 v[100:103], v[148:151], v[188:191], v[100:103]
	v_mfma_f32_16x16x32_bf16 v[92:95], v[134:137], v[196:199], v[92:95]
	v_mfma_f32_16x16x32_bf16 v[80:83], v[148:151], v[196:199], v[80:83]
	v_mfma_f32_16x16x32_bf16 v[124:127], v[144:147], v[176:179], v[124:127]
	v_mfma_f32_16x16x32_bf16 v[120:123], v[152:155], v[176:179], v[120:123]
	v_mfma_f32_16x16x32_bf16 v[116:119], v[144:147], v[184:187], v[116:119]
	v_mfma_f32_16x16x32_bf16 v[112:115], v[152:155], v[184:187], v[112:115]
	v_mfma_f32_16x16x32_bf16 v[108:111], v[144:147], v[192:195], v[108:111]
	v_mfma_f32_16x16x32_bf16 v[100:103], v[152:155], v[192:195], v[100:103]
	v_mfma_f32_16x16x32_bf16 v[92:95], v[144:147], v[200:203], v[92:95]
	v_mfma_f32_16x16x32_bf16 v[80:83], v[152:155], v[200:203], v[80:83]
	v_mfma_f32_16x16x32_bf16 v[104:107], v[156:159], v[172:175], v[104:107]
	v_mfma_f32_16x16x32_bf16 v[96:99], v[164:167], v[172:175], v[96:99]
	v_mfma_f32_16x16x32_bf16 v[88:91], v[156:159], v[180:183], v[88:91]
	v_mfma_f32_16x16x32_bf16 v[84:87], v[164:167], v[180:183], v[84:87]
	v_mfma_f32_16x16x32_bf16 v[76:79], v[156:159], v[188:191], v[76:79]
	v_mfma_f32_16x16x32_bf16 v[72:75], v[164:167], v[188:191], v[72:75]
	v_mfma_f32_16x16x32_bf16 v[68:71], v[156:159], v[196:199], v[68:71]
	v_mfma_f32_16x16x32_bf16 v[64:67], v[164:167], v[196:199], v[64:67]
	v_mfma_f32_16x16x32_bf16 v[104:107], v[160:163], v[176:179], v[104:107]
	v_mfma_f32_16x16x32_bf16 v[96:99], v[168:171], v[176:179], v[96:99]
	v_mfma_f32_16x16x32_bf16 v[88:91], v[160:163], v[184:187], v[88:91]
	v_mfma_f32_16x16x32_bf16 v[84:87], v[168:171], v[184:187], v[84:87]
	v_mfma_f32_16x16x32_bf16 v[76:79], v[160:163], v[192:195], v[76:79]
	v_mfma_f32_16x16x32_bf16 v[72:75], v[168:171], v[192:195], v[72:75]
	v_mfma_f32_16x16x32_bf16 v[68:71], v[160:163], v[200:203], v[68:71]
	v_mfma_f32_16x16x32_bf16 v[64:67], v[168:171], v[200:203], v[64:67]
	s_barrier
; #define PG8_STAGE(bufoff, gbase, voff) do { _Pragma("unroll") for (int _i = 0; _i < 2; ++_i) \
;         __builtin_amdgcn_global_load_lds((const unsigned*)((const char*)(gbase) + (voff)[_i]), (PG8_LAS unsigned*)(lds + (bufoff) + ldsw + _i * 8192), 16, 0, 0); } while (0)
; #define PG8_LDA(dst, b, h) do { _Pragma("unroll") for (int m = 0; m < 4; ++m) _Pragma("unroll") for (int k = 0; k < 2; ++k) dst[m][k] = *(const PG8_LAS bf16x8*)(lds + PG8_SA(b, h) + aoff + m * 2048 + k * 1024); } while (0)
; #define PG8_MMA(ai, bj, At, Bt) do { __builtin_amdgcn_s_setprio(1); _Pragma("unroll") for (int m = 0; m < 4; ++m) _Pragma("unroll") for (int n = 0; n < 2; ++n) _Pragma("unroll") for (int k = 0; k < 2; ++k) \
;         acc[ai][bj][m][n] = __builtin_amdgcn_mfma_f32_16x16x32_bf16(Bt[n][k], At[m][k], acc[ai][bj][m][n], 0, 0, 0); __builtin_amdgcn_s_setprio(0); } while (0)
; #define PG8_WAIT_V(n) asm volatile("s_waitcnt vmcnt(" #n ")" ::: "memory")
; #define PG8_WAIT_L(n) asm volatile("s_waitcnt lgkmcnt(" #n ")" ::: "memory")
; #define PG8_BAR __builtin_amdgcn_s_barrier()
; #define PG8_SCHED __builtin_amdgcn_sched_barrier(0)
; template <class Epi, class Sched, bool ALIGN_EPI = false, bool SP2 = false>
; __device__ __forceinline__ void gemm_phase(PG8_LAS unsigned char* lds, const Gemm g, const Sched& S, const Epi& E) {
;     ...
;             PG8_LDA(At, 1, 1); PG8_STAGE(PG8_SB(1, 0), b3, voffB); PG8_STAGE(PG8_SB(1, 1), b3 + hstepB, voffB); PG8_STAGE(PG8_SA(1, 0), a3, voffA);
;             PG8_WAIT_V(8); PG8_WAIT_L(0); PG8_BAR; PG8_MMA(1, 0, At, B0); PG8_MMA(1, 1, At, B1); PG8_BAR; PG8_SCHED;
;     ...
;         if constexpr (ALIGN_EPI) { if (wr == 0) PG8_BAR; }
	s_add_i32 s0, s28, s19
	v_lshl_add_u64 v[138:139], v[138:139], 0, s[10:11]
	s_mov_b32 m0, s0
	ds_read_b128 v[172:175], v143 offset:49152
	ds_read_b128 v[176:179], v143 offset:50176
	ds_read_b128 v[180:183], v143 offset:51200
	ds_read_b128 v[184:187], v143 offset:52224
	ds_read_b128 v[188:191], v143 offset:53248
	ds_read_b128 v[192:195], v143 offset:54272
	ds_read_b128 v[196:199], v143 offset:55296
	ds_read_b128 v[200:203], v143 offset:56320
	global_load_lds_dwordx4 v[138:139], off
	s_add_i32 m0, s0, 0x2000
	s_add_u32 s0, s22, 0xb0080
	v_lshl_add_u64 v[138:139], v[204:205], 0, s[10:11]
	s_addc_u32 s1, s23, 0
	s_add_i32 s22, s29, s19
	global_load_lds_dwordx4 v[138:139], off
	s_mov_b32 m0, s22
	s_nop 0
	global_load_lds_dwordx4 v208, s[0:1]
	s_add_i32 m0, s22, 0x2000
	s_nop 0
	global_load_lds_dwordx4 v128, s[0:1]
	v_lshl_add_u64 v[138:139], v[206:207], 0, s[10:11]
	s_mov_b32 m0, s46
	s_nop 0
	global_load_lds_dwordx4 v[138:139], off
	v_lshl_add_u64 v[138:139], v[210:211], 0, s[10:11]
	s_mov_b32 m0, s47
	s_nop 0
	global_load_lds_dwordx4 v[138:139], off
	s_waitcnt vmcnt(8)
	s_waitcnt lgkmcnt(0)
	s_barrier
	v_mfma_f32_16x16x32_bf16 v[60:63], v[134:137], v[172:175], v[60:63]
	v_mfma_f32_16x16x32_bf16 v[56:59], v[148:151], v[172:175], v[56:59]
	v_mfma_f32_16x16x32_bf16 v[52:55], v[134:137], v[180:183], v[52:55]
	v_mfma_f32_16x16x32_bf16 v[48:51], v[148:151], v[180:183], v[48:51]
	v_mfma_f32_16x16x32_bf16 v[44:47], v[134:137], v[188:191], v[44:47]
	v_mfma_f32_16x16x32_bf16 v[32:35], v[148:151], v[188:191], v[32:35]
	v_mfma_f32_16x16x32_bf16 v[16:19], v[134:137], v[196:199], v[16:19]
	v_mfma_f32_16x16x32_bf16 v[8:11], v[148:151], v[196:199], v[8:11]
	v_mfma_f32_16x16x32_bf16 v[60:63], v[144:147], v[176:179], v[60:63]
	v_mfma_f32_16x16x32_bf16 v[56:59], v[152:155], v[176:179], v[56:59]
	v_mfma_f32_16x16x32_bf16 v[52:55], v[144:147], v[184:187], v[52:55]
	v_mfma_f32_16x16x32_bf16 v[48:51], v[152:155], v[184:187], v[48:51]
	v_mfma_f32_16x16x32_bf16 v[44:47], v[144:147], v[192:195], v[44:47]
	v_mfma_f32_16x16x32_bf16 v[32:35], v[152:155], v[192:195], v[32:35]
	v_mfma_f32_16x16x32_bf16 v[16:19], v[144:147], v[200:203], v[16:19]
	v_mfma_f32_16x16x32_bf16 v[8:11], v[152:155], v[200:203], v[8:11]
	v_mfma_f32_16x16x32_bf16 v[40:43], v[156:159], v[172:175], v[40:43]
	v_mfma_f32_16x16x32_bf16 v[36:39], v[164:167], v[172:175], v[36:39]
	v_mfma_f32_16x16x32_bf16 v[28:31], v[156:159], v[180:183], v[28:31]
	v_mfma_f32_16x16x32_bf16 v[24:27], v[164:167], v[180:183], v[24:27]
	v_mfma_f32_16x16x32_bf16 v[20:23], v[156:159], v[188:191], v[20:23]
	v_mfma_f32_16x16x32_bf16 v[12:15], v[164:167], v[188:191], v[12:15]
	v_mfma_f32_16x16x32_bf16 v[4:7], v[156:159], v[196:199], v[4:7]
	v_mfma_f32_16x16x32_bf16 v[0:3], v[164:167], v[196:199], v[0:3]
	v_mfma_f32_16x16x32_bf16 v[40:43], v[160:163], v[176:179], v[40:43]
	v_mfma_f32_16x16x32_bf16 v[36:39], v[168:171], v[176:179], v[36:39]
	v_mfma_f32_16x16x32_bf16 v[28:31], v[160:163], v[184:187], v[28:31]
	v_mfma_f32_16x16x32_bf16 v[24:27], v[168:171], v[184:187], v[24:27]
	v_mfma_f32_16x16x32_bf16 v[20:23], v[160:163], v[192:195], v[20:23]
	v_mfma_f32_16x16x32_bf16 v[12:15], v[168:171], v[192:195], v[12:15]
	v_mfma_f32_16x16x32_bf16 v[4:7], v[160:163], v[200:203], v[4:7]
	v_mfma_f32_16x16x32_bf16 v[0:3], v[168:171], v[200:203], v[0:3]
	s_barrier
	s_add_i32 s51, s51, 2
	s_add_u32 s14, s14, 0x100
	s_addc_u32 s15, s15, 0
	s_cmp_gt_u32 s51, 41
	s_mov_b64 s[0:1], s[20:21]
	s_cbranch_scc0 .LBB0_215
	s_and_b64 vcc, exec, s[42:43]
	s_cbranch_vccz .LBB0_218
	s_barrier

; #define PG8_STAGE(bufoff, gbase, voff) do { _Pragma("unroll") for (int _i = 0; _i < 2; ++_i) \
;         __builtin_amdgcn_global_load_lds((const unsigned*)((const char*)(gbase) + (voff)[_i]), (PG8_LAS unsigned*)(lds + (bufoff) + ldsw + _i * 8192), 16, 0, 0); } while (0)
; #define PG8_LDA(dst, b, h) do { _Pragma("unroll") for (int m = 0; m < 4; ++m) _Pragma("unroll") for (int k = 0; k < 2; ++k) dst[m][k] = *(const PG8_LAS bf16x8*)(lds + PG8_SA(b, h) + aoff + m * 2048 + k * 1024); } while (0)
; #define PG8_LDB(dst, b, h) do { _Pragma("unroll") for (int n = 0; n < 2; ++n) _Pragma("unroll") for (int k = 0; k < 2; ++k) dst[n][k] = *(const PG8_LAS bf16x8*)(lds + PG8_SB(b, h) + boff + n * 2048 + k * 1024); } while (0)
; #define PG8_WAIT_V(n) asm volatile("s_waitcnt vmcnt(" #n ")" ::: "memory")
; #define PG8_WAIT_L(n) asm volatile("s_waitcnt lgkmcnt(" #n ")" ::: "memory")
; #define PG8_BAR __builtin_amdgcn_s_barrier()
; #define PG8_SCHED __builtin_amdgcn_sched_barrier(0)
; template <class Epi, class Sched, bool ALIGN_EPI = false, bool SP2 = false>
; __device__ __forceinline__ void gemm_phase(PG8_LAS unsigned char* lds, const Gemm g, const Sched& S, const Epi& E) {
;     ...
;         const char* nA = has_next ? (const char*)g.A + (size_t)nxt.pm * tstepA : cA; const char* nB = has_next ? (const char*)g.Bt + (size_t)nxt.pn * tstepB : cB;
;         for (int t = 0; t < nt; t += 2) {
;             const bool last = (t == nt - 2);
;             const char* a1 = cA + (size_t)(t + 1) * kstep;
;             const char* a2 = last ? nA : cA + (size_t)(t + 2) * kstep; const char* b2 = last ? nB : cB + (size_t)(t + 2) * kstep;
;             const char* a3 = a2 + kstep; const char* b3 = b2 + kstep;
;             if (last && has_next) S.a_ready(nxt);
;             if constexpr (SP2) {
;             PG8_LDB(B0, 0, 0); PG8_LDB(B1, 0, 1); PG8_SCHED; PG8_LDA(At, 0, 0); PG8_STAGE(PG8_SA(1, 1), a1 + hstepA, voffA);
;             PG8_WAIT_V(8); PG8_WAIT_L(0); PG8_BAR; PG8_MMA(0, 0, At, B0); PG8_MMA(0, 1, At, B1); PG8_BAR; PG8_SCHED;
;             PG8_LDA(At, 0, 1); PG8_STAGE(PG8_SB(0, 0), b2, voffB); PG8_STAGE(PG8_SB(0, 1), b2 + hstepB, voffB); PG8_STAGE(PG8_SA(0, 0), a2, voffA);
;             PG8_WAIT_V(8); PG8_WAIT_L(0); PG8_BAR; PG8_MMA(1, 0, At, B0); PG8_MMA(1, 1, At, B1); PG8_BAR; PG8_SCHED;
.LBB0_338:
	s_add_u32 s22, s0, 0xfffc0080
	s_addc_u32 s23, s1, -1
	s_add_i32 s28, 0, 0x10000
	s_cmp_eq_u32 s51, 12
	s_cselect_b32 s25, s14, s23
	s_cselect_b32 s24, s15, s22
	v_add_u32_e32 v138, s28, v142
	s_cselect_b32 s23, s21, s50
	s_cselect_b32 s22, s41, s49
	s_add_i32 s29, 0, 0x14000
	ds_read_b128 v[146:149], v138
	ds_read_b128 v[150:153], v138 offset:1024
	ds_read_b128 v[154:157], v138 offset:2048
	ds_read_b128 v[158:161], v138 offset:3072
	v_add_u32_e32 v138, s29, v142
	ds_read_b128 v[162:165], v138
	ds_read_b128 v[166:169], v138 offset:1024
	ds_read_b128 v[170:173], v138 offset:2048
	ds_read_b128 v[174:177], v138 offset:3072
	s_add_i32 m0, s26, 0xc000
	ds_read_b128 v[178:181], v144
	ds_read_b128 v[182:185], v144 offset:1024
	ds_read_b128 v[186:189], v144 offset:2048
	ds_read_b128 v[190:193], v144 offset:3072
	ds_read_b128 v[194:197], v144 offset:4096
	ds_read_b128 v[198:201], v144 offset:5120
	ds_read_b128 v[202:205], v144 offset:6144
	ds_read_b128 v[210:213], v144 offset:7168
	global_load_lds_dwordx4 v134, s[0:1]
	s_add_i32 m0, s26, 0xe000
	s_nop 0
	global_load_lds_dwordx4 v136, s[0:1]
	s_waitcnt vmcnt(8)
	s_waitcnt lgkmcnt(0)
	s_barrier
	v_mfma_f32_16x16x32_bf16 v[124:127], v[146:149], v[178:181], v[124:127]
	v_mfma_f32_16x16x32_bf16 v[120:123], v[154:157], v[178:181], v[120:123]
	v_mfma_f32_16x16x32_bf16 v[116:119], v[146:149], v[186:189], v[116:119]
	v_mfma_f32_16x16x32_bf16 v[108:111], v[154:157], v[186:189], v[108:111]
	v_mfma_f32_16x16x32_bf16 v[100:103], v[146:149], v[194:197], v[100:103]
	v_mfma_f32_16x16x32_bf16 v[92:95], v[154:157], v[194:197], v[92:95]
	v_mfma_f32_16x16x32_bf16 v[84:87], v[146:149], v[202:205], v[84:87]
	v_mfma_f32_16x16x32_bf16 v[76:79], v[154:157], v[202:205], v[76:79]
	v_mfma_f32_16x16x32_bf16 v[124:127], v[150:153], v[182:185], v[124:127]
	v_mfma_f32_16x16x32_bf16 v[120:123], v[158:161], v[182:185], v[120:123]
	v_mfma_f32_16x16x32_bf16 v[116:119], v[150:153], v[190:193], v[116:119]
	v_mfma_f32_16x16x32_bf16 v[108:111], v[158:161], v[190:193], v[108:111]
	v_mfma_f32_16x16x32_bf16 v[100:103], v[150:153], v[198:201], v[100:103]
	v_mfma_f32_16x16x32_bf16 v[92:95], v[158:161], v[198:201], v[92:95]
	v_mfma_f32_16x16x32_bf16 v[84:87], v[150:153], v[210:213], v[84:87]
	v_mfma_f32_16x16x32_bf16 v[76:79], v[158:161], v[210:213], v[76:79]
	v_mfma_f32_16x16x32_bf16 v[112:115], v[162:165], v[178:181], v[112:115]
	v_mfma_f32_16x16x32_bf16 v[104:107], v[170:173], v[178:181], v[104:107]
	v_mfma_f32_16x16x32_bf16 v[96:99], v[162:165], v[186:189], v[96:99]
	v_mfma_f32_16x16x32_bf16 v[88:91], v[170:173], v[186:189], v[88:91]
	v_mfma_f32_16x16x32_bf16 v[80:83], v[162:165], v[194:197], v[80:83]
	v_mfma_f32_16x16x32_bf16 v[72:75], v[170:173], v[194:197], v[72:75]
	v_mfma_f32_16x16x32_bf16 v[68:71], v[162:165], v[202:205], v[68:71]
	v_mfma_f32_16x16x32_bf16 v[64:67], v[170:173], v[202:205], v[64:67]
	v_mfma_f32_16x16x32_bf16 v[112:115], v[166:169], v[182:185], v[112:115]
	v_mfma_f32_16x16x32_bf16 v[104:107], v[174:177], v[182:185], v[104:107]
	v_mfma_f32_16x16x32_bf16 v[96:99], v[166:169], v[190:193], v[96:99]
	v_mfma_f32_16x16x32_bf16 v[88:91], v[174:177], v[190:193], v[88:91]
	v_mfma_f32_16x16x32_bf16 v[80:83], v[166:169], v[198:201], v[80:83]
	v_mfma_f32_16x16x32_bf16 v[72:75], v[174:177], v[198:201], v[72:75]
	v_mfma_f32_16x16x32_bf16 v[68:71], v[166:169], v[210:213], v[68:71]
	v_mfma_f32_16x16x32_bf16 v[64:67], v[174:177], v[210:213], v[64:67]
	s_barrier
	s_add_i32 s28, s28, s18
	v_lshl_add_u64 v[140:141], s[22:23], 0, v[208:209]
	s_mov_b32 m0, s28
	ds_read_b128 v[178:181], v144 offset:16384
	ds_read_b128 v[182:185], v144 offset:17408
	ds_read_b128 v[186:189], v144 offset:18432
	ds_read_b128 v[190:193], v144 offset:19456
	ds_read_b128 v[194:197], v144 offset:20480
	ds_read_b128 v[198:201], v144 offset:21504
	ds_read_b128 v[202:205], v144 offset:22528
	ds_read_b128 v[210:213], v144 offset:23552
	global_load_lds_dwordx4 v208, s[22:23]
	s_add_i32 m0, s28, 0x2000
	s_add_u32 s52, s22, 0x40000
	v_lshl_add_u64 v[206:207], s[22:23], 0, v[128:129]
	s_addc_u32 s53, s23, 0
	s_add_i32 s28, s29, s18
	global_load_lds_dwordx4 v128, s[22:23]
	s_mov_b32 m0, s28
	v_lshl_add_u64 v[224:225], s[24:25], 0, v[130:131]
	global_load_lds_dwordx4 v208, s[52:53]
	s_add_i32 m0, s28, 0x2000
	s_nop 0
	global_load_lds_dwordx4 v128, s[52:53]
	v_lshl_add_u64 v[222:223], s[24:25], 0, v[132:133]
	s_mov_b32 m0, s26
	s_nop 0
	global_load_lds_dwordx4 v132, s[24:25]
	s_mov_b32 m0, s34
	s_nop 0
	global_load_lds_dwordx4 v130, s[24:25]
	s_waitcnt vmcnt(8)
	s_waitcnt lgkmcnt(0)
	s_barrier
; #define PG8_STAGE(bufoff, gbase, voff) do { _Pragma("unroll") for (int _i = 0; _i < 2; ++_i) \
;         __builtin_amdgcn_global_load_lds((const unsigned*)((const char*)(gbase) + (voff)[_i]), (PG8_LAS unsigned*)(lds + (bufoff) + ldsw + _i * 8192), 16, 0, 0); } while (0)
; #define PG8_LDA(dst, b, h) do { _Pragma("unroll") for (int m = 0; m < 4; ++m) _Pragma("unroll") for (int k = 0; k < 2; ++k) dst[m][k] = *(const PG8_LAS bf16x8*)(lds + PG8_SA(b, h) + aoff + m * 2048 + k * 1024); } while (0)
; #define PG8_LDB(dst, b, h) do { _Pragma("unroll") for (int n = 0; n < 2; ++n) _Pragma("unroll") for (int k = 0; k < 2; ++k) dst[n][k] = *(const PG8_LAS bf16x8*)(lds + PG8_SB(b, h) + boff + n * 2048 + k * 1024); } while (0)
; #define PG8_MMA(ai, bj, At, Bt) do { __builtin_amdgcn_s_setprio(1); _Pragma("unroll") for (int m = 0; m < 4; ++m) _Pragma("unroll") for (int n = 0; n < 2; ++n) _Pragma("unroll") for (int k = 0; k < 2; ++k) \
;         acc[ai][bj][m][n] = __builtin_amdgcn_mfma_f32_16x16x32_bf16(Bt[n][k], At[m][k], acc[ai][bj][m][n], 0, 0, 0); __builtin_amdgcn_s_setprio(0); } while (0)
; #define PG8_WAIT_V(n) asm volatile("s_waitcnt vmcnt(" #n ")" ::: "memory")
; #define PG8_WAIT_L(n) asm volatile("s_waitcnt lgkmcnt(" #n ")" ::: "memory")
; #define PG8_BAR __builtin_amdgcn_s_barrier()
; #define PG8_SCHED __builtin_amdgcn_sched_barrier(0)
; template <class Epi, class Sched, bool ALIGN_EPI = false, bool SP2 = false>
; __device__ __forceinline__ void gemm_phase(PG8_LAS unsigned char* lds, const Gemm g, const Sched& S, const Epi& E) {
;     ...
;             PG8_WAIT_V(8); PG8_WAIT_L(0); PG8_BAR; PG8_MMA(1, 0, At, B0); PG8_MMA(1, 1, At, B1); PG8_BAR; PG8_SCHED;
;             PG8_LDB(B0, 1, 0); PG8_LDB(B1, 1, 1); PG8_SCHED; PG8_LDA(At, 1, 0); PG8_STAGE(PG8_SA(0, 1), a2 + hstepA, voffA);
;             PG8_WAIT_V(8); PG8_WAIT_L(0); PG8_BAR; PG8_MMA(0, 0, At, B0); PG8_MMA(0, 1, At, B1); PG8_BAR; PG8_SCHED;
	v_mfma_f32_16x16x32_bf16 v[60:63], v[146:149], v[178:181], v[60:63]
	v_mfma_f32_16x16x32_bf16 v[56:59], v[154:157], v[178:181], v[56:59]
	v_mfma_f32_16x16x32_bf16 v[52:55], v[146:149], v[186:189], v[52:55]
	v_mfma_f32_16x16x32_bf16 v[44:47], v[154:157], v[186:189], v[44:47]
	v_mfma_f32_16x16x32_bf16 v[36:39], v[146:149], v[194:197], v[36:39]
	v_mfma_f32_16x16x32_bf16 v[28:31], v[154:157], v[194:197], v[28:31]
	v_mfma_f32_16x16x32_bf16 v[20:23], v[146:149], v[202:205], v[20:23]
	v_mfma_f32_16x16x32_bf16 v[12:15], v[154:157], v[202:205], v[12:15]
	v_mfma_f32_16x16x32_bf16 v[60:63], v[150:153], v[182:185], v[60:63]
	v_mfma_f32_16x16x32_bf16 v[56:59], v[158:161], v[182:185], v[56:59]
	v_mfma_f32_16x16x32_bf16 v[52:55], v[150:153], v[190:193], v[52:55]
	v_mfma_f32_16x16x32_bf16 v[44:47], v[158:161], v[190:193], v[44:47]
	v_mfma_f32_16x16x32_bf16 v[36:39], v[150:153], v[198:201], v[36:39]
	v_mfma_f32_16x16x32_bf16 v[28:31], v[158:161], v[198:201], v[28:31]
	v_mfma_f32_16x16x32_bf16 v[20:23], v[150:153], v[210:213], v[20:23]
	v_mfma_f32_16x16x32_bf16 v[12:15], v[158:161], v[210:213], v[12:15]
	v_mfma_f32_16x16x32_bf16 v[48:51], v[162:165], v[178:181], v[48:51]
	v_mfma_f32_16x16x32_bf16 v[40:43], v[170:173], v[178:181], v[40:43]
	v_mfma_f32_16x16x32_bf16 v[32:35], v[162:165], v[186:189], v[32:35]
	v_mfma_f32_16x16x32_bf16 v[24:27], v[170:173], v[186:189], v[24:27]
	v_mfma_f32_16x16x32_bf16 v[16:19], v[162:165], v[194:197], v[16:19]
	v_mfma_f32_16x16x32_bf16 v[8:11], v[170:173], v[194:197], v[8:11]
	v_mfma_f32_16x16x32_bf16 v[4:7], v[162:165], v[202:205], v[4:7]
	v_mfma_f32_16x16x32_bf16 v[0:3], v[170:173], v[202:205], v[0:3]
	v_mfma_f32_16x16x32_bf16 v[48:51], v[166:169], v[182:185], v[48:51]
	v_mfma_f32_16x16x32_bf16 v[40:43], v[174:177], v[182:185], v[40:43]
	v_mfma_f32_16x16x32_bf16 v[32:35], v[166:169], v[190:193], v[32:35]
	v_mfma_f32_16x16x32_bf16 v[24:27], v[174:177], v[190:193], v[24:27]
	v_mfma_f32_16x16x32_bf16 v[16:19], v[166:169], v[198:201], v[16:19]
	v_mfma_f32_16x16x32_bf16 v[8:11], v[174:177], v[198:201], v[8:11]
	v_mfma_f32_16x16x32_bf16 v[4:7], v[166:169], v[210:213], v[4:7]
	v_mfma_f32_16x16x32_bf16 v[0:3], v[174:177], v[210:213], v[0:3]
	s_barrier
	s_add_i32 s28, 0, 0x18000
	v_add_u32_e32 v138, s28, v142
	s_add_i32 s29, 0, 0x1c000
	ds_read_b128 v[146:149], v138
	ds_read_b128 v[150:153], v138 offset:1024
	ds_read_b128 v[154:157], v138 offset:2048
	ds_read_b128 v[158:161], v138 offset:3072
	v_add_u32_e32 v138, s29, v142
	ds_read_b128 v[162:165], v138
	ds_read_b128 v[166:169], v138 offset:1024
	ds_read_b128 v[170:173], v138 offset:2048
	ds_read_b128 v[174:177], v138 offset:3072
	s_add_u32 s24, s24, 0x40000
	s_addc_u32 s25, s25, 0
	s_mov_b32 m0, s35
	ds_read_b128 v[178:181], v144 offset:32768
	ds_read_b128 v[182:185], v144 offset:33792
	ds_read_b128 v[186:189], v144 offset:34816
	ds_read_b128 v[190:193], v144 offset:35840
	ds_read_b128 v[194:197], v144 offset:36864
	ds_read_b128 v[198:201], v144 offset:37888
	ds_read_b128 v[202:205], v144 offset:38912
	ds_read_b128 v[210:213], v144 offset:39936
	global_load_lds_dwordx4 v132, s[24:25]
	v_lshl_add_u64 v[226:227], s[24:25], 0, v[130:131]
	s_mov_b32 m0, s39
	s_nop 0
	global_load_lds_dwordx4 v130, s[24:25]
	s_waitcnt vmcnt(8)
	s_waitcnt lgkmcnt(0)
	s_barrier
	v_mfma_f32_16x16x32_bf16 v[124:127], v[146:149], v[178:181], v[124:127]
	v_mfma_f32_16x16x32_bf16 v[120:123], v[154:157], v[178:181], v[120:123]
	v_mfma_f32_16x16x32_bf16 v[116:119], v[146:149], v[186:189], v[116:119]
	v_mfma_f32_16x16x32_bf16 v[108:111], v[154:157], v[186:189], v[108:111]
	v_mfma_f32_16x16x32_bf16 v[100:103], v[146:149], v[194:197], v[100:103]
	v_mfma_f32_16x16x32_bf16 v[92:95], v[154:157], v[194:197], v[92:95]
	v_mfma_f32_16x16x32_bf16 v[84:87], v[146:149], v[202:205], v[84:87]
	v_mfma_f32_16x16x32_bf16 v[76:79], v[154:157], v[202:205], v[76:79]
	v_mfma_f32_16x16x32_bf16 v[124:127], v[150:153], v[182:185], v[124:127]
	v_mfma_f32_16x16x32_bf16 v[120:123], v[158:161], v[182:185], v[120:123]
	v_mfma_f32_16x16x32_bf16 v[116:119], v[150:153], v[190:193], v[116:119]
	v_mfma_f32_16x16x32_bf16 v[108:111], v[158:161], v[190:193], v[108:111]
	v_mfma_f32_16x16x32_bf16 v[100:103], v[150:153], v[198:201], v[100:103]
	v_mfma_f32_16x16x32_bf16 v[92:95], v[158:161], v[198:201], v[92:95]
	v_mfma_f32_16x16x32_bf16 v[84:87], v[150:153], v[210:213], v[84:87]
	v_mfma_f32_16x16x32_bf16 v[76:79], v[158:161], v[210:213], v[76:79]
	v_mfma_f32_16x16x32_bf16 v[112:115], v[162:165], v[178:181], v[112:115]
	v_mfma_f32_16x16x32_bf16 v[104:107], v[170:173], v[178:181], v[104:107]
	v_mfma_f32_16x16x32_bf16 v[96:99], v[162:165], v[186:189], v[96:99]
	v_mfma_f32_16x16x32_bf16 v[88:91], v[170:173], v[186:189], v[88:91]
	v_mfma_f32_16x16x32_bf16 v[80:83], v[162:165], v[194:197], v[80:83]
	v_mfma_f32_16x16x32_bf16 v[72:75], v[170:173], v[194:197], v[72:75]
	v_mfma_f32_16x16x32_bf16 v[68:71], v[162:165], v[202:205], v[68:71]
	v_mfma_f32_16x16x32_bf16 v[64:67], v[170:173], v[202:205], v[64:67]
	v_mfma_f32_16x16x32_bf16 v[112:115], v[166:169], v[182:185], v[112:115]
	v_mfma_f32_16x16x32_bf16 v[104:107], v[174:177], v[182:185], v[104:107]
	v_mfma_f32_16x16x32_bf16 v[96:99], v[166:169], v[190:193], v[96:99]
	v_mfma_f32_16x16x32_bf16 v[88:91], v[174:177], v[190:193], v[88:91]
	v_mfma_f32_16x16x32_bf16 v[80:83], v[166:169], v[198:201], v[80:83]
	v_mfma_f32_16x16x32_bf16 v[72:75], v[174:177], v[198:201], v[72:75]
	v_mfma_f32_16x16x32_bf16 v[68:71], v[166:169], v[210:213], v[68:71]
	v_mfma_f32_16x16x32_bf16 v[64:67], v[174:177], v[210:213], v[64:67]
	s_barrier
; #define PG8_STAGE(bufoff, gbase, voff) do { _Pragma("unroll") for (int _i = 0; _i < 2; ++_i) \
;         __builtin_amdgcn_global_load_lds((const unsigned*)((const char*)(gbase) + (voff)[_i]), (PG8_LAS unsigned*)(lds + (bufoff) + ldsw + _i * 8192), 16, 0, 0); } while (0)
; #define PG8_LDA(dst, b, h) do { _Pragma("unroll") for (int m = 0; m < 4; ++m) _Pragma("unroll") for (int k = 0; k < 2; ++k) dst[m][k] = *(const PG8_LAS bf16x8*)(lds + PG8_SA(b, h) + aoff + m * 2048 + k * 1024); } while (0)
; #define PG8_MMA(ai, bj, At, Bt) do { __builtin_amdgcn_s_setprio(1); _Pragma("unroll") for (int m = 0; m < 4; ++m) _Pragma("unroll") for (int n = 0; n < 2; ++n) _Pragma("unroll") for (int k = 0; k < 2; ++k) \
;         acc[ai][bj][m][n] = __builtin_amdgcn_mfma_f32_16x16x32_bf16(Bt[n][k], At[m][k], acc[ai][bj][m][n], 0, 0, 0); __builtin_amdgcn_s_setprio(0); } while (0)
; #define PG8_WAIT_V(n) asm volatile("s_waitcnt vmcnt(" #n ")" ::: "memory")
; #define PG8_WAIT_L(n) asm volatile("s_waitcnt lgkmcnt(" #n ")" ::: "memory")
; #define PG8_BAR __builtin_amdgcn_s_barrier()
; #define PG8_SCHED __builtin_amdgcn_sched_barrier(0)
; template <class Epi, class Sched, bool ALIGN_EPI = false, bool SP2 = false>
; __device__ __forceinline__ void gemm_phase(PG8_LAS unsigned char* lds, const Gemm g, const Sched& S, const Epi& E) {
;     ...
;             PG8_LDA(At, 1, 1); PG8_STAGE(PG8_SB(1, 0), b3, voffB); PG8_STAGE(PG8_SB(1, 1), b3 + hstepB, voffB); PG8_STAGE(PG8_SA(1, 0), a3, voffA);
;             PG8_WAIT_V(8); PG8_WAIT_L(0); PG8_BAR; PG8_MMA(1, 0, At, B0); PG8_MMA(1, 1, At, B1); PG8_BAR; PG8_SCHED;
;     ...
;         if constexpr (ALIGN_EPI) { if (wr == 0) PG8_BAR; }
	s_add_i32 s24, s28, s18
	v_lshl_add_u64 v[140:141], v[140:141], 0, s[10:11]
	s_mov_b32 m0, s24
	ds_read_b128 v[178:181], v144 offset:49152
	ds_read_b128 v[182:185], v144 offset:50176
	ds_read_b128 v[186:189], v144 offset:51200
	ds_read_b128 v[190:193], v144 offset:52224
	ds_read_b128 v[194:197], v144 offset:53248
	ds_read_b128 v[198:201], v144 offset:54272
	ds_read_b128 v[202:205], v144 offset:55296
	ds_read_b128 v[210:213], v144 offset:56320
	global_load_lds_dwordx4 v[140:141], off
	s_add_i32 m0, s24, 0x2000
	s_add_u32 s22, s22, 0x40080
	v_lshl_add_u64 v[140:141], v[206:207], 0, s[10:11]
	s_addc_u32 s23, s23, 0
	s_add_i32 s24, s29, s18
	global_load_lds_dwordx4 v[140:141], off
	s_mov_b32 m0, s24
	s_nop 0
	global_load_lds_dwordx4 v208, s[22:23]
	s_add_i32 m0, s24, 0x2000
	s_nop 0
	global_load_lds_dwordx4 v128, s[22:23]
	v_lshl_add_u64 v[140:141], v[222:223], 0, s[10:11]
	s_mov_b32 m0, s12
	s_nop 0
	global_load_lds_dwordx4 v[140:141], off
	v_lshl_add_u64 v[140:141], v[224:225], 0, s[10:11]
	s_mov_b32 m0, s43
	s_nop 0
	global_load_lds_dwordx4 v[140:141], off
	s_waitcnt vmcnt(8)
	s_waitcnt lgkmcnt(0)
	s_barrier
	v_mfma_f32_16x16x32_bf16 v[60:63], v[146:149], v[178:181], v[60:63]
	v_mfma_f32_16x16x32_bf16 v[56:59], v[154:157], v[178:181], v[56:59]
	v_mfma_f32_16x16x32_bf16 v[52:55], v[146:149], v[186:189], v[52:55]
	v_mfma_f32_16x16x32_bf16 v[44:47], v[154:157], v[186:189], v[44:47]
	v_mfma_f32_16x16x32_bf16 v[36:39], v[146:149], v[194:197], v[36:39]
	v_mfma_f32_16x16x32_bf16 v[28:31], v[154:157], v[194:197], v[28:31]
	v_mfma_f32_16x16x32_bf16 v[20:23], v[146:149], v[202:205], v[20:23]
	v_mfma_f32_16x16x32_bf16 v[12:15], v[154:157], v[202:205], v[12:15]
	v_mfma_f32_16x16x32_bf16 v[60:63], v[150:153], v[182:185], v[60:63]
	v_mfma_f32_16x16x32_bf16 v[56:59], v[158:161], v[182:185], v[56:59]
	v_mfma_f32_16x16x32_bf16 v[52:55], v[150:153], v[190:193], v[52:55]
	v_mfma_f32_16x16x32_bf16 v[44:47], v[158:161], v[190:193], v[44:47]
	v_mfma_f32_16x16x32_bf16 v[36:39], v[150:153], v[198:201], v[36:39]
	v_mfma_f32_16x16x32_bf16 v[28:31], v[158:161], v[198:201], v[28:31]
	v_mfma_f32_16x16x32_bf16 v[20:23], v[150:153], v[210:213], v[20:23]
	v_mfma_f32_16x16x32_bf16 v[12:15], v[158:161], v[210:213], v[12:15]
	v_mfma_f32_16x16x32_bf16 v[48:51], v[162:165], v[178:181], v[48:51]
	v_mfma_f32_16x16x32_bf16 v[40:43], v[170:173], v[178:181], v[40:43]
	v_mfma_f32_16x16x32_bf16 v[32:35], v[162:165], v[186:189], v[32:35]
	v_mfma_f32_16x16x32_bf16 v[24:27], v[170:173], v[186:189], v[24:27]
	v_mfma_f32_16x16x32_bf16 v[16:19], v[162:165], v[194:197], v[16:19]
	v_mfma_f32_16x16x32_bf16 v[8:11], v[170:173], v[194:197], v[8:11]
	v_mfma_f32_16x16x32_bf16 v[4:7], v[162:165], v[202:205], v[4:7]
	v_mfma_f32_16x16x32_bf16 v[0:3], v[170:173], v[202:205], v[0:3]
	v_mfma_f32_16x16x32_bf16 v[48:51], v[166:169], v[182:185], v[48:51]
	v_mfma_f32_16x16x32_bf16 v[40:43], v[174:177], v[182:185], v[40:43]
	v_mfma_f32_16x16x32_bf16 v[32:35], v[166:169], v[190:193], v[32:35]
	v_mfma_f32_16x16x32_bf16 v[24:27], v[174:177], v[190:193], v[24:27]
	v_mfma_f32_16x16x32_bf16 v[16:19], v[166:169], v[198:201], v[16:19]
	v_mfma_f32_16x16x32_bf16 v[8:11], v[174:177], v[198:201], v[8:11]
	v_mfma_f32_16x16x32_bf16 v[4:7], v[166:169], v[210:213], v[4:7]
	v_mfma_f32_16x16x32_bf16 v[0:3], v[174:177], v[210:213], v[0:3]
	s_barrier
	s_add_i32 s51, s51, 2
	s_add_u32 s0, s0, 0x100
	s_addc_u32 s1, s1, 0
	s_add_u32 s49, s49, 0x100
	s_addc_u32 s50, s50, 0
	s_cmp_gt_u32 s51, 13
	s_cbranch_scc0 .LBB0_338
	s_and_b64 vcc, exec, s[8:9]
	s_cbranch_vccz .LBB0_341
	s_barrier

; #define PG8_STAGE(bufoff, gbase, voff) do { _Pragma("unroll") for (int _i = 0; _i < 2; ++_i) \
;         __builtin_amdgcn_global_load_lds((const unsigned*)((const char*)(gbase) + (voff)[_i]), (PG8_LAS unsigned*)(lds + (bufoff) + ldsw + _i * 8192), 16, 0, 0); } while (0)
; #define PG8_LDA(dst, b, h) do { _Pragma("unroll") for (int m = 0; m < 4; ++m) _Pragma("unroll") for (int k = 0; k < 2; ++k) dst[m][k] = *(const PG8_LAS bf16x8*)(lds + PG8_SA(b, h) + aoff + m * 2048 + k * 1024); } while (0)
; #define PG8_LDB(dst, b, h) do { _Pragma("unroll") for (int n = 0; n < 2; ++n) _Pragma("unroll") for (int k = 0; k < 2; ++k) dst[n][k] = *(const PG8_LAS bf16x8*)(lds + PG8_SB(b, h) + boff + n * 2048 + k * 1024); } while (0)
; #define PG8_WAIT_V(n) asm volatile("s_waitcnt vmcnt(" #n ")" ::: "memory")
; #define PG8_WAIT_L(n) asm volatile("s_waitcnt lgkmcnt(" #n ")" ::: "memory")
; #define PG8_BAR __builtin_amdgcn_s_barrier()
; #define PG8_SCHED __builtin_amdgcn_sched_barrier(0)
; template <class Epi, class Sched, bool ALIGN_EPI = false, bool SP2 = false>
; __device__ __forceinline__ void gemm_phase(PG8_LAS unsigned char* lds, const Gemm g, const Sched& S, const Epi& E) {
;     ...
;         const char* nA = has_next ? (const char*)g.A + (size_t)nxt.pm * tstepA : cA; const char* nB = has_next ? (const char*)g.Bt + (size_t)nxt.pn * tstepB : cB;
;         for (int t = 0; t < nt; t += 2) {
;             const bool last = (t == nt - 2);
;             const char* a1 = cA + (size_t)(t + 1) * kstep;
;             const char* a2 = last ? nA : cA + (size_t)(t + 2) * kstep; const char* b2 = last ? nB : cB + (size_t)(t + 2) * kstep;
;             const char* a3 = a2 + kstep; const char* b3 = b2 + kstep;
;             if (last && has_next) S.a_ready(nxt);
;             if constexpr (SP2) {
;             PG8_LDB(B0, 0, 0); PG8_LDB(B1, 0, 1); PG8_SCHED; PG8_LDA(At, 0, 0); PG8_STAGE(PG8_SA(1, 1), a1 + hstepA, voffA);
;             PG8_WAIT_V(8); PG8_WAIT_L(0); PG8_BAR; PG8_MMA(0, 0, At, B0); PG8_MMA(0, 1, At, B1); PG8_BAR; PG8_SCHED;
;             PG8_LDA(At, 0, 1); PG8_STAGE(PG8_SB(0, 0), b2, voffB); PG8_STAGE(PG8_SB(0, 1), b2 + hstepB, voffB); PG8_STAGE(PG8_SA(0, 0), a2, voffA);
;             PG8_WAIT_V(8); PG8_WAIT_L(0); PG8_BAR; PG8_MMA(1, 0, At, B0); PG8_MMA(1, 1, At, B1); PG8_BAR; PG8_SCHED;
.LBB0_354:
	s_add_u32 s22, s44, 0xfffc0080
	s_addc_u32 s23, s45, -1
	s_add_i32 s28, 0, 0x10000
	s_cmp_eq_u32 s51, 12
	s_cselect_b32 s47, s14, s23
	s_cselect_b32 s46, s15, s22
	s_cselect_b32 s23, s1, s50
	s_cselect_b32 s22, s41, s49
	s_add_i32 s29, 0, 0x14000
	v_add_u32_e32 v154, s28, v139
	v_add_u32_e32 v170, s29, v139
	ds_read_b128 v[142:145], v154
	ds_read_b128 v[146:149], v154 offset:1024
	ds_read_b128 v[150:153], v154 offset:2048
	ds_read_b128 v[154:157], v154 offset:3072
	ds_read_b128 v[158:161], v170
	ds_read_b128 v[162:165], v170 offset:1024
	ds_read_b128 v[166:169], v170 offset:2048
	ds_read_b128 v[170:173], v170 offset:3072
	s_add_i32 m0, s21, 0xc000
	ds_read_b128 v[174:177], v141
	ds_read_b128 v[178:181], v141 offset:1024
	ds_read_b128 v[182:185], v141 offset:2048
	ds_read_b128 v[186:189], v141 offset:3072
	ds_read_b128 v[190:193], v141 offset:4096
	ds_read_b128 v[194:197], v141 offset:5120
	ds_read_b128 v[198:201], v141 offset:6144
	ds_read_b128 v[202:205], v141 offset:7168
	global_load_lds_dwordx4 v134, s[44:45]
	s_add_i32 m0, s21, 0xe000
	s_nop 0
	global_load_lds_dwordx4 v136, s[44:45]
	s_waitcnt vmcnt(8)
	s_waitcnt lgkmcnt(0)
	s_barrier
	v_mfma_f32_16x16x32_bf16 v[124:127], v[142:145], v[174:177], v[124:127]
	v_mfma_f32_16x16x32_bf16 v[120:123], v[150:153], v[174:177], v[120:123]
	v_mfma_f32_16x16x32_bf16 v[116:119], v[142:145], v[182:185], v[116:119]
	v_mfma_f32_16x16x32_bf16 v[112:115], v[150:153], v[182:185], v[112:115]
	v_mfma_f32_16x16x32_bf16 v[100:103], v[142:145], v[190:193], v[100:103]
	v_mfma_f32_16x16x32_bf16 v[96:99], v[150:153], v[190:193], v[96:99]
	v_mfma_f32_16x16x32_bf16 v[84:87], v[142:145], v[198:201], v[84:87]
	v_mfma_f32_16x16x32_bf16 v[80:83], v[150:153], v[198:201], v[80:83]
	v_mfma_f32_16x16x32_bf16 v[124:127], v[146:149], v[178:181], v[124:127]
	v_mfma_f32_16x16x32_bf16 v[120:123], v[154:157], v[178:181], v[120:123]
	v_mfma_f32_16x16x32_bf16 v[116:119], v[146:149], v[186:189], v[116:119]
	v_mfma_f32_16x16x32_bf16 v[112:115], v[154:157], v[186:189], v[112:115]
	v_mfma_f32_16x16x32_bf16 v[100:103], v[146:149], v[194:197], v[100:103]
	v_mfma_f32_16x16x32_bf16 v[96:99], v[154:157], v[194:197], v[96:99]
	v_mfma_f32_16x16x32_bf16 v[84:87], v[146:149], v[202:205], v[84:87]
	v_mfma_f32_16x16x32_bf16 v[80:83], v[154:157], v[202:205], v[80:83]
	v_mfma_f32_16x16x32_bf16 v[108:111], v[158:161], v[174:177], v[108:111]
	v_mfma_f32_16x16x32_bf16 v[104:107], v[166:169], v[174:177], v[104:107]
	v_mfma_f32_16x16x32_bf16 v[92:95], v[158:161], v[182:185], v[92:95]
	v_mfma_f32_16x16x32_bf16 v[88:91], v[166:169], v[182:185], v[88:91]
	v_mfma_f32_16x16x32_bf16 v[76:79], v[158:161], v[190:193], v[76:79]
	v_mfma_f32_16x16x32_bf16 v[72:75], v[166:169], v[190:193], v[72:75]
	v_mfma_f32_16x16x32_bf16 v[68:71], v[158:161], v[198:201], v[68:71]
	v_mfma_f32_16x16x32_bf16 v[64:67], v[166:169], v[198:201], v[64:67]
	v_mfma_f32_16x16x32_bf16 v[108:111], v[162:165], v[178:181], v[108:111]
	v_mfma_f32_16x16x32_bf16 v[104:107], v[170:173], v[178:181], v[104:107]
	v_mfma_f32_16x16x32_bf16 v[92:95], v[162:165], v[186:189], v[92:95]
	v_mfma_f32_16x16x32_bf16 v[88:91], v[170:173], v[186:189], v[88:91]
	v_mfma_f32_16x16x32_bf16 v[76:79], v[162:165], v[194:197], v[76:79]
	v_mfma_f32_16x16x32_bf16 v[72:75], v[170:173], v[194:197], v[72:75]
	v_mfma_f32_16x16x32_bf16 v[68:71], v[162:165], v[202:205], v[68:71]
	v_mfma_f32_16x16x32_bf16 v[64:67], v[170:173], v[202:205], v[64:67]
	s_barrier
	s_add_i32 s28, s28, s18
	v_lshl_add_u64 v[206:207], s[22:23], 0, v[208:209]
	s_mov_b32 m0, s28
	ds_read_b128 v[174:177], v141 offset:16384
	ds_read_b128 v[178:181], v141 offset:17408
	ds_read_b128 v[182:185], v141 offset:18432
	ds_read_b128 v[186:189], v141 offset:19456
	ds_read_b128 v[190:193], v141 offset:20480
	ds_read_b128 v[194:197], v141 offset:21504
	ds_read_b128 v[198:201], v141 offset:22528
	ds_read_b128 v[202:205], v141 offset:23552
	global_load_lds_dwordx4 v208, s[22:23]
	s_add_i32 m0, s28, 0x2000
	s_add_u32 s52, s22, 0x40000
	v_lshl_add_u64 v[210:211], s[22:23], 0, v[128:129]
	s_addc_u32 s53, s23, 0
	s_add_i32 s28, s29, s18
	global_load_lds_dwordx4 v128, s[22:23]
	s_mov_b32 m0, s28
	v_lshl_add_u64 v[222:223], s[46:47], 0, v[130:131]
	global_load_lds_dwordx4 v208, s[52:53]
	s_add_i32 m0, s28, 0x2000
	s_nop 0
	global_load_lds_dwordx4 v128, s[52:53]
	v_lshl_add_u64 v[212:213], s[46:47], 0, v[132:133]
	s_mov_b32 m0, s21
	s_nop 0
	global_load_lds_dwordx4 v132, s[46:47]
	s_mov_b32 m0, s12
	s_nop 0
	global_load_lds_dwordx4 v130, s[46:47]
	s_waitcnt vmcnt(8)
	s_waitcnt lgkmcnt(0)
	s_barrier
; #define PG8_STAGE(bufoff, gbase, voff) do { _Pragma("unroll") for (int _i = 0; _i < 2; ++_i) \
;         __builtin_amdgcn_global_load_lds((const unsigned*)((const char*)(gbase) + (voff)[_i]), (PG8_LAS unsigned*)(lds + (bufoff) + ldsw + _i * 8192), 16, 0, 0); } while (0)
; #define PG8_LDA(dst, b, h) do { _Pragma("unroll") for (int m = 0; m < 4; ++m) _Pragma("unroll") for (int k = 0; k < 2; ++k) dst[m][k] = *(const PG8_LAS bf16x8*)(lds + PG8_SA(b, h) + aoff + m * 2048 + k * 1024); } while (0)
; #define PG8_LDB(dst, b, h) do { _Pragma("unroll") for (int n = 0; n < 2; ++n) _Pragma("unroll") for (int k = 0; k < 2; ++k) dst[n][k] = *(const PG8_LAS bf16x8*)(lds + PG8_SB(b, h) + boff + n * 2048 + k * 1024); } while (0)
; #define PG8_MMA(ai, bj, At, Bt) do { __builtin_amdgcn_s_setprio(1); _Pragma("unroll") for (int m = 0; m < 4; ++m) _Pragma("unroll") for (int n = 0; n < 2; ++n) _Pragma("unroll") for (int k = 0; k < 2; ++k) \
;         acc[ai][bj][m][n] = __builtin_amdgcn_mfma_f32_16x16x32_bf16(Bt[n][k], At[m][k], acc[ai][bj][m][n], 0, 0, 0); __builtin_amdgcn_s_setprio(0); } while (0)
; #define PG8_WAIT_V(n) asm volatile("s_waitcnt vmcnt(" #n ")" ::: "memory")
; #define PG8_WAIT_L(n) asm volatile("s_waitcnt lgkmcnt(" #n ")" ::: "memory")
; #define PG8_BAR __builtin_amdgcn_s_barrier()
; #define PG8_SCHED __builtin_amdgcn_sched_barrier(0)
; template <class Epi, class Sched, bool ALIGN_EPI = false, bool SP2 = false>
; __device__ __forceinline__ void gemm_phase(PG8_LAS unsigned char* lds, const Gemm g, const Sched& S, const Epi& E) {
;     ...
;             PG8_WAIT_V(8); PG8_WAIT_L(0); PG8_BAR; PG8_MMA(1, 0, At, B0); PG8_MMA(1, 1, At, B1); PG8_BAR; PG8_SCHED;
;             PG8_LDB(B0, 1, 0); PG8_LDB(B1, 1, 1); PG8_SCHED; PG8_LDA(At, 1, 0); PG8_STAGE(PG8_SA(0, 1), a2 + hstepA, voffA);
;             PG8_WAIT_V(8); PG8_WAIT_L(0); PG8_BAR; PG8_MMA(0, 0, At, B0); PG8_MMA(0, 1, At, B1); PG8_BAR; PG8_SCHED;
	v_mfma_f32_16x16x32_bf16 v[60:63], v[142:145], v[174:177], v[60:63]
	v_mfma_f32_16x16x32_bf16 v[56:59], v[150:153], v[174:177], v[56:59]
	v_mfma_f32_16x16x32_bf16 v[52:55], v[142:145], v[182:185], v[52:55]
	v_mfma_f32_16x16x32_bf16 v[48:51], v[150:153], v[182:185], v[48:51]
	v_mfma_f32_16x16x32_bf16 v[36:39], v[142:145], v[190:193], v[36:39]
	v_mfma_f32_16x16x32_bf16 v[32:35], v[150:153], v[190:193], v[32:35]
	v_mfma_f32_16x16x32_bf16 v[20:23], v[142:145], v[198:201], v[20:23]
	v_mfma_f32_16x16x32_bf16 v[16:19], v[150:153], v[198:201], v[16:19]
	v_mfma_f32_16x16x32_bf16 v[60:63], v[146:149], v[178:181], v[60:63]
	v_mfma_f32_16x16x32_bf16 v[56:59], v[154:157], v[178:181], v[56:59]
	v_mfma_f32_16x16x32_bf16 v[52:55], v[146:149], v[186:189], v[52:55]
	v_mfma_f32_16x16x32_bf16 v[48:51], v[154:157], v[186:189], v[48:51]
	v_mfma_f32_16x16x32_bf16 v[36:39], v[146:149], v[194:197], v[36:39]
	v_mfma_f32_16x16x32_bf16 v[32:35], v[154:157], v[194:197], v[32:35]
	v_mfma_f32_16x16x32_bf16 v[20:23], v[146:149], v[202:205], v[20:23]
	v_mfma_f32_16x16x32_bf16 v[16:19], v[154:157], v[202:205], v[16:19]
	v_mfma_f32_16x16x32_bf16 v[44:47], v[158:161], v[174:177], v[44:47]
	v_mfma_f32_16x16x32_bf16 v[40:43], v[166:169], v[174:177], v[40:43]
	v_mfma_f32_16x16x32_bf16 v[28:31], v[158:161], v[182:185], v[28:31]
	v_mfma_f32_16x16x32_bf16 v[24:27], v[166:169], v[182:185], v[24:27]
	v_mfma_f32_16x16x32_bf16 v[12:15], v[158:161], v[190:193], v[12:15]
	v_mfma_f32_16x16x32_bf16 v[8:11], v[166:169], v[190:193], v[8:11]
	v_mfma_f32_16x16x32_bf16 v[4:7], v[158:161], v[198:201], v[4:7]
	v_mfma_f32_16x16x32_bf16 v[0:3], v[166:169], v[198:201], v[0:3]
	v_mfma_f32_16x16x32_bf16 v[44:47], v[162:165], v[178:181], v[44:47]
	v_mfma_f32_16x16x32_bf16 v[40:43], v[170:173], v[178:181], v[40:43]
	v_mfma_f32_16x16x32_bf16 v[28:31], v[162:165], v[186:189], v[28:31]
	v_mfma_f32_16x16x32_bf16 v[24:27], v[170:173], v[186:189], v[24:27]
	v_mfma_f32_16x16x32_bf16 v[12:15], v[162:165], v[194:197], v[12:15]
	v_mfma_f32_16x16x32_bf16 v[8:11], v[170:173], v[194:197], v[8:11]
	v_mfma_f32_16x16x32_bf16 v[4:7], v[162:165], v[202:205], v[4:7]
	v_mfma_f32_16x16x32_bf16 v[0:3], v[170:173], v[202:205], v[0:3]
	s_barrier
	s_add_i32 s28, 0, 0x18000
	s_add_i32 s29, 0, 0x1c000
	v_add_u32_e32 v154, s28, v139
	v_add_u32_e32 v170, s29, v139
	ds_read_b128 v[142:145], v154
	ds_read_b128 v[146:149], v154 offset:1024
	ds_read_b128 v[150:153], v154 offset:2048
	ds_read_b128 v[154:157], v154 offset:3072
	ds_read_b128 v[158:161], v170
	ds_read_b128 v[162:165], v170 offset:1024
	ds_read_b128 v[166:169], v170 offset:2048
	ds_read_b128 v[170:173], v170 offset:3072
	s_add_u32 s46, s46, 0x40000
	s_addc_u32 s47, s47, 0
	s_mov_b32 m0, s26
	ds_read_b128 v[174:177], v141 offset:32768
	ds_read_b128 v[178:181], v141 offset:33792
	ds_read_b128 v[182:185], v141 offset:34816
	ds_read_b128 v[186:189], v141 offset:35840
	ds_read_b128 v[190:193], v141 offset:36864
	ds_read_b128 v[194:197], v141 offset:37888
	ds_read_b128 v[198:201], v141 offset:38912
	ds_read_b128 v[202:205], v141 offset:39936
	global_load_lds_dwordx4 v132, s[46:47]
	v_lshl_add_u64 v[224:225], s[46:47], 0, v[130:131]
	s_mov_b32 m0, s34
	s_nop 0
	global_load_lds_dwordx4 v130, s[46:47]
	s_waitcnt vmcnt(8)
	s_waitcnt lgkmcnt(0)
	s_barrier
	v_mfma_f32_16x16x32_bf16 v[124:127], v[142:145], v[174:177], v[124:127]
	v_mfma_f32_16x16x32_bf16 v[120:123], v[150:153], v[174:177], v[120:123]
	v_mfma_f32_16x16x32_bf16 v[116:119], v[142:145], v[182:185], v[116:119]
	v_mfma_f32_16x16x32_bf16 v[112:115], v[150:153], v[182:185], v[112:115]
	v_mfma_f32_16x16x32_bf16 v[100:103], v[142:145], v[190:193], v[100:103]
	v_mfma_f32_16x16x32_bf16 v[96:99], v[150:153], v[190:193], v[96:99]
	v_mfma_f32_16x16x32_bf16 v[84:87], v[142:145], v[198:201], v[84:87]
	v_mfma_f32_16x16x32_bf16 v[80:83], v[150:153], v[198:201], v[80:83]
	v_mfma_f32_16x16x32_bf16 v[124:127], v[146:149], v[178:181], v[124:127]
	v_mfma_f32_16x16x32_bf16 v[120:123], v[154:157], v[178:181], v[120:123]
	v_mfma_f32_16x16x32_bf16 v[116:119], v[146:149], v[186:189], v[116:119]
	v_mfma_f32_16x16x32_bf16 v[112:115], v[154:157], v[186:189], v[112:115]
	v_mfma_f32_16x16x32_bf16 v[100:103], v[146:149], v[194:197], v[100:103]
	v_mfma_f32_16x16x32_bf16 v[96:99], v[154:157], v[194:197], v[96:99]
	v_mfma_f32_16x16x32_bf16 v[84:87], v[146:149], v[202:205], v[84:87]
	v_mfma_f32_16x16x32_bf16 v[80:83], v[154:157], v[202:205], v[80:83]
	v_mfma_f32_16x16x32_bf16 v[108:111], v[158:161], v[174:177], v[108:111]
	v_mfma_f32_16x16x32_bf16 v[104:107], v[166:169], v[174:177], v[104:107]
	v_mfma_f32_16x16x32_bf16 v[92:95], v[158:161], v[182:185], v[92:95]
	v_mfma_f32_16x16x32_bf16 v[88:91], v[166:169], v[182:185], v[88:91]
	v_mfma_f32_16x16x32_bf16 v[76:79], v[158:161], v[190:193], v[76:79]
	v_mfma_f32_16x16x32_bf16 v[72:75], v[166:169], v[190:193], v[72:75]
	v_mfma_f32_16x16x32_bf16 v[68:71], v[158:161], v[198:201], v[68:71]
	v_mfma_f32_16x16x32_bf16 v[64:67], v[166:169], v[198:201], v[64:67]
	v_mfma_f32_16x16x32_bf16 v[108:111], v[162:165], v[178:181], v[108:111]
	v_mfma_f32_16x16x32_bf16 v[104:107], v[170:173], v[178:181], v[104:107]
	v_mfma_f32_16x16x32_bf16 v[92:95], v[162:165], v[186:189], v[92:95]
	v_mfma_f32_16x16x32_bf16 v[88:91], v[170:173], v[186:189], v[88:91]
	v_mfma_f32_16x16x32_bf16 v[76:79], v[162:165], v[194:197], v[76:79]
	v_mfma_f32_16x16x32_bf16 v[72:75], v[170:173], v[194:197], v[72:75]
	v_mfma_f32_16x16x32_bf16 v[68:71], v[162:165], v[202:205], v[68:71]
	v_mfma_f32_16x16x32_bf16 v[64:67], v[170:173], v[202:205], v[64:67]
	s_barrier
; #define PG8_STAGE(bufoff, gbase, voff) do { _Pragma("unroll") for (int _i = 0; _i < 2; ++_i) \
;         __builtin_amdgcn_global_load_lds((const unsigned*)((const char*)(gbase) + (voff)[_i]), (PG8_LAS unsigned*)(lds + (bufoff) + ldsw + _i * 8192), 16, 0, 0); } while (0)
; #define PG8_LDA(dst, b, h) do { _Pragma("unroll") for (int m = 0; m < 4; ++m) _Pragma("unroll") for (int k = 0; k < 2; ++k) dst[m][k] = *(const PG8_LAS bf16x8*)(lds + PG8_SA(b, h) + aoff + m * 2048 + k * 1024); } while (0)
; #define PG8_MMA(ai, bj, At, Bt) do { __builtin_amdgcn_s_setprio(1); _Pragma("unroll") for (int m = 0; m < 4; ++m) _Pragma("unroll") for (int n = 0; n < 2; ++n) _Pragma("unroll") for (int k = 0; k < 2; ++k) \
;         acc[ai][bj][m][n] = __builtin_amdgcn_mfma_f32_16x16x32_bf16(Bt[n][k], At[m][k], acc[ai][bj][m][n], 0, 0, 0); __builtin_amdgcn_s_setprio(0); } while (0)
; #define PG8_WAIT_V(n) asm volatile("s_waitcnt vmcnt(" #n ")" ::: "memory")
; #define PG8_WAIT_L(n) asm volatile("s_waitcnt lgkmcnt(" #n ")" ::: "memory")
; #define PG8_BAR __builtin_amdgcn_s_barrier()
; #define PG8_SCHED __builtin_amdgcn_sched_barrier(0)
; template <class Epi, class Sched, bool ALIGN_EPI = false, bool SP2 = false>
; __device__ __forceinline__ void gemm_phase(PG8_LAS unsigned char* lds, const Gemm g, const Sched& S, const Epi& E) {
;     ...
;             PG8_LDA(At, 1, 1); PG8_STAGE(PG8_SB(1, 0), b3, voffB); PG8_STAGE(PG8_SB(1, 1), b3 + hstepB, voffB); PG8_STAGE(PG8_SA(1, 0), a3, voffA);
;             PG8_WAIT_V(8); PG8_WAIT_L(0); PG8_BAR; PG8_MMA(1, 0, At, B0); PG8_MMA(1, 1, At, B1); PG8_BAR; PG8_SCHED;
;     ...
;         if constexpr (ALIGN_EPI) { if (wr == 0) PG8_BAR; }
	s_add_i32 s28, s28, s18
	v_lshl_add_u64 v[206:207], v[206:207], 0, s[10:11]
	s_mov_b32 m0, s28
	ds_read_b128 v[174:177], v141 offset:49152
	ds_read_b128 v[178:181], v141 offset:50176
	ds_read_b128 v[182:185], v141 offset:51200
	ds_read_b128 v[186:189], v141 offset:52224
	ds_read_b128 v[190:193], v141 offset:53248
	ds_read_b128 v[194:197], v141 offset:54272
	ds_read_b128 v[198:201], v141 offset:55296
	ds_read_b128 v[202:205], v141 offset:56320
	global_load_lds_dwordx4 v[206:207], off
	s_add_i32 m0, s28, 0x2000
	s_add_u32 s22, s22, 0x40080
	v_lshl_add_u64 v[206:207], v[210:211], 0, s[10:11]
	s_addc_u32 s23, s23, 0
	s_add_i32 s28, s29, s18
	global_load_lds_dwordx4 v[206:207], off
	s_mov_b32 m0, s28
	s_nop 0
	global_load_lds_dwordx4 v208, s[22:23]
	s_add_i32 m0, s28, 0x2000
	s_nop 0
	global_load_lds_dwordx4 v128, s[22:23]
	v_lshl_add_u64 v[206:207], v[212:213], 0, s[10:11]
	s_mov_b32 m0, s35
	s_nop 0
	global_load_lds_dwordx4 v[206:207], off
	v_lshl_add_u64 v[206:207], v[222:223], 0, s[10:11]
	s_mov_b32 m0, s39
	s_nop 0
	global_load_lds_dwordx4 v[206:207], off
	s_waitcnt vmcnt(8)
	s_waitcnt lgkmcnt(0)
	s_barrier
	v_mfma_f32_16x16x32_bf16 v[60:63], v[142:145], v[174:177], v[60:63]
	v_mfma_f32_16x16x32_bf16 v[56:59], v[150:153], v[174:177], v[56:59]
	v_mfma_f32_16x16x32_bf16 v[52:55], v[142:145], v[182:185], v[52:55]
	v_mfma_f32_16x16x32_bf16 v[48:51], v[150:153], v[182:185], v[48:51]
	v_mfma_f32_16x16x32_bf16 v[36:39], v[142:145], v[190:193], v[36:39]
	v_mfma_f32_16x16x32_bf16 v[32:35], v[150:153], v[190:193], v[32:35]
	v_mfma_f32_16x16x32_bf16 v[20:23], v[142:145], v[198:201], v[20:23]
	v_mfma_f32_16x16x32_bf16 v[16:19], v[150:153], v[198:201], v[16:19]
	v_mfma_f32_16x16x32_bf16 v[60:63], v[146:149], v[178:181], v[60:63]
	v_mfma_f32_16x16x32_bf16 v[56:59], v[154:157], v[178:181], v[56:59]
	v_mfma_f32_16x16x32_bf16 v[52:55], v[146:149], v[186:189], v[52:55]
	v_mfma_f32_16x16x32_bf16 v[48:51], v[154:157], v[186:189], v[48:51]
	v_mfma_f32_16x16x32_bf16 v[36:39], v[146:149], v[194:197], v[36:39]
	v_mfma_f32_16x16x32_bf16 v[32:35], v[154:157], v[194:197], v[32:35]
	v_mfma_f32_16x16x32_bf16 v[20:23], v[146:149], v[202:205], v[20:23]
	v_mfma_f32_16x16x32_bf16 v[16:19], v[154:157], v[202:205], v[16:19]
	v_mfma_f32_16x16x32_bf16 v[44:47], v[158:161], v[174:177], v[44:47]
	v_mfma_f32_16x16x32_bf16 v[40:43], v[166:169], v[174:177], v[40:43]
	v_mfma_f32_16x16x32_bf16 v[28:31], v[158:161], v[182:185], v[28:31]
	v_mfma_f32_16x16x32_bf16 v[24:27], v[166:169], v[182:185], v[24:27]
	v_mfma_f32_16x16x32_bf16 v[12:15], v[158:161], v[190:193], v[12:15]
	v_mfma_f32_16x16x32_bf16 v[8:11], v[166:169], v[190:193], v[8:11]
	v_mfma_f32_16x16x32_bf16 v[4:7], v[158:161], v[198:201], v[4:7]
	v_mfma_f32_16x16x32_bf16 v[0:3], v[166:169], v[198:201], v[0:3]
	v_mfma_f32_16x16x32_bf16 v[44:47], v[162:165], v[178:181], v[44:47]
	v_mfma_f32_16x16x32_bf16 v[40:43], v[170:173], v[178:181], v[40:43]
	v_mfma_f32_16x16x32_bf16 v[28:31], v[162:165], v[186:189], v[28:31]
	v_mfma_f32_16x16x32_bf16 v[24:27], v[170:173], v[186:189], v[24:27]
	v_mfma_f32_16x16x32_bf16 v[12:15], v[162:165], v[194:197], v[12:15]
	v_mfma_f32_16x16x32_bf16 v[8:11], v[170:173], v[194:197], v[8:11]
	v_mfma_f32_16x16x32_bf16 v[4:7], v[162:165], v[202:205], v[4:7]
	v_mfma_f32_16x16x32_bf16 v[0:3], v[170:173], v[202:205], v[0:3]
	s_barrier
	s_add_i32 s51, s51, 2
	s_add_u32 s44, s44, 0x100
	s_addc_u32 s45, s45, 0
	s_add_u32 s49, s49, 0x100
	s_addc_u32 s50, s50, 0
	s_cmp_gt_u32 s51, 13
	s_cbranch_scc0 .LBB0_354
	s_and_b64 vcc, exec, s[8:9]
	s_cbranch_vccz .LBB0_357
	s_barrier

; #define PG8_STAGE(bufoff, gbase, voff) do { _Pragma("unroll") for (int _i = 0; _i < 2; ++_i) \
;         __builtin_amdgcn_global_load_lds((const unsigned*)((const char*)(gbase) + (voff)[_i]), (PG8_LAS unsigned*)(lds + (bufoff) + ldsw + _i * 8192), 16, 0, 0); } while (0)
; #define PG8_LDA(dst, b, h) do { _Pragma("unroll") for (int m = 0; m < 4; ++m) _Pragma("unroll") for (int k = 0; k < 2; ++k) dst[m][k] = *(const PG8_LAS bf16x8*)(lds + PG8_SA(b, h) + aoff + m * 2048 + k * 1024); } while (0)
; #define PG8_LDB(dst, b, h) do { _Pragma("unroll") for (int n = 0; n < 2; ++n) _Pragma("unroll") for (int k = 0; k < 2; ++k) dst[n][k] = *(const PG8_LAS bf16x8*)(lds + PG8_SB(b, h) + boff + n * 2048 + k * 1024); } while (0)
; #define PG8_WAIT_V(n) asm volatile("s_waitcnt vmcnt(" #n ")" ::: "memory")
; #define PG8_WAIT_L(n) asm volatile("s_waitcnt lgkmcnt(" #n ")" ::: "memory")
; #define PG8_BAR __builtin_amdgcn_s_barrier()
; #define PG8_SCHED __builtin_amdgcn_sched_barrier(0)
; template <class Epi, class Sched, bool ALIGN_EPI = false, bool SP2 = false>
; __device__ __forceinline__ void gemm_phase(PG8_LAS unsigned char* lds, const Gemm g, const Sched& S, const Epi& E) {
;     ...
;         const char* nA = has_next ? (const char*)g.A + (size_t)nxt.pm * tstepA : cA; const char* nB = has_next ? (const char*)g.Bt + (size_t)nxt.pn * tstepB : cB;
;         for (int t = 0; t < nt; t += 2) {
;             const bool last = (t == nt - 2);
;             const char* a1 = cA + (size_t)(t + 1) * kstep;
;             const char* a2 = last ? nA : cA + (size_t)(t + 2) * kstep; const char* b2 = last ? nB : cB + (size_t)(t + 2) * kstep;
;             const char* a3 = a2 + kstep; const char* b3 = b2 + kstep;
;             if (last && has_next) S.a_ready(nxt);
;             if constexpr (SP2) {
;             PG8_LDB(B0, 0, 0); PG8_LDB(B1, 0, 1); PG8_SCHED; PG8_LDA(At, 0, 0); PG8_STAGE(PG8_SA(1, 1), a1 + hstepA, voffA);
;             PG8_WAIT_V(8); PG8_WAIT_L(0); PG8_BAR; PG8_MMA(0, 0, At, B0); PG8_MMA(0, 1, At, B1); PG8_BAR; PG8_SCHED;
;             PG8_LDA(At, 0, 1); PG8_STAGE(PG8_SB(0, 0), b2, voffB); PG8_STAGE(PG8_SB(0, 1), b2 + hstepB, voffB); PG8_STAGE(PG8_SA(0, 0), a2, voffA);
;             PG8_WAIT_V(8); PG8_WAIT_L(0); PG8_BAR; PG8_MMA(1, 0, At, B0); PG8_MMA(1, 1, At, B1); PG8_BAR; PG8_SCHED;
.LBB0_607:
	s_add_u32 s22, s0, 0xfffc0080
	s_addc_u32 s23, s1, -1
	s_add_i32 s28, 0, 0x10000
	s_cmp_eq_u32 s51, 12
	s_cselect_b32 s25, s14, s23
	s_cselect_b32 s24, s15, s22
	s_cselect_b32 s23, s9, s50
	s_cselect_b32 s22, s38, s43
	s_add_i32 s29, 0, 0x14000
	v_add_u32_e32 v154, s28, v143
	v_add_u32_e32 v170, s29, v143
	ds_read_b128 v[138:141], v154
	ds_read_b128 v[146:149], v154 offset:1024
	ds_read_b128 v[150:153], v154 offset:2048
	ds_read_b128 v[154:157], v154 offset:3072
	ds_read_b128 v[158:161], v170
	ds_read_b128 v[162:165], v170 offset:1024
	ds_read_b128 v[166:169], v170 offset:2048
	ds_read_b128 v[170:173], v170 offset:3072
	s_add_i32 m0, s21, 0xc000
	ds_read_b128 v[174:177], v145
	ds_read_b128 v[178:181], v145 offset:1024
	ds_read_b128 v[182:185], v145 offset:2048
	ds_read_b128 v[186:189], v145 offset:3072
	ds_read_b128 v[190:193], v145 offset:4096
	ds_read_b128 v[194:197], v145 offset:5120
	ds_read_b128 v[198:201], v145 offset:6144
	ds_read_b128 v[202:205], v145 offset:7168
	global_load_lds_dwordx4 v134, s[0:1]
	s_add_i32 m0, s21, 0xe000
	s_nop 0
	global_load_lds_dwordx4 v136, s[0:1]
	s_waitcnt vmcnt(8)
	s_waitcnt lgkmcnt(0)
	s_barrier
	v_mfma_f32_16x16x32_bf16 v[124:127], v[138:141], v[174:177], v[124:127]
	v_mfma_f32_16x16x32_bf16 v[120:123], v[150:153], v[174:177], v[120:123]
	v_mfma_f32_16x16x32_bf16 v[108:111], v[138:141], v[182:185], v[108:111]
	v_mfma_f32_16x16x32_bf16 v[104:107], v[150:153], v[182:185], v[104:107]
	v_mfma_f32_16x16x32_bf16 v[92:95], v[138:141], v[190:193], v[92:95]
	v_mfma_f32_16x16x32_bf16 v[88:91], v[150:153], v[190:193], v[88:91]
	v_mfma_f32_16x16x32_bf16 v[76:79], v[138:141], v[198:201], v[76:79]
	v_mfma_f32_16x16x32_bf16 v[72:75], v[150:153], v[198:201], v[72:75]
	v_mfma_f32_16x16x32_bf16 v[124:127], v[146:149], v[178:181], v[124:127]
	v_mfma_f32_16x16x32_bf16 v[120:123], v[154:157], v[178:181], v[120:123]
	v_mfma_f32_16x16x32_bf16 v[108:111], v[146:149], v[186:189], v[108:111]
	v_mfma_f32_16x16x32_bf16 v[104:107], v[154:157], v[186:189], v[104:107]
	v_mfma_f32_16x16x32_bf16 v[92:95], v[146:149], v[194:197], v[92:95]
	v_mfma_f32_16x16x32_bf16 v[88:91], v[154:157], v[194:197], v[88:91]
	v_mfma_f32_16x16x32_bf16 v[76:79], v[146:149], v[202:205], v[76:79]
	v_mfma_f32_16x16x32_bf16 v[72:75], v[154:157], v[202:205], v[72:75]
	v_mfma_f32_16x16x32_bf16 v[116:119], v[158:161], v[174:177], v[116:119]
	v_mfma_f32_16x16x32_bf16 v[112:115], v[166:169], v[174:177], v[112:115]
	v_mfma_f32_16x16x32_bf16 v[100:103], v[158:161], v[182:185], v[100:103]
	v_mfma_f32_16x16x32_bf16 v[96:99], v[166:169], v[182:185], v[96:99]
	v_mfma_f32_16x16x32_bf16 v[84:87], v[158:161], v[190:193], v[84:87]
	v_mfma_f32_16x16x32_bf16 v[80:83], v[166:169], v[190:193], v[80:83]
	v_mfma_f32_16x16x32_bf16 v[68:71], v[158:161], v[198:201], v[68:71]
	v_mfma_f32_16x16x32_bf16 v[64:67], v[166:169], v[198:201], v[64:67]
	v_mfma_f32_16x16x32_bf16 v[116:119], v[162:165], v[178:181], v[116:119]
	v_mfma_f32_16x16x32_bf16 v[112:115], v[170:173], v[178:181], v[112:115]
	v_mfma_f32_16x16x32_bf16 v[100:103], v[162:165], v[186:189], v[100:103]
	v_mfma_f32_16x16x32_bf16 v[96:99], v[170:173], v[186:189], v[96:99]
	v_mfma_f32_16x16x32_bf16 v[84:87], v[162:165], v[194:197], v[84:87]
	v_mfma_f32_16x16x32_bf16 v[80:83], v[170:173], v[194:197], v[80:83]
	v_mfma_f32_16x16x32_bf16 v[68:71], v[162:165], v[202:205], v[68:71]
	v_mfma_f32_16x16x32_bf16 v[64:67], v[170:173], v[202:205], v[64:67]
	s_barrier
	s_add_i32 s28, s28, s26
	v_lshl_add_u64 v[206:207], s[22:23], 0, v[208:209]
	s_mov_b32 m0, s28
	ds_read_b128 v[174:177], v145 offset:16384
	ds_read_b128 v[178:181], v145 offset:17408
	ds_read_b128 v[182:185], v145 offset:18432
	ds_read_b128 v[186:189], v145 offset:19456
	ds_read_b128 v[190:193], v145 offset:20480
	ds_read_b128 v[194:197], v145 offset:21504
	ds_read_b128 v[198:201], v145 offset:22528
	ds_read_b128 v[202:205], v145 offset:23552
	global_load_lds_dwordx4 v208, s[22:23]
	s_add_i32 m0, s28, 0x2000
	s_add_u32 s52, s22, 0x40000
	v_lshl_add_u64 v[210:211], s[22:23], 0, v[128:129]
	s_addc_u32 s53, s23, 0
	s_add_i32 s28, s29, s26
	global_load_lds_dwordx4 v128, s[22:23]
	s_mov_b32 m0, s28
	v_lshl_add_u64 v[222:223], s[24:25], 0, v[130:131]
	global_load_lds_dwordx4 v208, s[52:53]
	s_add_i32 m0, s28, 0x2000
	s_nop 0
	global_load_lds_dwordx4 v128, s[52:53]
	v_lshl_add_u64 v[212:213], s[24:25], 0, v[132:133]
	s_mov_b32 m0, s21
	s_nop 0
	global_load_lds_dwordx4 v132, s[24:25]
	s_mov_b32 m0, s18
	s_nop 0
	global_load_lds_dwordx4 v130, s[24:25]
	s_waitcnt vmcnt(8)
	s_waitcnt lgkmcnt(0)
	s_barrier
; #define PG8_STAGE(bufoff, gbase, voff) do { _Pragma("unroll") for (int _i = 0; _i < 2; ++_i) \
;         __builtin_amdgcn_global_load_lds((const unsigned*)((const char*)(gbase) + (voff)[_i]), (PG8_LAS unsigned*)(lds + (bufoff) + ldsw + _i * 8192), 16, 0, 0); } while (0)
; #define PG8_LDA(dst, b, h) do { _Pragma("unroll") for (int m = 0; m < 4; ++m) _Pragma("unroll") for (int k = 0; k < 2; ++k) dst[m][k] = *(const PG8_LAS bf16x8*)(lds + PG8_SA(b, h) + aoff + m * 2048 + k * 1024); } while (0)
; #define PG8_LDB(dst, b, h) do { _Pragma("unroll") for (int n = 0; n < 2; ++n) _Pragma("unroll") for (int k = 0; k < 2; ++k) dst[n][k] = *(const PG8_LAS bf16x8*)(lds + PG8_SB(b, h) + boff + n * 2048 + k * 1024); } while (0)
; #define PG8_MMA(ai, bj, At, Bt) do { __builtin_amdgcn_s_setprio(1); _Pragma("unroll") for (int m = 0; m < 4; ++m) _Pragma("unroll") for (int n = 0; n < 2; ++n) _Pragma("unroll") for (int k = 0; k < 2; ++k) \
;         acc[ai][bj][m][n] = __builtin_amdgcn_mfma_f32_16x16x32_bf16(Bt[n][k], At[m][k], acc[ai][bj][m][n], 0, 0, 0); __builtin_amdgcn_s_setprio(0); } while (0)
; #define PG8_WAIT_V(n) asm volatile("s_waitcnt vmcnt(" #n ")" ::: "memory")
; #define PG8_WAIT_L(n) asm volatile("s_waitcnt lgkmcnt(" #n ")" ::: "memory")
; #define PG8_BAR __builtin_amdgcn_s_barrier()
; #define PG8_SCHED __builtin_amdgcn_sched_barrier(0)
; template <class Epi, class Sched, bool ALIGN_EPI = false, bool SP2 = false>
; __device__ __forceinline__ void gemm_phase(PG8_LAS unsigned char* lds, const Gemm g, const Sched& S, const Epi& E) {
;     ...
;             PG8_WAIT_V(8); PG8_WAIT_L(0); PG8_BAR; PG8_MMA(1, 0, At, B0); PG8_MMA(1, 1, At, B1); PG8_BAR; PG8_SCHED;
;             PG8_LDB(B0, 1, 0); PG8_LDB(B1, 1, 1); PG8_SCHED; PG8_LDA(At, 1, 0); PG8_STAGE(PG8_SA(0, 1), a2 + hstepA, voffA);
;             PG8_WAIT_V(8); PG8_WAIT_L(0); PG8_BAR; PG8_MMA(0, 0, At, B0); PG8_MMA(0, 1, At, B1); PG8_BAR; PG8_SCHED;
	v_mfma_f32_16x16x32_bf16 v[60:63], v[138:141], v[174:177], v[60:63]
	v_mfma_f32_16x16x32_bf16 v[56:59], v[150:153], v[174:177], v[56:59]
	v_mfma_f32_16x16x32_bf16 v[44:47], v[138:141], v[182:185], v[44:47]
	v_mfma_f32_16x16x32_bf16 v[40:43], v[150:153], v[182:185], v[40:43]
	v_mfma_f32_16x16x32_bf16 v[28:31], v[138:141], v[190:193], v[28:31]
	v_mfma_f32_16x16x32_bf16 v[24:27], v[150:153], v[190:193], v[24:27]
	v_mfma_f32_16x16x32_bf16 v[12:15], v[138:141], v[198:201], v[12:15]
	v_mfma_f32_16x16x32_bf16 v[8:11], v[150:153], v[198:201], v[8:11]
	v_mfma_f32_16x16x32_bf16 v[60:63], v[146:149], v[178:181], v[60:63]
	v_mfma_f32_16x16x32_bf16 v[56:59], v[154:157], v[178:181], v[56:59]
	v_mfma_f32_16x16x32_bf16 v[44:47], v[146:149], v[186:189], v[44:47]
	v_mfma_f32_16x16x32_bf16 v[40:43], v[154:157], v[186:189], v[40:43]
	v_mfma_f32_16x16x32_bf16 v[28:31], v[146:149], v[194:197], v[28:31]
	v_mfma_f32_16x16x32_bf16 v[24:27], v[154:157], v[194:197], v[24:27]
	v_mfma_f32_16x16x32_bf16 v[12:15], v[146:149], v[202:205], v[12:15]
	v_mfma_f32_16x16x32_bf16 v[8:11], v[154:157], v[202:205], v[8:11]
	v_mfma_f32_16x16x32_bf16 v[52:55], v[158:161], v[174:177], v[52:55]
	v_mfma_f32_16x16x32_bf16 v[48:51], v[166:169], v[174:177], v[48:51]
	v_mfma_f32_16x16x32_bf16 v[36:39], v[158:161], v[182:185], v[36:39]
	v_mfma_f32_16x16x32_bf16 v[32:35], v[166:169], v[182:185], v[32:35]
	v_mfma_f32_16x16x32_bf16 v[20:23], v[158:161], v[190:193], v[20:23]
	v_mfma_f32_16x16x32_bf16 v[16:19], v[166:169], v[190:193], v[16:19]
	v_mfma_f32_16x16x32_bf16 v[4:7], v[158:161], v[198:201], v[4:7]
	v_mfma_f32_16x16x32_bf16 v[0:3], v[166:169], v[198:201], v[0:3]
	v_mfma_f32_16x16x32_bf16 v[52:55], v[162:165], v[178:181], v[52:55]
	v_mfma_f32_16x16x32_bf16 v[48:51], v[170:173], v[178:181], v[48:51]
	v_mfma_f32_16x16x32_bf16 v[36:39], v[162:165], v[186:189], v[36:39]
	v_mfma_f32_16x16x32_bf16 v[32:35], v[170:173], v[186:189], v[32:35]
	v_mfma_f32_16x16x32_bf16 v[20:23], v[162:165], v[194:197], v[20:23]
	v_mfma_f32_16x16x32_bf16 v[16:19], v[170:173], v[194:197], v[16:19]
	v_mfma_f32_16x16x32_bf16 v[4:7], v[162:165], v[202:205], v[4:7]
	v_mfma_f32_16x16x32_bf16 v[0:3], v[170:173], v[202:205], v[0:3]
	s_barrier
	s_add_i32 s28, 0, 0x18000
	s_add_i32 s29, 0, 0x1c000
	v_add_u32_e32 v154, s28, v143
	v_add_u32_e32 v170, s29, v143
	ds_read_b128 v[138:141], v154
	ds_read_b128 v[146:149], v154 offset:1024
	ds_read_b128 v[150:153], v154 offset:2048
	ds_read_b128 v[154:157], v154 offset:3072
	ds_read_b128 v[158:161], v170
	ds_read_b128 v[162:165], v170 offset:1024
	ds_read_b128 v[166:169], v170 offset:2048
	ds_read_b128 v[170:173], v170 offset:3072
	s_add_u32 s24, s24, 0x40000
	s_addc_u32 s25, s25, 0
	s_mov_b32 m0, s19
	ds_read_b128 v[174:177], v145 offset:32768
	ds_read_b128 v[178:181], v145 offset:33792
	ds_read_b128 v[182:185], v145 offset:34816
	ds_read_b128 v[186:189], v145 offset:35840
	ds_read_b128 v[190:193], v145 offset:36864
	ds_read_b128 v[194:197], v145 offset:37888
	ds_read_b128 v[198:201], v145 offset:38912
	ds_read_b128 v[202:205], v145 offset:39936
	global_load_lds_dwordx4 v132, s[24:25]
	v_lshl_add_u64 v[224:225], s[24:25], 0, v[130:131]
	s_mov_b32 m0, s34
	s_nop 0
	global_load_lds_dwordx4 v130, s[24:25]
	s_waitcnt vmcnt(8)
	s_waitcnt lgkmcnt(0)
	s_barrier
	v_mfma_f32_16x16x32_bf16 v[124:127], v[138:141], v[174:177], v[124:127]
	v_mfma_f32_16x16x32_bf16 v[120:123], v[150:153], v[174:177], v[120:123]
	v_mfma_f32_16x16x32_bf16 v[108:111], v[138:141], v[182:185], v[108:111]
	v_mfma_f32_16x16x32_bf16 v[104:107], v[150:153], v[182:185], v[104:107]
	v_mfma_f32_16x16x32_bf16 v[92:95], v[138:141], v[190:193], v[92:95]
	v_mfma_f32_16x16x32_bf16 v[88:91], v[150:153], v[190:193], v[88:91]
	v_mfma_f32_16x16x32_bf16 v[76:79], v[138:141], v[198:201], v[76:79]
	v_mfma_f32_16x16x32_bf16 v[72:75], v[150:153], v[198:201], v[72:75]
	v_mfma_f32_16x16x32_bf16 v[124:127], v[146:149], v[178:181], v[124:127]
	v_mfma_f32_16x16x32_bf16 v[120:123], v[154:157], v[178:181], v[120:123]
	v_mfma_f32_16x16x32_bf16 v[108:111], v[146:149], v[186:189], v[108:111]
	v_mfma_f32_16x16x32_bf16 v[104:107], v[154:157], v[186:189], v[104:107]
	v_mfma_f32_16x16x32_bf16 v[92:95], v[146:149], v[194:197], v[92:95]
	v_mfma_f32_16x16x32_bf16 v[88:91], v[154:157], v[194:197], v[88:91]
	v_mfma_f32_16x16x32_bf16 v[76:79], v[146:149], v[202:205], v[76:79]
	v_mfma_f32_16x16x32_bf16 v[72:75], v[154:157], v[202:205], v[72:75]
	v_mfma_f32_16x16x32_bf16 v[116:119], v[158:161], v[174:177], v[116:119]
	v_mfma_f32_16x16x32_bf16 v[112:115], v[166:169], v[174:177], v[112:115]
	v_mfma_f32_16x16x32_bf16 v[100:103], v[158:161], v[182:185], v[100:103]
	v_mfma_f32_16x16x32_bf16 v[96:99], v[166:169], v[182:185], v[96:99]
	v_mfma_f32_16x16x32_bf16 v[84:87], v[158:161], v[190:193], v[84:87]
	v_mfma_f32_16x16x32_bf16 v[80:83], v[166:169], v[190:193], v[80:83]
	v_mfma_f32_16x16x32_bf16 v[68:71], v[158:161], v[198:201], v[68:71]
	v_mfma_f32_16x16x32_bf16 v[64:67], v[166:169], v[198:201], v[64:67]
	v_mfma_f32_16x16x32_bf16 v[116:119], v[162:165], v[178:181], v[116:119]
	v_mfma_f32_16x16x32_bf16 v[112:115], v[170:173], v[178:181], v[112:115]
	v_mfma_f32_16x16x32_bf16 v[100:103], v[162:165], v[186:189], v[100:103]
	v_mfma_f32_16x16x32_bf16 v[96:99], v[170:173], v[186:189], v[96:99]
	v_mfma_f32_16x16x32_bf16 v[84:87], v[162:165], v[194:197], v[84:87]
	v_mfma_f32_16x16x32_bf16 v[80:83], v[170:173], v[194:197], v[80:83]
	v_mfma_f32_16x16x32_bf16 v[68:71], v[162:165], v[202:205], v[68:71]
	v_mfma_f32_16x16x32_bf16 v[64:67], v[170:173], v[202:205], v[64:67]
	s_barrier
; #define PG8_STAGE(bufoff, gbase, voff) do { _Pragma("unroll") for (int _i = 0; _i < 2; ++_i) \
;         __builtin_amdgcn_global_load_lds((const unsigned*)((const char*)(gbase) + (voff)[_i]), (PG8_LAS unsigned*)(lds + (bufoff) + ldsw + _i * 8192), 16, 0, 0); } while (0)
; #define PG8_LDA(dst, b, h) do { _Pragma("unroll") for (int m = 0; m < 4; ++m) _Pragma("unroll") for (int k = 0; k < 2; ++k) dst[m][k] = *(const PG8_LAS bf16x8*)(lds + PG8_SA(b, h) + aoff + m * 2048 + k * 1024); } while (0)
; #define PG8_MMA(ai, bj, At, Bt) do { __builtin_amdgcn_s_setprio(1); _Pragma("unroll") for (int m = 0; m < 4; ++m) _Pragma("unroll") for (int n = 0; n < 2; ++n) _Pragma("unroll") for (int k = 0; k < 2; ++k) \
;         acc[ai][bj][m][n] = __builtin_amdgcn_mfma_f32_16x16x32_bf16(Bt[n][k], At[m][k], acc[ai][bj][m][n], 0, 0, 0); __builtin_amdgcn_s_setprio(0); } while (0)
; #define PG8_WAIT_V(n) asm volatile("s_waitcnt vmcnt(" #n ")" ::: "memory")
; #define PG8_WAIT_L(n) asm volatile("s_waitcnt lgkmcnt(" #n ")" ::: "memory")
; #define PG8_BAR __builtin_amdgcn_s_barrier()
; #define PG8_SCHED __builtin_amdgcn_sched_barrier(0)
; template <class Epi, class Sched, bool ALIGN_EPI = false, bool SP2 = false>
; __device__ __forceinline__ void gemm_phase(PG8_LAS unsigned char* lds, const Gemm g, const Sched& S, const Epi& E) {
;     ...
;             PG8_LDA(At, 1, 1); PG8_STAGE(PG8_SB(1, 0), b3, voffB); PG8_STAGE(PG8_SB(1, 1), b3 + hstepB, voffB); PG8_STAGE(PG8_SA(1, 0), a3, voffA);
;             PG8_WAIT_V(8); PG8_WAIT_L(0); PG8_BAR; PG8_MMA(1, 0, At, B0); PG8_MMA(1, 1, At, B1); PG8_BAR; PG8_SCHED;
;     ...
;         if constexpr (ALIGN_EPI) { if (wr == 0) PG8_BAR; }
	s_add_i32 s24, s28, s26
	v_lshl_add_u64 v[206:207], v[206:207], 0, s[10:11]
	s_mov_b32 m0, s24
	ds_read_b128 v[174:177], v145 offset:49152
	ds_read_b128 v[178:181], v145 offset:50176
	ds_read_b128 v[182:185], v145 offset:51200
	ds_read_b128 v[186:189], v145 offset:52224
	ds_read_b128 v[190:193], v145 offset:53248
	ds_read_b128 v[194:197], v145 offset:54272
	ds_read_b128 v[198:201], v145 offset:55296
	ds_read_b128 v[202:205], v145 offset:56320
	global_load_lds_dwordx4 v[206:207], off
	s_add_i32 m0, s24, 0x2000
	s_add_u32 s22, s22, 0x40080
	v_lshl_add_u64 v[206:207], v[210:211], 0, s[10:11]
	s_addc_u32 s23, s23, 0
	s_add_i32 s24, s29, s26
	global_load_lds_dwordx4 v[206:207], off
	s_mov_b32 m0, s24
	s_nop 0
	global_load_lds_dwordx4 v208, s[22:23]
	s_add_i32 m0, s24, 0x2000
	s_nop 0
	global_load_lds_dwordx4 v128, s[22:23]
	v_lshl_add_u64 v[206:207], v[212:213], 0, s[10:11]
	s_mov_b32 m0, s35
	s_nop 0
	global_load_lds_dwordx4 v[206:207], off
	v_lshl_add_u64 v[206:207], v[222:223], 0, s[10:11]
	s_mov_b32 m0, s39
	s_nop 0
	global_load_lds_dwordx4 v[206:207], off
	s_waitcnt vmcnt(8)
	s_waitcnt lgkmcnt(0)
	s_barrier
	v_mfma_f32_16x16x32_bf16 v[60:63], v[138:141], v[174:177], v[60:63]
	v_mfma_f32_16x16x32_bf16 v[56:59], v[150:153], v[174:177], v[56:59]
	v_mfma_f32_16x16x32_bf16 v[44:47], v[138:141], v[182:185], v[44:47]
	v_mfma_f32_16x16x32_bf16 v[40:43], v[150:153], v[182:185], v[40:43]
	v_mfma_f32_16x16x32_bf16 v[28:31], v[138:141], v[190:193], v[28:31]
	v_mfma_f32_16x16x32_bf16 v[24:27], v[150:153], v[190:193], v[24:27]
	v_mfma_f32_16x16x32_bf16 v[12:15], v[138:141], v[198:201], v[12:15]
	v_mfma_f32_16x16x32_bf16 v[8:11], v[150:153], v[198:201], v[8:11]
	v_mfma_f32_16x16x32_bf16 v[60:63], v[146:149], v[178:181], v[60:63]
	v_mfma_f32_16x16x32_bf16 v[56:59], v[154:157], v[178:181], v[56:59]
	v_mfma_f32_16x16x32_bf16 v[44:47], v[146:149], v[186:189], v[44:47]
	v_mfma_f32_16x16x32_bf16 v[40:43], v[154:157], v[186:189], v[40:43]
	v_mfma_f32_16x16x32_bf16 v[28:31], v[146:149], v[194:197], v[28:31]
	v_mfma_f32_16x16x32_bf16 v[24:27], v[154:157], v[194:197], v[24:27]
	v_mfma_f32_16x16x32_bf16 v[12:15], v[146:149], v[202:205], v[12:15]
	v_mfma_f32_16x16x32_bf16 v[8:11], v[154:157], v[202:205], v[8:11]
	v_mfma_f32_16x16x32_bf16 v[52:55], v[158:161], v[174:177], v[52:55]
	v_mfma_f32_16x16x32_bf16 v[48:51], v[166:169], v[174:177], v[48:51]
	v_mfma_f32_16x16x32_bf16 v[36:39], v[158:161], v[182:185], v[36:39]
	v_mfma_f32_16x16x32_bf16 v[32:35], v[166:169], v[182:185], v[32:35]
	v_mfma_f32_16x16x32_bf16 v[20:23], v[158:161], v[190:193], v[20:23]
	v_mfma_f32_16x16x32_bf16 v[16:19], v[166:169], v[190:193], v[16:19]
	v_mfma_f32_16x16x32_bf16 v[4:7], v[158:161], v[198:201], v[4:7]
	v_mfma_f32_16x16x32_bf16 v[0:3], v[166:169], v[198:201], v[0:3]
	v_mfma_f32_16x16x32_bf16 v[52:55], v[162:165], v[178:181], v[52:55]
	v_mfma_f32_16x16x32_bf16 v[48:51], v[170:173], v[178:181], v[48:51]
	v_mfma_f32_16x16x32_bf16 v[36:39], v[162:165], v[186:189], v[36:39]
	v_mfma_f32_16x16x32_bf16 v[32:35], v[170:173], v[186:189], v[32:35]
	v_mfma_f32_16x16x32_bf16 v[20:23], v[162:165], v[194:197], v[20:23]
	v_mfma_f32_16x16x32_bf16 v[16:19], v[170:173], v[194:197], v[16:19]
	v_mfma_f32_16x16x32_bf16 v[4:7], v[162:165], v[202:205], v[4:7]
	v_mfma_f32_16x16x32_bf16 v[0:3], v[170:173], v[202:205], v[0:3]
	s_barrier
	s_add_i32 s51, s51, 2
	s_add_u32 s0, s0, 0x100
	s_addc_u32 s1, s1, 0
	s_add_u32 s43, s43, 0x100
	s_addc_u32 s50, s50, 0
	s_cmp_gt_u32 s51, 13
	s_cbranch_scc0 .LBB0_607
	s_and_b64 vcc, exec, s[6:7]
	s_cbranch_vccz .LBB0_610
	s_barrier

; #define PG8_STAGE(bufoff, gbase, voff) do { _Pragma("unroll") for (int _i = 0; _i < 2; ++_i) \
;         __builtin_amdgcn_global_load_lds((const unsigned*)((const char*)(gbase) + (voff)[_i]), (PG8_LAS unsigned*)(lds + (bufoff) + ldsw + _i * 8192), 16, 0, 0); } while (0)
; #define PG8_LDA(dst, b, h) do { _Pragma("unroll") for (int m = 0; m < 4; ++m) _Pragma("unroll") for (int k = 0; k < 2; ++k) dst[m][k] = *(const PG8_LAS bf16x8*)(lds + PG8_SA(b, h) + aoff + m * 2048 + k * 1024); } while (0)
; #define PG8_LDB(dst, b, h) do { _Pragma("unroll") for (int n = 0; n < 2; ++n) _Pragma("unroll") for (int k = 0; k < 2; ++k) dst[n][k] = *(const PG8_LAS bf16x8*)(lds + PG8_SB(b, h) + boff + n * 2048 + k * 1024); } while (0)
; #define PG8_WAIT_V(n) asm volatile("s_waitcnt vmcnt(" #n ")" ::: "memory")
; #define PG8_WAIT_L(n) asm volatile("s_waitcnt lgkmcnt(" #n ")" ::: "memory")
; #define PG8_BAR __builtin_amdgcn_s_barrier()
; #define PG8_SCHED __builtin_amdgcn_sched_barrier(0)
; template <class Epi, class Sched, bool ALIGN_EPI = false, bool SP2 = false>
; __device__ __forceinline__ void gemm_phase(PG8_LAS unsigned char* lds, const Gemm g, const Sched& S, const Epi& E) {
;     ...
;         const char* nA = has_next ? (const char*)g.A + (size_t)nxt.pm * tstepA : cA; const char* nB = has_next ? (const char*)g.Bt + (size_t)nxt.pn * tstepB : cB;
;         for (int t = 0; t < nt; t += 2) {
;             const bool last = (t == nt - 2);
;             const char* a1 = cA + (size_t)(t + 1) * kstep;
;             const char* a2 = last ? nA : cA + (size_t)(t + 2) * kstep; const char* b2 = last ? nB : cB + (size_t)(t + 2) * kstep;
;             const char* a3 = a2 + kstep; const char* b3 = b2 + kstep;
;             if (last && has_next) S.a_ready(nxt);
;             if constexpr (SP2) {
;             PG8_LDB(B0, 0, 0); PG8_LDB(B1, 0, 1); PG8_SCHED; PG8_LDA(At, 0, 0); PG8_STAGE(PG8_SA(1, 1), a1 + hstepA, voffA);
;             PG8_WAIT_V(8); PG8_WAIT_L(0); PG8_BAR; PG8_MMA(0, 0, At, B0); PG8_MMA(0, 1, At, B1); PG8_BAR; PG8_SCHED;
;             PG8_LDA(At, 0, 1); PG8_STAGE(PG8_SB(0, 0), b2, voffB); PG8_STAGE(PG8_SB(0, 1), b2 + hstepB, voffB); PG8_STAGE(PG8_SA(0, 0), a2, voffA);
;             PG8_WAIT_V(8); PG8_WAIT_L(0); PG8_BAR; PG8_MMA(1, 0, At, B0); PG8_MMA(1, 1, At, B1); PG8_BAR; PG8_SCHED;
.LBB0_690:
	s_add_u32 s4, s0, 0x100
	s_addc_u32 s5, s1, 0
	s_add_i32 s28, 0, 0x10000
	s_cmp_eq_u32 s34, 4
	s_cselect_b32 s23, s49, s5
	s_cselect_b32 s22, s48, s4
	s_cselect_b32 s21, s14, s19
	s_cselect_b32 s20, s15, s18
	s_add_i32 s29, 0, 0x14000
	v_add_u32_e32 v140, s28, v211
	v_add_u32_e32 v156, s29, v211
	ds_read_b128 v[128:131], v140
	ds_read_b128 v[132:135], v140 offset:1024
	ds_read_b128 v[136:139], v140 offset:2048
	ds_read_b128 v[140:143], v140 offset:3072
	ds_read_b128 v[144:147], v156
	ds_read_b128 v[148:151], v156 offset:1024
	ds_read_b128 v[152:155], v156 offset:2048
	ds_read_b128 v[156:159], v156 offset:3072
	v_lshl_add_u64 v[202:203], s[0:1], 0, v[198:199]
	s_add_i32 m0, s53, 0xc000
	ds_read_b128 v[160:163], v231
	ds_read_b128 v[164:167], v231 offset:1024
	ds_read_b128 v[168:171], v231 offset:2048
	ds_read_b128 v[172:175], v231 offset:3072
	ds_read_b128 v[176:179], v231 offset:4096
	ds_read_b128 v[180:183], v231 offset:5120
	ds_read_b128 v[184:187], v231 offset:6144
	ds_read_b128 v[188:191], v231 offset:7168
	global_load_lds_dwordx4 v[202:203], off
	v_lshl_add_u64 v[202:203], s[0:1], 0, v[200:201]
	s_add_i32 m0, s53, 0xe000
	s_nop 0
	global_load_lds_dwordx4 v[202:203], off
	s_waitcnt vmcnt(8)
	s_waitcnt lgkmcnt(0)
	s_barrier
	v_mfma_f32_16x16x32_bf16 v[124:127], v[128:131], v[160:163], v[124:127]
	v_mfma_f32_16x16x32_bf16 v[120:123], v[136:139], v[160:163], v[120:123]
	v_mfma_f32_16x16x32_bf16 v[112:115], v[128:131], v[168:171], v[112:115]
	v_mfma_f32_16x16x32_bf16 v[104:107], v[136:139], v[168:171], v[104:107]
	v_mfma_f32_16x16x32_bf16 v[96:99], v[128:131], v[176:179], v[96:99]
	v_mfma_f32_16x16x32_bf16 v[88:91], v[136:139], v[176:179], v[88:91]
	v_mfma_f32_16x16x32_bf16 v[80:83], v[128:131], v[184:187], v[80:83]
	v_mfma_f32_16x16x32_bf16 v[72:75], v[136:139], v[184:187], v[72:75]
	v_mfma_f32_16x16x32_bf16 v[124:127], v[132:135], v[164:167], v[124:127]
	v_mfma_f32_16x16x32_bf16 v[120:123], v[140:143], v[164:167], v[120:123]
	v_mfma_f32_16x16x32_bf16 v[112:115], v[132:135], v[172:175], v[112:115]
	v_mfma_f32_16x16x32_bf16 v[104:107], v[140:143], v[172:175], v[104:107]
	v_mfma_f32_16x16x32_bf16 v[96:99], v[132:135], v[180:183], v[96:99]
	v_mfma_f32_16x16x32_bf16 v[88:91], v[140:143], v[180:183], v[88:91]
	v_mfma_f32_16x16x32_bf16 v[80:83], v[132:135], v[188:191], v[80:83]
	v_mfma_f32_16x16x32_bf16 v[72:75], v[140:143], v[188:191], v[72:75]
	v_mfma_f32_16x16x32_bf16 v[116:119], v[144:147], v[160:163], v[116:119]
	v_mfma_f32_16x16x32_bf16 v[108:111], v[152:155], v[160:163], v[108:111]
	v_mfma_f32_16x16x32_bf16 v[100:103], v[144:147], v[168:171], v[100:103]
	v_mfma_f32_16x16x32_bf16 v[92:95], v[152:155], v[168:171], v[92:95]
	v_mfma_f32_16x16x32_bf16 v[84:87], v[144:147], v[176:179], v[84:87]
	v_mfma_f32_16x16x32_bf16 v[76:79], v[152:155], v[176:179], v[76:79]
	v_mfma_f32_16x16x32_bf16 v[68:71], v[144:147], v[184:187], v[68:71]
	v_mfma_f32_16x16x32_bf16 v[64:67], v[152:155], v[184:187], v[64:67]
	v_mfma_f32_16x16x32_bf16 v[116:119], v[148:151], v[164:167], v[116:119]
	v_mfma_f32_16x16x32_bf16 v[108:111], v[156:159], v[164:167], v[108:111]
	v_mfma_f32_16x16x32_bf16 v[100:103], v[148:151], v[172:175], v[100:103]
	v_mfma_f32_16x16x32_bf16 v[92:95], v[156:159], v[172:175], v[92:95]
	v_mfma_f32_16x16x32_bf16 v[84:87], v[148:151], v[180:183], v[84:87]
	v_mfma_f32_16x16x32_bf16 v[76:79], v[156:159], v[180:183], v[76:79]
	v_mfma_f32_16x16x32_bf16 v[68:71], v[148:151], v[188:191], v[68:71]
	v_mfma_f32_16x16x32_bf16 v[64:67], v[156:159], v[188:191], v[64:67]
	s_barrier
	s_add_i32 s0, s28, s56
	v_lshl_add_u64 v[202:203], s[20:21], 0, v[208:209]
	s_mov_b32 m0, s0
	ds_read_b128 v[160:163], v231 offset:16384
	ds_read_b128 v[164:167], v231 offset:17408
	ds_read_b128 v[168:171], v231 offset:18432
	ds_read_b128 v[172:175], v231 offset:19456
	ds_read_b128 v[176:179], v231 offset:20480
	ds_read_b128 v[180:183], v231 offset:21504
	ds_read_b128 v[184:187], v231 offset:22528
	ds_read_b128 v[188:191], v231 offset:23552
	global_load_lds_dwordx4 v208, s[20:21]
	s_add_i32 m0, s0, 0x2000
	s_add_u32 s0, s20, 0x20000
	v_lshl_add_u64 v[204:205], s[20:21], 0, v[196:197]
	s_addc_u32 s1, s21, 0
	s_add_i32 s28, s29, s56
	global_load_lds_dwordx4 v196, s[20:21]
	s_mov_b32 m0, s28
	v_lshl_add_u64 v[212:213], s[22:23], 0, v[194:195]
	global_load_lds_dwordx4 v208, s[0:1]
	s_add_i32 m0, s28, 0x2000
	s_nop 0
	global_load_lds_dwordx4 v196, s[0:1]
	v_lshl_add_u64 v[206:207], s[22:23], 0, v[192:193]
	s_mov_b32 m0, s53
	s_nop 0
	global_load_lds_dwordx4 v192, s[22:23]
	s_mov_b32 m0, s57
	s_nop 0
	global_load_lds_dwordx4 v194, s[22:23]
	s_waitcnt vmcnt(8)
	s_waitcnt lgkmcnt(0)
	s_barrier
; #define PG8_STAGE(bufoff, gbase, voff) do { _Pragma("unroll") for (int _i = 0; _i < 2; ++_i) \
;         __builtin_amdgcn_global_load_lds((const unsigned*)((const char*)(gbase) + (voff)[_i]), (PG8_LAS unsigned*)(lds + (bufoff) + ldsw + _i * 8192), 16, 0, 0); } while (0)
; #define PG8_LDA(dst, b, h) do { _Pragma("unroll") for (int m = 0; m < 4; ++m) _Pragma("unroll") for (int k = 0; k < 2; ++k) dst[m][k] = *(const PG8_LAS bf16x8*)(lds + PG8_SA(b, h) + aoff + m * 2048 + k * 1024); } while (0)
; #define PG8_LDB(dst, b, h) do { _Pragma("unroll") for (int n = 0; n < 2; ++n) _Pragma("unroll") for (int k = 0; k < 2; ++k) dst[n][k] = *(const PG8_LAS bf16x8*)(lds + PG8_SB(b, h) + boff + n * 2048 + k * 1024); } while (0)
; #define PG8_MMA(ai, bj, At, Bt) do { __builtin_amdgcn_s_setprio(1); _Pragma("unroll") for (int m = 0; m < 4; ++m) _Pragma("unroll") for (int n = 0; n < 2; ++n) _Pragma("unroll") for (int k = 0; k < 2; ++k) \
;         acc[ai][bj][m][n] = __builtin_amdgcn_mfma_f32_16x16x32_bf16(Bt[n][k], At[m][k], acc[ai][bj][m][n], 0, 0, 0); __builtin_amdgcn_s_setprio(0); } while (0)
; #define PG8_WAIT_V(n) asm volatile("s_waitcnt vmcnt(" #n ")" ::: "memory")
; #define PG8_WAIT_L(n) asm volatile("s_waitcnt lgkmcnt(" #n ")" ::: "memory")
; #define PG8_BAR __builtin_amdgcn_s_barrier()
; #define PG8_SCHED __builtin_amdgcn_sched_barrier(0)
; template <class Epi, class Sched, bool ALIGN_EPI = false, bool SP2 = false>
; __device__ __forceinline__ void gemm_phase(PG8_LAS unsigned char* lds, const Gemm g, const Sched& S, const Epi& E) {
;     ...
;             PG8_WAIT_V(8); PG8_WAIT_L(0); PG8_BAR; PG8_MMA(1, 0, At, B0); PG8_MMA(1, 1, At, B1); PG8_BAR; PG8_SCHED;
;             PG8_LDB(B0, 1, 0); PG8_LDB(B1, 1, 1); PG8_SCHED; PG8_LDA(At, 1, 0); PG8_STAGE(PG8_SA(0, 1), a2 + hstepA, voffA);
;             PG8_WAIT_V(8); PG8_WAIT_L(0); PG8_BAR; PG8_MMA(0, 0, At, B0); PG8_MMA(0, 1, At, B1); PG8_BAR; PG8_SCHED;
	v_mfma_f32_16x16x32_bf16 v[60:63], v[128:131], v[160:163], v[60:63]
	v_mfma_f32_16x16x32_bf16 v[56:59], v[136:139], v[160:163], v[56:59]
	v_mfma_f32_16x16x32_bf16 v[48:51], v[128:131], v[168:171], v[48:51]
	v_mfma_f32_16x16x32_bf16 v[40:43], v[136:139], v[168:171], v[40:43]
	v_mfma_f32_16x16x32_bf16 v[32:35], v[128:131], v[176:179], v[32:35]
	v_mfma_f32_16x16x32_bf16 v[24:27], v[136:139], v[176:179], v[24:27]
	v_mfma_f32_16x16x32_bf16 v[16:19], v[128:131], v[184:187], v[16:19]
	v_mfma_f32_16x16x32_bf16 v[8:11], v[136:139], v[184:187], v[8:11]
	v_mfma_f32_16x16x32_bf16 v[60:63], v[132:135], v[164:167], v[60:63]
	v_mfma_f32_16x16x32_bf16 v[56:59], v[140:143], v[164:167], v[56:59]
	v_mfma_f32_16x16x32_bf16 v[48:51], v[132:135], v[172:175], v[48:51]
	v_mfma_f32_16x16x32_bf16 v[40:43], v[140:143], v[172:175], v[40:43]
	v_mfma_f32_16x16x32_bf16 v[32:35], v[132:135], v[180:183], v[32:35]
	v_mfma_f32_16x16x32_bf16 v[24:27], v[140:143], v[180:183], v[24:27]
	v_mfma_f32_16x16x32_bf16 v[16:19], v[132:135], v[188:191], v[16:19]
	v_mfma_f32_16x16x32_bf16 v[8:11], v[140:143], v[188:191], v[8:11]
	v_mfma_f32_16x16x32_bf16 v[52:55], v[144:147], v[160:163], v[52:55]
	v_mfma_f32_16x16x32_bf16 v[44:47], v[152:155], v[160:163], v[44:47]
	v_mfma_f32_16x16x32_bf16 v[36:39], v[144:147], v[168:171], v[36:39]
	v_mfma_f32_16x16x32_bf16 v[28:31], v[152:155], v[168:171], v[28:31]
	v_mfma_f32_16x16x32_bf16 v[20:23], v[144:147], v[176:179], v[20:23]
	v_mfma_f32_16x16x32_bf16 v[12:15], v[152:155], v[176:179], v[12:15]
	v_mfma_f32_16x16x32_bf16 v[4:7], v[144:147], v[184:187], v[4:7]
	v_mfma_f32_16x16x32_bf16 v[0:3], v[152:155], v[184:187], v[0:3]
	v_mfma_f32_16x16x32_bf16 v[52:55], v[148:151], v[164:167], v[52:55]
	v_mfma_f32_16x16x32_bf16 v[44:47], v[156:159], v[164:167], v[44:47]
	v_mfma_f32_16x16x32_bf16 v[36:39], v[148:151], v[172:175], v[36:39]
	v_mfma_f32_16x16x32_bf16 v[28:31], v[156:159], v[172:175], v[28:31]
	v_mfma_f32_16x16x32_bf16 v[20:23], v[148:151], v[180:183], v[20:23]
	v_mfma_f32_16x16x32_bf16 v[12:15], v[156:159], v[180:183], v[12:15]
	v_mfma_f32_16x16x32_bf16 v[4:7], v[148:151], v[188:191], v[4:7]
	v_mfma_f32_16x16x32_bf16 v[0:3], v[156:159], v[188:191], v[0:3]
	s_barrier
	s_add_i32 s28, 0, 0x18000
	s_add_i32 s29, 0, 0x1c000
	v_add_u32_e32 v140, s28, v211
	v_add_u32_e32 v156, s29, v211
	ds_read_b128 v[128:131], v140
	ds_read_b128 v[132:135], v140 offset:1024
	ds_read_b128 v[136:139], v140 offset:2048
	ds_read_b128 v[140:143], v140 offset:3072
	ds_read_b128 v[144:147], v156
	ds_read_b128 v[148:151], v156 offset:1024
	ds_read_b128 v[152:155], v156 offset:2048
	ds_read_b128 v[156:159], v156 offset:3072
	s_add_u32 s0, s22, 0x60000
	s_addc_u32 s1, s23, 0
	s_mov_b32 m0, s58
	ds_read_b128 v[160:163], v231 offset:32768
	ds_read_b128 v[164:167], v231 offset:33792
	ds_read_b128 v[168:171], v231 offset:34816
	ds_read_b128 v[172:175], v231 offset:35840
	ds_read_b128 v[176:179], v231 offset:36864
	ds_read_b128 v[180:183], v231 offset:37888
	ds_read_b128 v[184:187], v231 offset:38912
	ds_read_b128 v[188:191], v231 offset:39936
	global_load_lds_dwordx4 v192, s[0:1]
	s_mov_b32 m0, s59
	s_nop 0
	global_load_lds_dwordx4 v194, s[0:1]
	s_waitcnt vmcnt(8)
	s_waitcnt lgkmcnt(0)
	s_barrier
	v_mfma_f32_16x16x32_bf16 v[124:127], v[128:131], v[160:163], v[124:127]
	v_mfma_f32_16x16x32_bf16 v[120:123], v[136:139], v[160:163], v[120:123]
	v_mfma_f32_16x16x32_bf16 v[112:115], v[128:131], v[168:171], v[112:115]
	v_mfma_f32_16x16x32_bf16 v[104:107], v[136:139], v[168:171], v[104:107]
	v_mfma_f32_16x16x32_bf16 v[96:99], v[128:131], v[176:179], v[96:99]
	v_mfma_f32_16x16x32_bf16 v[88:91], v[136:139], v[176:179], v[88:91]
	v_mfma_f32_16x16x32_bf16 v[80:83], v[128:131], v[184:187], v[80:83]
	v_mfma_f32_16x16x32_bf16 v[72:75], v[136:139], v[184:187], v[72:75]
	v_mfma_f32_16x16x32_bf16 v[124:127], v[132:135], v[164:167], v[124:127]
	v_mfma_f32_16x16x32_bf16 v[120:123], v[140:143], v[164:167], v[120:123]
	v_mfma_f32_16x16x32_bf16 v[112:115], v[132:135], v[172:175], v[112:115]
	v_mfma_f32_16x16x32_bf16 v[104:107], v[140:143], v[172:175], v[104:107]
	v_mfma_f32_16x16x32_bf16 v[96:99], v[132:135], v[180:183], v[96:99]
	v_mfma_f32_16x16x32_bf16 v[88:91], v[140:143], v[180:183], v[88:91]
	v_mfma_f32_16x16x32_bf16 v[80:83], v[132:135], v[188:191], v[80:83]
	v_mfma_f32_16x16x32_bf16 v[72:75], v[140:143], v[188:191], v[72:75]
	v_mfma_f32_16x16x32_bf16 v[116:119], v[144:147], v[160:163], v[116:119]
	v_mfma_f32_16x16x32_bf16 v[108:111], v[152:155], v[160:163], v[108:111]
	v_mfma_f32_16x16x32_bf16 v[100:103], v[144:147], v[168:171], v[100:103]
	v_mfma_f32_16x16x32_bf16 v[92:95], v[152:155], v[168:171], v[92:95]
	v_mfma_f32_16x16x32_bf16 v[84:87], v[144:147], v[176:179], v[84:87]
	v_mfma_f32_16x16x32_bf16 v[76:79], v[152:155], v[176:179], v[76:79]
	v_mfma_f32_16x16x32_bf16 v[68:71], v[144:147], v[184:187], v[68:71]
	v_mfma_f32_16x16x32_bf16 v[64:67], v[152:155], v[184:187], v[64:67]
	v_mfma_f32_16x16x32_bf16 v[116:119], v[148:151], v[164:167], v[116:119]
	v_mfma_f32_16x16x32_bf16 v[108:111], v[156:159], v[164:167], v[108:111]
	v_mfma_f32_16x16x32_bf16 v[100:103], v[148:151], v[172:175], v[100:103]
	v_mfma_f32_16x16x32_bf16 v[92:95], v[156:159], v[172:175], v[92:95]
	v_mfma_f32_16x16x32_bf16 v[84:87], v[148:151], v[180:183], v[84:87]
	v_mfma_f32_16x16x32_bf16 v[76:79], v[156:159], v[180:183], v[76:79]
	v_mfma_f32_16x16x32_bf16 v[68:71], v[148:151], v[188:191], v[68:71]
	v_mfma_f32_16x16x32_bf16 v[64:67], v[156:159], v[188:191], v[64:67]
	s_barrier
; #define PG8_STAGE(bufoff, gbase, voff) do { _Pragma("unroll") for (int _i = 0; _i < 2; ++_i) \
;         __builtin_amdgcn_global_load_lds((const unsigned*)((const char*)(gbase) + (voff)[_i]), (PG8_LAS unsigned*)(lds + (bufoff) + ldsw + _i * 8192), 16, 0, 0); } while (0)
; #define PG8_LDA(dst, b, h) do { _Pragma("unroll") for (int m = 0; m < 4; ++m) _Pragma("unroll") for (int k = 0; k < 2; ++k) dst[m][k] = *(const PG8_LAS bf16x8*)(lds + PG8_SA(b, h) + aoff + m * 2048 + k * 1024); } while (0)
; #define PG8_MMA(ai, bj, At, Bt) do { __builtin_amdgcn_s_setprio(1); _Pragma("unroll") for (int m = 0; m < 4; ++m) _Pragma("unroll") for (int n = 0; n < 2; ++n) _Pragma("unroll") for (int k = 0; k < 2; ++k) \
;         acc[ai][bj][m][n] = __builtin_amdgcn_mfma_f32_16x16x32_bf16(Bt[n][k], At[m][k], acc[ai][bj][m][n], 0, 0, 0); __builtin_amdgcn_s_setprio(0); } while (0)
; #define PG8_WAIT_V(n) asm volatile("s_waitcnt vmcnt(" #n ")" ::: "memory")
; #define PG8_WAIT_L(n) asm volatile("s_waitcnt lgkmcnt(" #n ")" ::: "memory")
; #define PG8_BAR __builtin_amdgcn_s_barrier()
; #define PG8_SCHED __builtin_amdgcn_sched_barrier(0)
; template <class Epi, class Sched, bool ALIGN_EPI = false, bool SP2 = false>
; __device__ __forceinline__ void gemm_phase(PG8_LAS unsigned char* lds, const Gemm g, const Sched& S, const Epi& E) {
;     ...
;             PG8_LDA(At, 1, 1); PG8_STAGE(PG8_SB(1, 0), b3, voffB); PG8_STAGE(PG8_SB(1, 1), b3 + hstepB, voffB); PG8_STAGE(PG8_SA(1, 0), a3, voffA);
;             PG8_WAIT_V(8); PG8_WAIT_L(0); PG8_BAR; PG8_MMA(1, 0, At, B0); PG8_MMA(1, 1, At, B1); PG8_BAR; PG8_SCHED;
;     ...
;         if constexpr (ALIGN_EPI) { if (wr == 0) PG8_BAR; }
	s_add_i32 s0, s28, s56
	v_lshl_add_u64 v[202:203], v[202:203], 0, s[10:11]
	s_mov_b32 m0, s0
	ds_read_b128 v[160:163], v231 offset:49152
	ds_read_b128 v[164:167], v231 offset:50176
	ds_read_b128 v[168:171], v231 offset:51200
	ds_read_b128 v[172:175], v231 offset:52224
	ds_read_b128 v[176:179], v231 offset:53248
	ds_read_b128 v[180:183], v231 offset:54272
	ds_read_b128 v[184:187], v231 offset:55296
	ds_read_b128 v[188:191], v231 offset:56320
	global_load_lds_dwordx4 v[202:203], off
	s_add_i32 m0, s0, 0x2000
	s_add_u32 s0, s20, 0x20080
	v_lshl_add_u64 v[202:203], v[204:205], 0, s[10:11]
	s_addc_u32 s1, s21, 0
	s_add_i32 s20, s29, s56
	global_load_lds_dwordx4 v[202:203], off
	s_mov_b32 m0, s20
	s_nop 0
	global_load_lds_dwordx4 v208, s[0:1]
	s_add_i32 m0, s20, 0x2000
	s_nop 0
	global_load_lds_dwordx4 v196, s[0:1]
	v_lshl_add_u64 v[202:203], v[206:207], 0, s[10:11]
	s_mov_b32 m0, s61
	s_nop 0
	global_load_lds_dwordx4 v[202:203], off
	v_lshl_add_u64 v[202:203], v[212:213], 0, s[10:11]
	s_mov_b32 m0, s62
	s_nop 0
	global_load_lds_dwordx4 v[202:203], off
	s_waitcnt vmcnt(8)
	s_waitcnt lgkmcnt(0)
	s_barrier
	v_mfma_f32_16x16x32_bf16 v[60:63], v[128:131], v[160:163], v[60:63]
	v_mfma_f32_16x16x32_bf16 v[56:59], v[136:139], v[160:163], v[56:59]
	v_mfma_f32_16x16x32_bf16 v[48:51], v[128:131], v[168:171], v[48:51]
	v_mfma_f32_16x16x32_bf16 v[40:43], v[136:139], v[168:171], v[40:43]
	v_mfma_f32_16x16x32_bf16 v[32:35], v[128:131], v[176:179], v[32:35]
	v_mfma_f32_16x16x32_bf16 v[24:27], v[136:139], v[176:179], v[24:27]
	v_mfma_f32_16x16x32_bf16 v[16:19], v[128:131], v[184:187], v[16:19]
	v_mfma_f32_16x16x32_bf16 v[8:11], v[136:139], v[184:187], v[8:11]
	v_mfma_f32_16x16x32_bf16 v[60:63], v[132:135], v[164:167], v[60:63]
	v_mfma_f32_16x16x32_bf16 v[56:59], v[140:143], v[164:167], v[56:59]
	v_mfma_f32_16x16x32_bf16 v[48:51], v[132:135], v[172:175], v[48:51]
	v_mfma_f32_16x16x32_bf16 v[40:43], v[140:143], v[172:175], v[40:43]
	v_mfma_f32_16x16x32_bf16 v[32:35], v[132:135], v[180:183], v[32:35]
	v_mfma_f32_16x16x32_bf16 v[24:27], v[140:143], v[180:183], v[24:27]
	v_mfma_f32_16x16x32_bf16 v[16:19], v[132:135], v[188:191], v[16:19]
	v_mfma_f32_16x16x32_bf16 v[8:11], v[140:143], v[188:191], v[8:11]
	v_mfma_f32_16x16x32_bf16 v[52:55], v[144:147], v[160:163], v[52:55]
	v_mfma_f32_16x16x32_bf16 v[44:47], v[152:155], v[160:163], v[44:47]
	v_mfma_f32_16x16x32_bf16 v[36:39], v[144:147], v[168:171], v[36:39]
	v_mfma_f32_16x16x32_bf16 v[28:31], v[152:155], v[168:171], v[28:31]
	v_mfma_f32_16x16x32_bf16 v[20:23], v[144:147], v[176:179], v[20:23]
	v_mfma_f32_16x16x32_bf16 v[12:15], v[152:155], v[176:179], v[12:15]
	v_mfma_f32_16x16x32_bf16 v[4:7], v[144:147], v[184:187], v[4:7]
	v_mfma_f32_16x16x32_bf16 v[0:3], v[152:155], v[184:187], v[0:3]
	v_mfma_f32_16x16x32_bf16 v[52:55], v[148:151], v[164:167], v[52:55]
	v_mfma_f32_16x16x32_bf16 v[44:47], v[156:159], v[164:167], v[44:47]
	v_mfma_f32_16x16x32_bf16 v[36:39], v[148:151], v[172:175], v[36:39]
	v_mfma_f32_16x16x32_bf16 v[28:31], v[156:159], v[172:175], v[28:31]
	v_mfma_f32_16x16x32_bf16 v[20:23], v[148:151], v[180:183], v[20:23]
	v_mfma_f32_16x16x32_bf16 v[12:15], v[156:159], v[180:183], v[12:15]
	v_mfma_f32_16x16x32_bf16 v[4:7], v[148:151], v[188:191], v[4:7]
	v_mfma_f32_16x16x32_bf16 v[0:3], v[156:159], v[188:191], v[0:3]
	s_barrier
	s_add_i32 s34, s34, 2
	s_add_u32 s18, s18, 0x100
	s_addc_u32 s19, s19, 0
	s_cmp_gt_u32 s34, 5
	s_mov_b64 s[0:1], s[4:5]
	s_cbranch_scc0 .LBB0_690
	s_and_b64 vcc, exec, s[44:45]
	s_cbranch_vccz .LBB0_693
	s_barrier

; #define PG8_STAGE(bufoff, gbase, voff) do { _Pragma("unroll") for (int _i = 0; _i < 2; ++_i) \
;         __builtin_amdgcn_global_load_lds((const unsigned*)((const char*)(gbase) + (voff)[_i]), (PG8_LAS unsigned*)(lds + (bufoff) + ldsw + _i * 8192), 16, 0, 0); } while (0)
; #define PG8_LDA(dst, b, h) do { _Pragma("unroll") for (int m = 0; m < 4; ++m) _Pragma("unroll") for (int k = 0; k < 2; ++k) dst[m][k] = *(const PG8_LAS bf16x8*)(lds + PG8_SA(b, h) + aoff + m * 2048 + k * 1024); } while (0)
; #define PG8_LDB(dst, b, h) do { _Pragma("unroll") for (int n = 0; n < 2; ++n) _Pragma("unroll") for (int k = 0; k < 2; ++k) dst[n][k] = *(const PG8_LAS bf16x8*)(lds + PG8_SB(b, h) + boff + n * 2048 + k * 1024); } while (0)
; #define PG8_WAIT_V(n) asm volatile("s_waitcnt vmcnt(" #n ")" ::: "memory")
; #define PG8_WAIT_L(n) asm volatile("s_waitcnt lgkmcnt(" #n ")" ::: "memory")
; #define PG8_BAR __builtin_amdgcn_s_barrier()
; #define PG8_SCHED __builtin_amdgcn_sched_barrier(0)
; template <class Epi, class Sched, bool ALIGN_EPI = false, bool SP2 = false>
; __device__ __forceinline__ void gemm_phase(PG8_LAS unsigned char* lds, const Gemm g, const Sched& S, const Epi& E) {
;     ...
;         const char* nA = has_next ? (const char*)g.A + (size_t)nxt.pm * tstepA : cA; const char* nB = has_next ? (const char*)g.Bt + (size_t)nxt.pn * tstepB : cB;
;         for (int t = 0; t < nt; t += 2) {
;             const bool last = (t == nt - 2);
;             const char* a1 = cA + (size_t)(t + 1) * kstep;
;             const char* a2 = last ? nA : cA + (size_t)(t + 2) * kstep; const char* b2 = last ? nB : cB + (size_t)(t + 2) * kstep;
;             const char* a3 = a2 + kstep; const char* b3 = b2 + kstep;
;             if (last && has_next) S.a_ready(nxt);
;             if constexpr (SP2) {
;             PG8_LDB(B0, 0, 0); PG8_LDB(B1, 0, 1); PG8_SCHED; PG8_LDA(At, 0, 0); PG8_STAGE(PG8_SA(1, 1), a1 + hstepA, voffA);
;             PG8_WAIT_V(8); PG8_WAIT_L(0); PG8_BAR; PG8_MMA(0, 0, At, B0); PG8_MMA(0, 1, At, B1); PG8_BAR; PG8_SCHED;
;             PG8_LDA(At, 0, 1); PG8_STAGE(PG8_SB(0, 0), b2, voffB); PG8_STAGE(PG8_SB(0, 1), b2 + hstepB, voffB); PG8_STAGE(PG8_SA(0, 0), a2, voffA);
;             PG8_WAIT_V(8); PG8_WAIT_L(0); PG8_BAR; PG8_MMA(1, 0, At, B0); PG8_MMA(1, 1, At, B1); PG8_BAR; PG8_SCHED;
.LBB0_797:
	s_add_u32 s22, s0, 0xfffc0080
	s_addc_u32 s23, s1, -1
	s_add_i32 s28, 0, 0x10000
	s_cmp_eq_u32 s51, 12
	s_cselect_b32 s25, s14, s23
	s_cselect_b32 s24, s15, s22
	v_add_u32_e32 v138, s28, v141
	s_cselect_b32 s23, s9, s50
	s_cselect_b32 s22, s38, s43
	s_add_i32 s30, 0, 0x14000
	ds_read_b128 v[134:137], v138
	ds_read_b128 v[144:147], v138 offset:1024
	ds_read_b128 v[148:151], v138 offset:2048
	ds_read_b128 v[152:155], v138 offset:3072
	v_add_u32_e32 v138, s30, v141
	ds_read_b128 v[156:159], v138
	ds_read_b128 v[160:163], v138 offset:1024
	ds_read_b128 v[164:167], v138 offset:2048
	ds_read_b128 v[168:171], v138 offset:3072
	s_add_i32 m0, s21, 0xc000
	ds_read_b128 v[172:175], v143
	ds_read_b128 v[176:179], v143 offset:1024
	ds_read_b128 v[180:183], v143 offset:2048
	ds_read_b128 v[184:187], v143 offset:3072
	ds_read_b128 v[188:191], v143 offset:4096
	ds_read_b128 v[192:195], v143 offset:5120
	ds_read_b128 v[196:199], v143 offset:6144
	ds_read_b128 v[200:203], v143 offset:7168
	global_load_lds_dwordx4 v130, s[0:1]
	s_add_i32 m0, s21, 0xe000
	s_nop 0
	global_load_lds_dwordx4 v132, s[0:1]
	s_waitcnt vmcnt(8)
	s_waitcnt lgkmcnt(0)
	s_barrier
	v_mfma_f32_16x16x32_bf16 v[124:127], v[134:137], v[172:175], v[124:127]
	v_mfma_f32_16x16x32_bf16 v[120:123], v[148:151], v[172:175], v[120:123]
	v_mfma_f32_16x16x32_bf16 v[116:119], v[134:137], v[180:183], v[116:119]
	v_mfma_f32_16x16x32_bf16 v[112:115], v[148:151], v[180:183], v[112:115]
	v_mfma_f32_16x16x32_bf16 v[108:111], v[134:137], v[188:191], v[108:111]
	v_mfma_f32_16x16x32_bf16 v[100:103], v[148:151], v[188:191], v[100:103]
	v_mfma_f32_16x16x32_bf16 v[92:95], v[134:137], v[196:199], v[92:95]
	v_mfma_f32_16x16x32_bf16 v[80:83], v[148:151], v[196:199], v[80:83]
	v_mfma_f32_16x16x32_bf16 v[124:127], v[144:147], v[176:179], v[124:127]
	v_mfma_f32_16x16x32_bf16 v[120:123], v[152:155], v[176:179], v[120:123]
	v_mfma_f32_16x16x32_bf16 v[116:119], v[144:147], v[184:187], v[116:119]
	v_mfma_f32_16x16x32_bf16 v[112:115], v[152:155], v[184:187], v[112:115]
	v_mfma_f32_16x16x32_bf16 v[108:111], v[144:147], v[192:195], v[108:111]
	v_mfma_f32_16x16x32_bf16 v[100:103], v[152:155], v[192:195], v[100:103]
	v_mfma_f32_16x16x32_bf16 v[92:95], v[144:147], v[200:203], v[92:95]
	v_mfma_f32_16x16x32_bf16 v[80:83], v[152:155], v[200:203], v[80:83]
	v_mfma_f32_16x16x32_bf16 v[104:107], v[156:159], v[172:175], v[104:107]
	v_mfma_f32_16x16x32_bf16 v[96:99], v[164:167], v[172:175], v[96:99]
	v_mfma_f32_16x16x32_bf16 v[88:91], v[156:159], v[180:183], v[88:91]
	v_mfma_f32_16x16x32_bf16 v[84:87], v[164:167], v[180:183], v[84:87]
	v_mfma_f32_16x16x32_bf16 v[76:79], v[156:159], v[188:191], v[76:79]
	v_mfma_f32_16x16x32_bf16 v[72:75], v[164:167], v[188:191], v[72:75]
	v_mfma_f32_16x16x32_bf16 v[68:71], v[156:159], v[196:199], v[68:71]
	v_mfma_f32_16x16x32_bf16 v[64:67], v[164:167], v[196:199], v[64:67]
	v_mfma_f32_16x16x32_bf16 v[104:107], v[160:163], v[176:179], v[104:107]
	v_mfma_f32_16x16x32_bf16 v[96:99], v[168:171], v[176:179], v[96:99]
	v_mfma_f32_16x16x32_bf16 v[88:91], v[160:163], v[184:187], v[88:91]
	v_mfma_f32_16x16x32_bf16 v[84:87], v[168:171], v[184:187], v[84:87]
	v_mfma_f32_16x16x32_bf16 v[76:79], v[160:163], v[192:195], v[76:79]
	v_mfma_f32_16x16x32_bf16 v[72:75], v[168:171], v[192:195], v[72:75]
	v_mfma_f32_16x16x32_bf16 v[68:71], v[160:163], v[200:203], v[68:71]
	v_mfma_f32_16x16x32_bf16 v[64:67], v[168:171], v[200:203], v[64:67]
	s_barrier
	s_add_i32 s28, s28, s19
	v_lshl_add_u64 v[138:139], s[22:23], 0, v[208:209]
	s_mov_b32 m0, s28
	ds_read_b128 v[172:175], v143 offset:16384
	ds_read_b128 v[176:179], v143 offset:17408
	ds_read_b128 v[180:183], v143 offset:18432
	ds_read_b128 v[184:187], v143 offset:19456
	ds_read_b128 v[188:191], v143 offset:20480
	ds_read_b128 v[192:195], v143 offset:21504
	ds_read_b128 v[196:199], v143 offset:22528
	ds_read_b128 v[200:203], v143 offset:23552
	global_load_lds_dwordx4 v208, s[22:23]
	s_add_i32 m0, s28, 0x2000
	s_add_u32 s28, s22, 0x40000
	v_lshl_add_u64 v[204:205], s[22:23], 0, v[128:129]
	s_addc_u32 s29, s23, 0
	s_add_i32 s30, s30, s19
	global_load_lds_dwordx4 v128, s[22:23]
	s_mov_b32 m0, s30
	v_lshl_add_u64 v[210:211], s[24:25], 0, v[128:129]
	global_load_lds_dwordx4 v208, s[28:29]
	s_add_i32 m0, s30, 0x2000
	s_nop 0
	global_load_lds_dwordx4 v128, s[28:29]
	v_lshl_add_u64 v[206:207], s[24:25], 0, v[208:209]
	s_mov_b32 m0, s21
	s_nop 0
	global_load_lds_dwordx4 v208, s[24:25]
	s_mov_b32 m0, s26
	s_nop 0
	global_load_lds_dwordx4 v128, s[24:25]
	s_waitcnt vmcnt(8)
	s_waitcnt lgkmcnt(0)
	s_barrier
; #define PG8_STAGE(bufoff, gbase, voff) do { _Pragma("unroll") for (int _i = 0; _i < 2; ++_i) \
;         __builtin_amdgcn_global_load_lds((const unsigned*)((const char*)(gbase) + (voff)[_i]), (PG8_LAS unsigned*)(lds + (bufoff) + ldsw + _i * 8192), 16, 0, 0); } while (0)
; #define PG8_LDA(dst, b, h) do { _Pragma("unroll") for (int m = 0; m < 4; ++m) _Pragma("unroll") for (int k = 0; k < 2; ++k) dst[m][k] = *(const PG8_LAS bf16x8*)(lds + PG8_SA(b, h) + aoff + m * 2048 + k * 1024); } while (0)
; #define PG8_LDB(dst, b, h) do { _Pragma("unroll") for (int n = 0; n < 2; ++n) _Pragma("unroll") for (int k = 0; k < 2; ++k) dst[n][k] = *(const PG8_LAS bf16x8*)(lds + PG8_SB(b, h) + boff + n * 2048 + k * 1024); } while (0)
; #define PG8_MMA(ai, bj, At, Bt) do { __builtin_amdgcn_s_setprio(1); _Pragma("unroll") for (int m = 0; m < 4; ++m) _Pragma("unroll") for (int n = 0; n < 2; ++n) _Pragma("unroll") for (int k = 0; k < 2; ++k) \
;         acc[ai][bj][m][n] = __builtin_amdgcn_mfma_f32_16x16x32_bf16(Bt[n][k], At[m][k], acc[ai][bj][m][n], 0, 0, 0); __builtin_amdgcn_s_setprio(0); } while (0)
; #define PG8_WAIT_V(n) asm volatile("s_waitcnt vmcnt(" #n ")" ::: "memory")
; #define PG8_WAIT_L(n) asm volatile("s_waitcnt lgkmcnt(" #n ")" ::: "memory")
; #define PG8_BAR __builtin_amdgcn_s_barrier()
; #define PG8_SCHED __builtin_amdgcn_sched_barrier(0)
; template <class Epi, class Sched, bool ALIGN_EPI = false, bool SP2 = false>
; __device__ __forceinline__ void gemm_phase(PG8_LAS unsigned char* lds, const Gemm g, const Sched& S, const Epi& E) {
;     ...
;             PG8_WAIT_V(8); PG8_WAIT_L(0); PG8_BAR; PG8_MMA(1, 0, At, B0); PG8_MMA(1, 1, At, B1); PG8_BAR; PG8_SCHED;
;             PG8_LDB(B0, 1, 0); PG8_LDB(B1, 1, 1); PG8_SCHED; PG8_LDA(At, 1, 0); PG8_STAGE(PG8_SA(0, 1), a2 + hstepA, voffA);
;             PG8_WAIT_V(8); PG8_WAIT_L(0); PG8_BAR; PG8_MMA(0, 0, At, B0); PG8_MMA(0, 1, At, B1); PG8_BAR; PG8_SCHED;
	v_mfma_f32_16x16x32_bf16 v[60:63], v[134:137], v[172:175], v[60:63]
	v_mfma_f32_16x16x32_bf16 v[56:59], v[148:151], v[172:175], v[56:59]
	v_mfma_f32_16x16x32_bf16 v[52:55], v[134:137], v[180:183], v[52:55]
	v_mfma_f32_16x16x32_bf16 v[48:51], v[148:151], v[180:183], v[48:51]
	v_mfma_f32_16x16x32_bf16 v[44:47], v[134:137], v[188:191], v[44:47]
	v_mfma_f32_16x16x32_bf16 v[32:35], v[148:151], v[188:191], v[32:35]
	v_mfma_f32_16x16x32_bf16 v[16:19], v[134:137], v[196:199], v[16:19]
	v_mfma_f32_16x16x32_bf16 v[8:11], v[148:151], v[196:199], v[8:11]
	v_mfma_f32_16x16x32_bf16 v[60:63], v[144:147], v[176:179], v[60:63]
	v_mfma_f32_16x16x32_bf16 v[56:59], v[152:155], v[176:179], v[56:59]
	v_mfma_f32_16x16x32_bf16 v[52:55], v[144:147], v[184:187], v[52:55]
	v_mfma_f32_16x16x32_bf16 v[48:51], v[152:155], v[184:187], v[48:51]
	v_mfma_f32_16x16x32_bf16 v[44:47], v[144:147], v[192:195], v[44:47]
	v_mfma_f32_16x16x32_bf16 v[32:35], v[152:155], v[192:195], v[32:35]
	v_mfma_f32_16x16x32_bf16 v[16:19], v[144:147], v[200:203], v[16:19]
	v_mfma_f32_16x16x32_bf16 v[8:11], v[152:155], v[200:203], v[8:11]
	v_mfma_f32_16x16x32_bf16 v[40:43], v[156:159], v[172:175], v[40:43]
	v_mfma_f32_16x16x32_bf16 v[36:39], v[164:167], v[172:175], v[36:39]
	v_mfma_f32_16x16x32_bf16 v[28:31], v[156:159], v[180:183], v[28:31]
	v_mfma_f32_16x16x32_bf16 v[24:27], v[164:167], v[180:183], v[24:27]
	v_mfma_f32_16x16x32_bf16 v[20:23], v[156:159], v[188:191], v[20:23]
	v_mfma_f32_16x16x32_bf16 v[12:15], v[164:167], v[188:191], v[12:15]
	v_mfma_f32_16x16x32_bf16 v[4:7], v[156:159], v[196:199], v[4:7]
	v_mfma_f32_16x16x32_bf16 v[0:3], v[164:167], v[196:199], v[0:3]
	v_mfma_f32_16x16x32_bf16 v[40:43], v[160:163], v[176:179], v[40:43]
	v_mfma_f32_16x16x32_bf16 v[36:39], v[168:171], v[176:179], v[36:39]
	v_mfma_f32_16x16x32_bf16 v[28:31], v[160:163], v[184:187], v[28:31]
	v_mfma_f32_16x16x32_bf16 v[24:27], v[168:171], v[184:187], v[24:27]
	v_mfma_f32_16x16x32_bf16 v[20:23], v[160:163], v[192:195], v[20:23]
	v_mfma_f32_16x16x32_bf16 v[12:15], v[168:171], v[192:195], v[12:15]
	v_mfma_f32_16x16x32_bf16 v[4:7], v[160:163], v[200:203], v[4:7]
	v_mfma_f32_16x16x32_bf16 v[0:3], v[168:171], v[200:203], v[0:3]
	s_barrier
	s_add_i32 s28, 0, 0x18000
	s_add_i32 s29, 0, 0x1c000
	v_add_u32_e32 v152, s28, v141
	v_add_u32_e32 v168, s29, v141
	ds_read_b128 v[134:137], v152
	ds_read_b128 v[144:147], v152 offset:1024
	ds_read_b128 v[148:151], v152 offset:2048
	ds_read_b128 v[152:155], v152 offset:3072
	ds_read_b128 v[156:159], v168
	ds_read_b128 v[160:163], v168 offset:1024
	ds_read_b128 v[164:167], v168 offset:2048
	ds_read_b128 v[168:171], v168 offset:3072
	s_add_u32 s24, s24, 0x40000
	s_addc_u32 s25, s25, 0
	s_mov_b32 m0, s34
	ds_read_b128 v[172:175], v143 offset:32768
	ds_read_b128 v[176:179], v143 offset:33792
	ds_read_b128 v[180:183], v143 offset:34816
	ds_read_b128 v[184:187], v143 offset:35840
	ds_read_b128 v[188:191], v143 offset:36864
	ds_read_b128 v[192:195], v143 offset:37888
	ds_read_b128 v[196:199], v143 offset:38912
	ds_read_b128 v[200:203], v143 offset:39936
	global_load_lds_dwordx4 v208, s[24:25]
	s_mov_b32 m0, s35
	s_nop 0
	global_load_lds_dwordx4 v128, s[24:25]
	s_waitcnt vmcnt(8)
	s_waitcnt lgkmcnt(0)
	s_barrier
	v_mfma_f32_16x16x32_bf16 v[124:127], v[134:137], v[172:175], v[124:127]
	v_mfma_f32_16x16x32_bf16 v[120:123], v[148:151], v[172:175], v[120:123]
	v_mfma_f32_16x16x32_bf16 v[116:119], v[134:137], v[180:183], v[116:119]
	v_mfma_f32_16x16x32_bf16 v[112:115], v[148:151], v[180:183], v[112:115]
	v_mfma_f32_16x16x32_bf16 v[108:111], v[134:137], v[188:191], v[108:111]
	v_mfma_f32_16x16x32_bf16 v[100:103], v[148:151], v[188:191], v[100:103]
	v_mfma_f32_16x16x32_bf16 v[92:95], v[134:137], v[196:199], v[92:95]
	v_mfma_f32_16x16x32_bf16 v[80:83], v[148:151], v[196:199], v[80:83]
	v_mfma_f32_16x16x32_bf16 v[124:127], v[144:147], v[176:179], v[124:127]
	v_mfma_f32_16x16x32_bf16 v[120:123], v[152:155], v[176:179], v[120:123]
	v_mfma_f32_16x16x32_bf16 v[116:119], v[144:147], v[184:187], v[116:119]
	v_mfma_f32_16x16x32_bf16 v[112:115], v[152:155], v[184:187], v[112:115]
	v_mfma_f32_16x16x32_bf16 v[108:111], v[144:147], v[192:195], v[108:111]
	v_mfma_f32_16x16x32_bf16 v[100:103], v[152:155], v[192:195], v[100:103]
	v_mfma_f32_16x16x32_bf16 v[92:95], v[144:147], v[200:203], v[92:95]
	v_mfma_f32_16x16x32_bf16 v[80:83], v[152:155], v[200:203], v[80:83]
	v_mfma_f32_16x16x32_bf16 v[104:107], v[156:159], v[172:175], v[104:107]
	v_mfma_f32_16x16x32_bf16 v[96:99], v[164:167], v[172:175], v[96:99]
	v_mfma_f32_16x16x32_bf16 v[88:91], v[156:159], v[180:183], v[88:91]
	v_mfma_f32_16x16x32_bf16 v[84:87], v[164:167], v[180:183], v[84:87]
	v_mfma_f32_16x16x32_bf16 v[76:79], v[156:159], v[188:191], v[76:79]
	v_mfma_f32_16x16x32_bf16 v[72:75], v[164:167], v[188:191], v[72:75]
	v_mfma_f32_16x16x32_bf16 v[68:71], v[156:159], v[196:199], v[68:71]
	v_mfma_f32_16x16x32_bf16 v[64:67], v[164:167], v[196:199], v[64:67]
	v_mfma_f32_16x16x32_bf16 v[104:107], v[160:163], v[176:179], v[104:107]
	v_mfma_f32_16x16x32_bf16 v[96:99], v[168:171], v[176:179], v[96:99]
	v_mfma_f32_16x16x32_bf16 v[88:91], v[160:163], v[184:187], v[88:91]
	v_mfma_f32_16x16x32_bf16 v[84:87], v[168:171], v[184:187], v[84:87]
	v_mfma_f32_16x16x32_bf16 v[76:79], v[160:163], v[192:195], v[76:79]
	v_mfma_f32_16x16x32_bf16 v[72:75], v[168:171], v[192:195], v[72:75]
	v_mfma_f32_16x16x32_bf16 v[68:71], v[160:163], v[200:203], v[68:71]
	v_mfma_f32_16x16x32_bf16 v[64:67], v[168:171], v[200:203], v[64:67]
	s_barrier
; #define PG8_STAGE(bufoff, gbase, voff) do { _Pragma("unroll") for (int _i = 0; _i < 2; ++_i) \
;         __builtin_amdgcn_global_load_lds((const unsigned*)((const char*)(gbase) + (voff)[_i]), (PG8_LAS unsigned*)(lds + (bufoff) + ldsw + _i * 8192), 16, 0, 0); } while (0)
; #define PG8_LDA(dst, b, h) do { _Pragma("unroll") for (int m = 0; m < 4; ++m) _Pragma("unroll") for (int k = 0; k < 2; ++k) dst[m][k] = *(const PG8_LAS bf16x8*)(lds + PG8_SA(b, h) + aoff + m * 2048 + k * 1024); } while (0)
; #define PG8_MMA(ai, bj, At, Bt) do { __builtin_amdgcn_s_setprio(1); _Pragma("unroll") for (int m = 0; m < 4; ++m) _Pragma("unroll") for (int n = 0; n < 2; ++n) _Pragma("unroll") for (int k = 0; k < 2; ++k) \
;         acc[ai][bj][m][n] = __builtin_amdgcn_mfma_f32_16x16x32_bf16(Bt[n][k], At[m][k], acc[ai][bj][m][n], 0, 0, 0); __builtin_amdgcn_s_setprio(0); } while (0)
; #define PG8_WAIT_V(n) asm volatile("s_waitcnt vmcnt(" #n ")" ::: "memory")
; #define PG8_WAIT_L(n) asm volatile("s_waitcnt lgkmcnt(" #n ")" ::: "memory")
; #define PG8_BAR __builtin_amdgcn_s_barrier()
; #define PG8_SCHED __builtin_amdgcn_sched_barrier(0)
; template <class Epi, class Sched, bool ALIGN_EPI = false, bool SP2 = false>
; __device__ __forceinline__ void gemm_phase(PG8_LAS unsigned char* lds, const Gemm g, const Sched& S, const Epi& E) {
;     ...
;             PG8_LDA(At, 1, 1); PG8_STAGE(PG8_SB(1, 0), b3, voffB); PG8_STAGE(PG8_SB(1, 1), b3 + hstepB, voffB); PG8_STAGE(PG8_SA(1, 0), a3, voffA);
;             PG8_WAIT_V(8); PG8_WAIT_L(0); PG8_BAR; PG8_MMA(1, 0, At, B0); PG8_MMA(1, 1, At, B1); PG8_BAR; PG8_SCHED;
;     ...
;         if constexpr (ALIGN_EPI) { if (wr == 0) PG8_BAR; }
	s_add_i32 s24, s28, s19
	v_lshl_add_u64 v[138:139], v[138:139], 0, s[10:11]
	s_mov_b32 m0, s24
	ds_read_b128 v[172:175], v143 offset:49152
	ds_read_b128 v[176:179], v143 offset:50176
	ds_read_b128 v[180:183], v143 offset:51200
	ds_read_b128 v[184:187], v143 offset:52224
	ds_read_b128 v[188:191], v143 offset:53248
	ds_read_b128 v[192:195], v143 offset:54272
	ds_read_b128 v[196:199], v143 offset:55296
	ds_read_b128 v[200:203], v143 offset:56320
	global_load_lds_dwordx4 v[138:139], off
	s_add_i32 m0, s24, 0x2000
	s_add_u32 s22, s22, 0x40080
	v_lshl_add_u64 v[138:139], v[204:205], 0, s[10:11]
	s_addc_u32 s23, s23, 0
	s_add_i32 s24, s29, s19
	global_load_lds_dwordx4 v[138:139], off
	s_mov_b32 m0, s24
	s_nop 0
	global_load_lds_dwordx4 v208, s[22:23]
	s_add_i32 m0, s24, 0x2000
	s_nop 0
	global_load_lds_dwordx4 v128, s[22:23]
	v_lshl_add_u64 v[138:139], v[206:207], 0, s[10:11]
	s_mov_b32 m0, s39
	s_nop 0
	global_load_lds_dwordx4 v[138:139], off
	v_lshl_add_u64 v[138:139], v[210:211], 0, s[10:11]
	s_mov_b32 m0, s48
	s_nop 0
	global_load_lds_dwordx4 v[138:139], off
	s_waitcnt vmcnt(8)
	s_waitcnt lgkmcnt(0)
	s_barrier
	v_mfma_f32_16x16x32_bf16 v[60:63], v[134:137], v[172:175], v[60:63]
	v_mfma_f32_16x16x32_bf16 v[56:59], v[148:151], v[172:175], v[56:59]
	v_mfma_f32_16x16x32_bf16 v[52:55], v[134:137], v[180:183], v[52:55]
	v_mfma_f32_16x16x32_bf16 v[48:51], v[148:151], v[180:183], v[48:51]
	v_mfma_f32_16x16x32_bf16 v[44:47], v[134:137], v[188:191], v[44:47]
	v_mfma_f32_16x16x32_bf16 v[32:35], v[148:151], v[188:191], v[32:35]
	v_mfma_f32_16x16x32_bf16 v[16:19], v[134:137], v[196:199], v[16:19]
	v_mfma_f32_16x16x32_bf16 v[8:11], v[148:151], v[196:199], v[8:11]
	v_mfma_f32_16x16x32_bf16 v[60:63], v[144:147], v[176:179], v[60:63]
	v_mfma_f32_16x16x32_bf16 v[56:59], v[152:155], v[176:179], v[56:59]
	v_mfma_f32_16x16x32_bf16 v[52:55], v[144:147], v[184:187], v[52:55]
	v_mfma_f32_16x16x32_bf16 v[48:51], v[152:155], v[184:187], v[48:51]
	v_mfma_f32_16x16x32_bf16 v[44:47], v[144:147], v[192:195], v[44:47]
	v_mfma_f32_16x16x32_bf16 v[32:35], v[152:155], v[192:195], v[32:35]
	v_mfma_f32_16x16x32_bf16 v[16:19], v[144:147], v[200:203], v[16:19]
	v_mfma_f32_16x16x32_bf16 v[8:11], v[152:155], v[200:203], v[8:11]
	v_mfma_f32_16x16x32_bf16 v[40:43], v[156:159], v[172:175], v[40:43]
	v_mfma_f32_16x16x32_bf16 v[36:39], v[164:167], v[172:175], v[36:39]
	v_mfma_f32_16x16x32_bf16 v[28:31], v[156:159], v[180:183], v[28:31]
	v_mfma_f32_16x16x32_bf16 v[24:27], v[164:167], v[180:183], v[24:27]
	v_mfma_f32_16x16x32_bf16 v[20:23], v[156:159], v[188:191], v[20:23]
	v_mfma_f32_16x16x32_bf16 v[12:15], v[164:167], v[188:191], v[12:15]
	v_mfma_f32_16x16x32_bf16 v[4:7], v[156:159], v[196:199], v[4:7]
	v_mfma_f32_16x16x32_bf16 v[0:3], v[164:167], v[196:199], v[0:3]
	v_mfma_f32_16x16x32_bf16 v[40:43], v[160:163], v[176:179], v[40:43]
	v_mfma_f32_16x16x32_bf16 v[36:39], v[168:171], v[176:179], v[36:39]
	v_mfma_f32_16x16x32_bf16 v[28:31], v[160:163], v[184:187], v[28:31]
	v_mfma_f32_16x16x32_bf16 v[24:27], v[168:171], v[184:187], v[24:27]
	v_mfma_f32_16x16x32_bf16 v[20:23], v[160:163], v[192:195], v[20:23]
	v_mfma_f32_16x16x32_bf16 v[12:15], v[168:171], v[192:195], v[12:15]
	v_mfma_f32_16x16x32_bf16 v[4:7], v[160:163], v[200:203], v[4:7]
	v_mfma_f32_16x16x32_bf16 v[0:3], v[168:171], v[200:203], v[0:3]
	s_barrier
	s_add_i32 s51, s51, 2
	s_add_u32 s0, s0, 0x100
	s_addc_u32 s1, s1, 0
	s_add_u32 s43, s43, 0x100
	s_addc_u32 s50, s50, 0
	s_cmp_gt_u32 s51, 13
	s_cbranch_scc0 .LBB0_797
	s_and_b64 vcc, exec, s[6:7]
	s_cbranch_vccz .LBB0_800
	s_barrier

; #define PG8_STAGE(bufoff, gbase, voff) do { _Pragma("unroll") for (int _i = 0; _i < 2; ++_i) \
;         __builtin_amdgcn_global_load_lds((const unsigned*)((const char*)(gbase) + (voff)[_i]), (PG8_LAS unsigned*)(lds + (bufoff) + ldsw + _i * 8192), 16, 0, 0); } while (0)
; #define PG8_LDA(dst, b, h) do { _Pragma("unroll") for (int m = 0; m < 4; ++m) _Pragma("unroll") for (int k = 0; k < 2; ++k) dst[m][k] = *(const PG8_LAS bf16x8*)(lds + PG8_SA(b, h) + aoff + m * 2048 + k * 1024); } while (0)
; #define PG8_LDB(dst, b, h) do { _Pragma("unroll") for (int n = 0; n < 2; ++n) _Pragma("unroll") for (int k = 0; k < 2; ++k) dst[n][k] = *(const PG8_LAS bf16x8*)(lds + PG8_SB(b, h) + boff + n * 2048 + k * 1024); } while (0)
; #define PG8_WAIT_V(n) asm volatile("s_waitcnt vmcnt(" #n ")" ::: "memory")
; #define PG8_WAIT_L(n) asm volatile("s_waitcnt lgkmcnt(" #n ")" ::: "memory")
; #define PG8_BAR __builtin_amdgcn_s_barrier()
; #define PG8_SCHED __builtin_amdgcn_sched_barrier(0)
; template <class Epi, class Sched, bool ALIGN_EPI = false, bool SP2 = false>
; __device__ __forceinline__ void gemm_phase(PG8_LAS unsigned char* lds, const Gemm g, const Sched& S, const Epi& E) {
;     ...
;         const char* nA = has_next ? (const char*)g.A + (size_t)nxt.pm * tstepA : cA; const char* nB = has_next ? (const char*)g.Bt + (size_t)nxt.pn * tstepB : cB;
;         for (int t = 0; t < nt; t += 2) {
;             const bool last = (t == nt - 2);
;             const char* a1 = cA + (size_t)(t + 1) * kstep;
;             const char* a2 = last ? nA : cA + (size_t)(t + 2) * kstep; const char* b2 = last ? nB : cB + (size_t)(t + 2) * kstep;
;             const char* a3 = a2 + kstep; const char* b3 = b2 + kstep;
;             if (last && has_next) S.a_ready(nxt);
;             if constexpr (SP2) {
;             PG8_LDB(B0, 0, 0); PG8_LDB(B1, 0, 1); PG8_SCHED; PG8_LDA(At, 0, 0); PG8_STAGE(PG8_SA(1, 1), a1 + hstepA, voffA);
;             PG8_WAIT_V(8); PG8_WAIT_L(0); PG8_BAR; PG8_MMA(0, 0, At, B0); PG8_MMA(0, 1, At, B1); PG8_BAR; PG8_SCHED;
;             PG8_LDA(At, 0, 1); PG8_STAGE(PG8_SB(0, 0), b2, voffB); PG8_STAGE(PG8_SB(0, 1), b2 + hstepB, voffB); PG8_STAGE(PG8_SA(0, 0), a2, voffA);
;             PG8_WAIT_V(8); PG8_WAIT_L(0); PG8_BAR; PG8_MMA(1, 0, At, B0); PG8_MMA(1, 1, At, B1); PG8_BAR; PG8_SCHED;
.LBB0_920:
	s_add_u32 s22, s0, 0xfffc0080
	s_addc_u32 s23, s1, -1
	s_add_i32 s28, 0, 0x10000
	s_cmp_eq_u32 s51, 12
	s_cselect_b32 s25, s14, s23
	s_cselect_b32 s24, s15, s22
	v_add_u32_e32 v138, s28, v141
	s_cselect_b32 s23, s9, s50
	s_cselect_b32 s22, s38, s43
	s_add_i32 s30, 0, 0x14000
	ds_read_b128 v[144:147], v138
	ds_read_b128 v[148:151], v138 offset:1024
	ds_read_b128 v[152:155], v138 offset:2048
	ds_read_b128 v[156:159], v138 offset:3072
	v_add_u32_e32 v138, s30, v141
	ds_read_b128 v[160:163], v138
	ds_read_b128 v[164:167], v138 offset:1024
	ds_read_b128 v[168:171], v138 offset:2048
	ds_read_b128 v[172:175], v138 offset:3072
	s_add_i32 m0, s21, 0xc000
	ds_read_b128 v[176:179], v143
	ds_read_b128 v[180:183], v143 offset:1024
	ds_read_b128 v[184:187], v143 offset:2048
	ds_read_b128 v[188:191], v143 offset:3072
	ds_read_b128 v[192:195], v143 offset:4096
	ds_read_b128 v[196:199], v143 offset:5120
	ds_read_b128 v[200:203], v143 offset:6144
	ds_read_b128 v[204:207], v143 offset:7168
	global_load_lds_dwordx4 v134, s[0:1]
	s_add_i32 m0, s21, 0xe000
	s_nop 0
	global_load_lds_dwordx4 v136, s[0:1]
	s_waitcnt vmcnt(8)
	s_waitcnt lgkmcnt(0)
	s_barrier
	v_mfma_f32_16x16x32_bf16 v[124:127], v[144:147], v[176:179], v[124:127]
	v_mfma_f32_16x16x32_bf16 v[120:123], v[152:155], v[176:179], v[120:123]
	v_mfma_f32_16x16x32_bf16 v[108:111], v[144:147], v[184:187], v[108:111]
	v_mfma_f32_16x16x32_bf16 v[104:107], v[152:155], v[184:187], v[104:107]
	v_mfma_f32_16x16x32_bf16 v[92:95], v[144:147], v[192:195], v[92:95]
	v_mfma_f32_16x16x32_bf16 v[88:91], v[152:155], v[192:195], v[88:91]
	v_mfma_f32_16x16x32_bf16 v[76:79], v[144:147], v[200:203], v[76:79]
	v_mfma_f32_16x16x32_bf16 v[72:75], v[152:155], v[200:203], v[72:75]
	v_mfma_f32_16x16x32_bf16 v[124:127], v[148:151], v[180:183], v[124:127]
	v_mfma_f32_16x16x32_bf16 v[120:123], v[156:159], v[180:183], v[120:123]
	v_mfma_f32_16x16x32_bf16 v[108:111], v[148:151], v[188:191], v[108:111]
	v_mfma_f32_16x16x32_bf16 v[104:107], v[156:159], v[188:191], v[104:107]
	v_mfma_f32_16x16x32_bf16 v[92:95], v[148:151], v[196:199], v[92:95]
	v_mfma_f32_16x16x32_bf16 v[88:91], v[156:159], v[196:199], v[88:91]
	v_mfma_f32_16x16x32_bf16 v[76:79], v[148:151], v[204:207], v[76:79]
	v_mfma_f32_16x16x32_bf16 v[72:75], v[156:159], v[204:207], v[72:75]
	v_mfma_f32_16x16x32_bf16 v[116:119], v[160:163], v[176:179], v[116:119]
	v_mfma_f32_16x16x32_bf16 v[112:115], v[168:171], v[176:179], v[112:115]
	v_mfma_f32_16x16x32_bf16 v[100:103], v[160:163], v[184:187], v[100:103]
	v_mfma_f32_16x16x32_bf16 v[96:99], v[168:171], v[184:187], v[96:99]
	v_mfma_f32_16x16x32_bf16 v[84:87], v[160:163], v[192:195], v[84:87]
	v_mfma_f32_16x16x32_bf16 v[80:83], v[168:171], v[192:195], v[80:83]
	v_mfma_f32_16x16x32_bf16 v[68:71], v[160:163], v[200:203], v[68:71]
	v_mfma_f32_16x16x32_bf16 v[64:67], v[168:171], v[200:203], v[64:67]
	v_mfma_f32_16x16x32_bf16 v[116:119], v[164:167], v[180:183], v[116:119]
	v_mfma_f32_16x16x32_bf16 v[112:115], v[172:175], v[180:183], v[112:115]
	v_mfma_f32_16x16x32_bf16 v[100:103], v[164:167], v[188:191], v[100:103]
	v_mfma_f32_16x16x32_bf16 v[96:99], v[172:175], v[188:191], v[96:99]
	v_mfma_f32_16x16x32_bf16 v[84:87], v[164:167], v[196:199], v[84:87]
	v_mfma_f32_16x16x32_bf16 v[80:83], v[172:175], v[196:199], v[80:83]
	v_mfma_f32_16x16x32_bf16 v[68:71], v[164:167], v[204:207], v[68:71]
	v_mfma_f32_16x16x32_bf16 v[64:67], v[172:175], v[204:207], v[64:67]
	s_barrier
	s_add_i32 s28, s28, s18
	v_lshl_add_u64 v[138:139], s[22:23], 0, v[208:209]
	s_mov_b32 m0, s28
	ds_read_b128 v[176:179], v143 offset:16384
	ds_read_b128 v[180:183], v143 offset:17408
	ds_read_b128 v[184:187], v143 offset:18432
	ds_read_b128 v[188:191], v143 offset:19456
	ds_read_b128 v[192:195], v143 offset:20480
	ds_read_b128 v[196:199], v143 offset:21504
	ds_read_b128 v[200:203], v143 offset:22528
	ds_read_b128 v[204:207], v143 offset:23552
	global_load_lds_dwordx4 v208, s[22:23]
	s_add_i32 m0, s28, 0x2000
	s_add_u32 s28, s22, 0x40000
	v_lshl_add_u64 v[210:211], s[22:23], 0, v[128:129]
	s_addc_u32 s29, s23, 0
	s_add_i32 s30, s30, s18
	global_load_lds_dwordx4 v128, s[22:23]
	s_mov_b32 m0, s30
	v_lshl_add_u64 v[222:223], s[24:25], 0, v[130:131]
	global_load_lds_dwordx4 v208, s[28:29]
	s_add_i32 m0, s30, 0x2000
	s_nop 0
	global_load_lds_dwordx4 v128, s[28:29]
	v_lshl_add_u64 v[212:213], s[24:25], 0, v[132:133]
	s_mov_b32 m0, s21
	s_nop 0
	global_load_lds_dwordx4 v132, s[24:25]
	s_mov_b32 m0, s26
	s_nop 0
	global_load_lds_dwordx4 v130, s[24:25]
	s_waitcnt vmcnt(8)
	s_waitcnt lgkmcnt(0)
	s_barrier
; #define PG8_STAGE(bufoff, gbase, voff) do { _Pragma("unroll") for (int _i = 0; _i < 2; ++_i) \
;         __builtin_amdgcn_global_load_lds((const unsigned*)((const char*)(gbase) + (voff)[_i]), (PG8_LAS unsigned*)(lds + (bufoff) + ldsw + _i * 8192), 16, 0, 0); } while (0)
; #define PG8_LDA(dst, b, h) do { _Pragma("unroll") for (int m = 0; m < 4; ++m) _Pragma("unroll") for (int k = 0; k < 2; ++k) dst[m][k] = *(const PG8_LAS bf16x8*)(lds + PG8_SA(b, h) + aoff + m * 2048 + k * 1024); } while (0)
; #define PG8_LDB(dst, b, h) do { _Pragma("unroll") for (int n = 0; n < 2; ++n) _Pragma("unroll") for (int k = 0; k < 2; ++k) dst[n][k] = *(const PG8_LAS bf16x8*)(lds + PG8_SB(b, h) + boff + n * 2048 + k * 1024); } while (0)
; #define PG8_MMA(ai, bj, At, Bt) do { __builtin_amdgcn_s_setprio(1); _Pragma("unroll") for (int m = 0; m < 4; ++m) _Pragma("unroll") for (int n = 0; n < 2; ++n) _Pragma("unroll") for (int k = 0; k < 2; ++k) \
;         acc[ai][bj][m][n] = __builtin_amdgcn_mfma_f32_16x16x32_bf16(Bt[n][k], At[m][k], acc[ai][bj][m][n], 0, 0, 0); __builtin_amdgcn_s_setprio(0); } while (0)
; #define PG8_WAIT_V(n) asm volatile("s_waitcnt vmcnt(" #n ")" ::: "memory")
; #define PG8_WAIT_L(n) asm volatile("s_waitcnt lgkmcnt(" #n ")" ::: "memory")
; #define PG8_BAR __builtin_amdgcn_s_barrier()
; #define PG8_SCHED __builtin_amdgcn_sched_barrier(0)
; template <class Epi, class Sched, bool ALIGN_EPI = false, bool SP2 = false>
; __device__ __forceinline__ void gemm_phase(PG8_LAS unsigned char* lds, const Gemm g, const Sched& S, const Epi& E) {
;     ...
;             PG8_WAIT_V(8); PG8_WAIT_L(0); PG8_BAR; PG8_MMA(1, 0, At, B0); PG8_MMA(1, 1, At, B1); PG8_BAR; PG8_SCHED;
;             PG8_LDB(B0, 1, 0); PG8_LDB(B1, 1, 1); PG8_SCHED; PG8_LDA(At, 1, 0); PG8_STAGE(PG8_SA(0, 1), a2 + hstepA, voffA);
;             PG8_WAIT_V(8); PG8_WAIT_L(0); PG8_BAR; PG8_MMA(0, 0, At, B0); PG8_MMA(0, 1, At, B1); PG8_BAR; PG8_SCHED;
	v_mfma_f32_16x16x32_bf16 v[60:63], v[144:147], v[176:179], v[60:63]
	v_mfma_f32_16x16x32_bf16 v[56:59], v[152:155], v[176:179], v[56:59]
	v_mfma_f32_16x16x32_bf16 v[44:47], v[144:147], v[184:187], v[44:47]
	v_mfma_f32_16x16x32_bf16 v[40:43], v[152:155], v[184:187], v[40:43]
	v_mfma_f32_16x16x32_bf16 v[28:31], v[144:147], v[192:195], v[28:31]
	v_mfma_f32_16x16x32_bf16 v[24:27], v[152:155], v[192:195], v[24:27]
	v_mfma_f32_16x16x32_bf16 v[12:15], v[144:147], v[200:203], v[12:15]
	v_mfma_f32_16x16x32_bf16 v[8:11], v[152:155], v[200:203], v[8:11]
	v_mfma_f32_16x16x32_bf16 v[60:63], v[148:151], v[180:183], v[60:63]
	v_mfma_f32_16x16x32_bf16 v[56:59], v[156:159], v[180:183], v[56:59]
	v_mfma_f32_16x16x32_bf16 v[44:47], v[148:151], v[188:191], v[44:47]
	v_mfma_f32_16x16x32_bf16 v[40:43], v[156:159], v[188:191], v[40:43]
	v_mfma_f32_16x16x32_bf16 v[28:31], v[148:151], v[196:199], v[28:31]
	v_mfma_f32_16x16x32_bf16 v[24:27], v[156:159], v[196:199], v[24:27]
	v_mfma_f32_16x16x32_bf16 v[12:15], v[148:151], v[204:207], v[12:15]
	v_mfma_f32_16x16x32_bf16 v[8:11], v[156:159], v[204:207], v[8:11]
	v_mfma_f32_16x16x32_bf16 v[52:55], v[160:163], v[176:179], v[52:55]
	v_mfma_f32_16x16x32_bf16 v[48:51], v[168:171], v[176:179], v[48:51]
	v_mfma_f32_16x16x32_bf16 v[36:39], v[160:163], v[184:187], v[36:39]
	v_mfma_f32_16x16x32_bf16 v[32:35], v[168:171], v[184:187], v[32:35]
	v_mfma_f32_16x16x32_bf16 v[20:23], v[160:163], v[192:195], v[20:23]
	v_mfma_f32_16x16x32_bf16 v[16:19], v[168:171], v[192:195], v[16:19]
	v_mfma_f32_16x16x32_bf16 v[4:7], v[160:163], v[200:203], v[4:7]
	v_mfma_f32_16x16x32_bf16 v[0:3], v[168:171], v[200:203], v[0:3]
	v_mfma_f32_16x16x32_bf16 v[52:55], v[164:167], v[180:183], v[52:55]
	v_mfma_f32_16x16x32_bf16 v[48:51], v[172:175], v[180:183], v[48:51]
	v_mfma_f32_16x16x32_bf16 v[36:39], v[164:167], v[188:191], v[36:39]
	v_mfma_f32_16x16x32_bf16 v[32:35], v[172:175], v[188:191], v[32:35]
	v_mfma_f32_16x16x32_bf16 v[20:23], v[164:167], v[196:199], v[20:23]
	v_mfma_f32_16x16x32_bf16 v[16:19], v[172:175], v[196:199], v[16:19]
	v_mfma_f32_16x16x32_bf16 v[4:7], v[164:167], v[204:207], v[4:7]
	v_mfma_f32_16x16x32_bf16 v[0:3], v[172:175], v[204:207], v[0:3]
	s_barrier
	s_add_i32 s28, 0, 0x18000
	s_add_i32 s29, 0, 0x1c000
	v_add_u32_e32 v156, s28, v141
	v_add_u32_e32 v172, s29, v141
	ds_read_b128 v[144:147], v156
	ds_read_b128 v[148:151], v156 offset:1024
	ds_read_b128 v[152:155], v156 offset:2048
	ds_read_b128 v[156:159], v156 offset:3072
	ds_read_b128 v[160:163], v172
	ds_read_b128 v[164:167], v172 offset:1024
	ds_read_b128 v[168:171], v172 offset:2048
	ds_read_b128 v[172:175], v172 offset:3072
	s_add_u32 s24, s24, 0x40000
	s_addc_u32 s25, s25, 0
	s_mov_b32 m0, s34
	ds_read_b128 v[176:179], v143 offset:32768
	ds_read_b128 v[180:183], v143 offset:33792
	ds_read_b128 v[184:187], v143 offset:34816
	ds_read_b128 v[188:191], v143 offset:35840
	ds_read_b128 v[192:195], v143 offset:36864
	ds_read_b128 v[196:199], v143 offset:37888
	ds_read_b128 v[200:203], v143 offset:38912
	ds_read_b128 v[204:207], v143 offset:39936
	global_load_lds_dwordx4 v132, s[24:25]
	v_lshl_add_u64 v[224:225], s[24:25], 0, v[130:131]
	s_mov_b32 m0, s35
	s_nop 0
	global_load_lds_dwordx4 v130, s[24:25]
	s_waitcnt vmcnt(8)
	s_waitcnt lgkmcnt(0)
	s_barrier
	v_mfma_f32_16x16x32_bf16 v[124:127], v[144:147], v[176:179], v[124:127]
	v_mfma_f32_16x16x32_bf16 v[120:123], v[152:155], v[176:179], v[120:123]
	v_mfma_f32_16x16x32_bf16 v[108:111], v[144:147], v[184:187], v[108:111]
	v_mfma_f32_16x16x32_bf16 v[104:107], v[152:155], v[184:187], v[104:107]
	v_mfma_f32_16x16x32_bf16 v[92:95], v[144:147], v[192:195], v[92:95]
	v_mfma_f32_16x16x32_bf16 v[88:91], v[152:155], v[192:195], v[88:91]
	v_mfma_f32_16x16x32_bf16 v[76:79], v[144:147], v[200:203], v[76:79]
	v_mfma_f32_16x16x32_bf16 v[72:75], v[152:155], v[200:203], v[72:75]
	v_mfma_f32_16x16x32_bf16 v[124:127], v[148:151], v[180:183], v[124:127]
	v_mfma_f32_16x16x32_bf16 v[120:123], v[156:159], v[180:183], v[120:123]
	v_mfma_f32_16x16x32_bf16 v[108:111], v[148:151], v[188:191], v[108:111]
	v_mfma_f32_16x16x32_bf16 v[104:107], v[156:159], v[188:191], v[104:107]
	v_mfma_f32_16x16x32_bf16 v[92:95], v[148:151], v[196:199], v[92:95]
	v_mfma_f32_16x16x32_bf16 v[88:91], v[156:159], v[196:199], v[88:91]
	v_mfma_f32_16x16x32_bf16 v[76:79], v[148:151], v[204:207], v[76:79]
	v_mfma_f32_16x16x32_bf16 v[72:75], v[156:159], v[204:207], v[72:75]
	v_mfma_f32_16x16x32_bf16 v[116:119], v[160:163], v[176:179], v[116:119]
	v_mfma_f32_16x16x32_bf16 v[112:115], v[168:171], v[176:179], v[112:115]
	v_mfma_f32_16x16x32_bf16 v[100:103], v[160:163], v[184:187], v[100:103]
	v_mfma_f32_16x16x32_bf16 v[96:99], v[168:171], v[184:187], v[96:99]
	v_mfma_f32_16x16x32_bf16 v[84:87], v[160:163], v[192:195], v[84:87]
	v_mfma_f32_16x16x32_bf16 v[80:83], v[168:171], v[192:195], v[80:83]
	v_mfma_f32_16x16x32_bf16 v[68:71], v[160:163], v[200:203], v[68:71]
	v_mfma_f32_16x16x32_bf16 v[64:67], v[168:171], v[200:203], v[64:67]
	v_mfma_f32_16x16x32_bf16 v[116:119], v[164:167], v[180:183], v[116:119]
	v_mfma_f32_16x16x32_bf16 v[112:115], v[172:175], v[180:183], v[112:115]
	v_mfma_f32_16x16x32_bf16 v[100:103], v[164:167], v[188:191], v[100:103]
	v_mfma_f32_16x16x32_bf16 v[96:99], v[172:175], v[188:191], v[96:99]
	v_mfma_f32_16x16x32_bf16 v[84:87], v[164:167], v[196:199], v[84:87]
	v_mfma_f32_16x16x32_bf16 v[80:83], v[172:175], v[196:199], v[80:83]
	v_mfma_f32_16x16x32_bf16 v[68:71], v[164:167], v[204:207], v[68:71]
	v_mfma_f32_16x16x32_bf16 v[64:67], v[172:175], v[204:207], v[64:67]
	s_barrier
; #define PG8_STAGE(bufoff, gbase, voff) do { _Pragma("unroll") for (int _i = 0; _i < 2; ++_i) \
;         __builtin_amdgcn_global_load_lds((const unsigned*)((const char*)(gbase) + (voff)[_i]), (PG8_LAS unsigned*)(lds + (bufoff) + ldsw + _i * 8192), 16, 0, 0); } while (0)
; #define PG8_LDA(dst, b, h) do { _Pragma("unroll") for (int m = 0; m < 4; ++m) _Pragma("unroll") for (int k = 0; k < 2; ++k) dst[m][k] = *(const PG8_LAS bf16x8*)(lds + PG8_SA(b, h) + aoff + m * 2048 + k * 1024); } while (0)
; #define PG8_MMA(ai, bj, At, Bt) do { __builtin_amdgcn_s_setprio(1); _Pragma("unroll") for (int m = 0; m < 4; ++m) _Pragma("unroll") for (int n = 0; n < 2; ++n) _Pragma("unroll") for (int k = 0; k < 2; ++k) \
;         acc[ai][bj][m][n] = __builtin_amdgcn_mfma_f32_16x16x32_bf16(Bt[n][k], At[m][k], acc[ai][bj][m][n], 0, 0, 0); __builtin_amdgcn_s_setprio(0); } while (0)
; #define PG8_WAIT_V(n) asm volatile("s_waitcnt vmcnt(" #n ")" ::: "memory")
; #define PG8_WAIT_L(n) asm volatile("s_waitcnt lgkmcnt(" #n ")" ::: "memory")
; #define PG8_BAR __builtin_amdgcn_s_barrier()
; #define PG8_SCHED __builtin_amdgcn_sched_barrier(0)
; template <class Epi, class Sched, bool ALIGN_EPI = false, bool SP2 = false>
; __device__ __forceinline__ void gemm_phase(PG8_LAS unsigned char* lds, const Gemm g, const Sched& S, const Epi& E) {
;     ...
;             PG8_LDA(At, 1, 1); PG8_STAGE(PG8_SB(1, 0), b3, voffB); PG8_STAGE(PG8_SB(1, 1), b3 + hstepB, voffB); PG8_STAGE(PG8_SA(1, 0), a3, voffA);
;             PG8_WAIT_V(8); PG8_WAIT_L(0); PG8_BAR; PG8_MMA(1, 0, At, B0); PG8_MMA(1, 1, At, B1); PG8_BAR; PG8_SCHED;
;     ...
;         if constexpr (ALIGN_EPI) { if (wr == 0) PG8_BAR; }
	s_add_i32 s24, s28, s18
	v_lshl_add_u64 v[138:139], v[138:139], 0, s[10:11]
	s_mov_b32 m0, s24
	ds_read_b128 v[176:179], v143 offset:49152
	ds_read_b128 v[180:183], v143 offset:50176
	ds_read_b128 v[184:187], v143 offset:51200
	ds_read_b128 v[188:191], v143 offset:52224
	ds_read_b128 v[192:195], v143 offset:53248
	ds_read_b128 v[196:199], v143 offset:54272
	ds_read_b128 v[200:203], v143 offset:55296
	ds_read_b128 v[204:207], v143 offset:56320
	global_load_lds_dwordx4 v[138:139], off
	s_add_i32 m0, s24, 0x2000
	s_add_u32 s22, s22, 0x40080
	v_lshl_add_u64 v[138:139], v[210:211], 0, s[10:11]
	s_addc_u32 s23, s23, 0
	s_add_i32 s24, s29, s18
	global_load_lds_dwordx4 v[138:139], off
	s_mov_b32 m0, s24
	s_nop 0
	global_load_lds_dwordx4 v208, s[22:23]
	s_add_i32 m0, s24, 0x2000
	s_nop 0
	global_load_lds_dwordx4 v128, s[22:23]
	v_lshl_add_u64 v[138:139], v[212:213], 0, s[10:11]
	s_mov_b32 m0, s39
	s_nop 0
	global_load_lds_dwordx4 v[138:139], off
	v_lshl_add_u64 v[138:139], v[222:223], 0, s[10:11]
	s_mov_b32 m0, s48
	s_nop 0
	global_load_lds_dwordx4 v[138:139], off
	s_waitcnt vmcnt(8)
	s_waitcnt lgkmcnt(0)
	s_barrier
	v_mfma_f32_16x16x32_bf16 v[60:63], v[144:147], v[176:179], v[60:63]
	v_mfma_f32_16x16x32_bf16 v[56:59], v[152:155], v[176:179], v[56:59]
	v_mfma_f32_16x16x32_bf16 v[44:47], v[144:147], v[184:187], v[44:47]
	v_mfma_f32_16x16x32_bf16 v[40:43], v[152:155], v[184:187], v[40:43]
	v_mfma_f32_16x16x32_bf16 v[28:31], v[144:147], v[192:195], v[28:31]
	v_mfma_f32_16x16x32_bf16 v[24:27], v[152:155], v[192:195], v[24:27]
	v_mfma_f32_16x16x32_bf16 v[12:15], v[144:147], v[200:203], v[12:15]
	v_mfma_f32_16x16x32_bf16 v[8:11], v[152:155], v[200:203], v[8:11]
	v_mfma_f32_16x16x32_bf16 v[60:63], v[148:151], v[180:183], v[60:63]
	v_mfma_f32_16x16x32_bf16 v[56:59], v[156:159], v[180:183], v[56:59]
	v_mfma_f32_16x16x32_bf16 v[44:47], v[148:151], v[188:191], v[44:47]
	v_mfma_f32_16x16x32_bf16 v[40:43], v[156:159], v[188:191], v[40:43]
	v_mfma_f32_16x16x32_bf16 v[28:31], v[148:151], v[196:199], v[28:31]
	v_mfma_f32_16x16x32_bf16 v[24:27], v[156:159], v[196:199], v[24:27]
	v_mfma_f32_16x16x32_bf16 v[12:15], v[148:151], v[204:207], v[12:15]
	v_mfma_f32_16x16x32_bf16 v[8:11], v[156:159], v[204:207], v[8:11]
	v_mfma_f32_16x16x32_bf16 v[52:55], v[160:163], v[176:179], v[52:55]
	v_mfma_f32_16x16x32_bf16 v[48:51], v[168:171], v[176:179], v[48:51]
	v_mfma_f32_16x16x32_bf16 v[36:39], v[160:163], v[184:187], v[36:39]
	v_mfma_f32_16x16x32_bf16 v[32:35], v[168:171], v[184:187], v[32:35]
	v_mfma_f32_16x16x32_bf16 v[20:23], v[160:163], v[192:195], v[20:23]
	v_mfma_f32_16x16x32_bf16 v[16:19], v[168:171], v[192:195], v[16:19]
	v_mfma_f32_16x16x32_bf16 v[4:7], v[160:163], v[200:203], v[4:7]
	v_mfma_f32_16x16x32_bf16 v[0:3], v[168:171], v[200:203], v[0:3]
	v_mfma_f32_16x16x32_bf16 v[52:55], v[164:167], v[180:183], v[52:55]
	v_mfma_f32_16x16x32_bf16 v[48:51], v[172:175], v[180:183], v[48:51]
	v_mfma_f32_16x16x32_bf16 v[36:39], v[164:167], v[188:191], v[36:39]
	v_mfma_f32_16x16x32_bf16 v[32:35], v[172:175], v[188:191], v[32:35]
	v_mfma_f32_16x16x32_bf16 v[20:23], v[164:167], v[196:199], v[20:23]
	v_mfma_f32_16x16x32_bf16 v[16:19], v[172:175], v[196:199], v[16:19]
	v_mfma_f32_16x16x32_bf16 v[4:7], v[164:167], v[204:207], v[4:7]
	v_mfma_f32_16x16x32_bf16 v[0:3], v[172:175], v[204:207], v[0:3]
	s_barrier
	s_add_i32 s51, s51, 2
	s_add_u32 s0, s0, 0x100
	s_addc_u32 s1, s1, 0
	s_add_u32 s43, s43, 0x100
	s_addc_u32 s50, s50, 0
	s_cmp_gt_u32 s51, 13
	s_cbranch_scc0 .LBB0_920
	s_and_b64 vcc, exec, s[6:7]
	s_cbranch_vccz .LBB0_923
	s_barrier

; #define PG8_STAGE(bufoff, gbase, voff) do { _Pragma("unroll") for (int _i = 0; _i < 2; ++_i) \
;         __builtin_amdgcn_global_load_lds((const unsigned*)((const char*)(gbase) + (voff)[_i]), (PG8_LAS unsigned*)(lds + (bufoff) + ldsw + _i * 8192), 16, 0, 0); } while (0)
; #define PG8_LDA(dst, b, h) do { _Pragma("unroll") for (int m = 0; m < 4; ++m) _Pragma("unroll") for (int k = 0; k < 2; ++k) dst[m][k] = *(const PG8_LAS bf16x8*)(lds + PG8_SA(b, h) + aoff + m * 2048 + k * 1024); } while (0)
; #define PG8_LDB(dst, b, h) do { _Pragma("unroll") for (int n = 0; n < 2; ++n) _Pragma("unroll") for (int k = 0; k < 2; ++k) dst[n][k] = *(const PG8_LAS bf16x8*)(lds + PG8_SB(b, h) + boff + n * 2048 + k * 1024); } while (0)
; #define PG8_WAIT_V(n) asm volatile("s_waitcnt vmcnt(" #n ")" ::: "memory")
; #define PG8_WAIT_L(n) asm volatile("s_waitcnt lgkmcnt(" #n ")" ::: "memory")
; #define PG8_BAR __builtin_amdgcn_s_barrier()
; #define PG8_SCHED __builtin_amdgcn_sched_barrier(0)
; template <class Epi, class Sched, bool ALIGN_EPI = false, bool SP2 = false>
; __device__ __forceinline__ void gemm_phase(PG8_LAS unsigned char* lds, const Gemm g, const Sched& S, const Epi& E) {
;     ...
;         const char* nA = has_next ? (const char*)g.A + (size_t)nxt.pm * tstepA : cA; const char* nB = has_next ? (const char*)g.Bt + (size_t)nxt.pn * tstepB : cB;
;         for (int t = 0; t < nt; t += 2) {
;             const bool last = (t == nt - 2);
;             const char* a1 = cA + (size_t)(t + 1) * kstep;
;             const char* a2 = last ? nA : cA + (size_t)(t + 2) * kstep; const char* b2 = last ? nB : cB + (size_t)(t + 2) * kstep;
;             const char* a3 = a2 + kstep; const char* b3 = b2 + kstep;
;             if (last && has_next) S.a_ready(nxt);
;             if constexpr (SP2) {
;             PG8_LDB(B0, 0, 0); PG8_LDB(B1, 0, 1); PG8_SCHED; PG8_LDA(At, 0, 0); PG8_STAGE(PG8_SA(1, 1), a1 + hstepA, voffA);
;             PG8_WAIT_V(8); PG8_WAIT_L(0); PG8_BAR; PG8_MMA(0, 0, At, B0); PG8_MMA(0, 1, At, B1); PG8_BAR; PG8_SCHED;
;             PG8_LDA(At, 0, 1); PG8_STAGE(PG8_SB(0, 0), b2, voffB); PG8_STAGE(PG8_SB(0, 1), b2 + hstepB, voffB); PG8_STAGE(PG8_SA(0, 0), a2, voffA);
;             PG8_WAIT_V(8); PG8_WAIT_L(0); PG8_BAR; PG8_MMA(1, 0, At, B0); PG8_MMA(1, 1, At, B1); PG8_BAR; PG8_SCHED;
.LBB0_1000:
	s_add_u32 s20, s0, 0x100
	s_addc_u32 s21, s1, 0
	s_add_i32 s28, 0, 0x10000
	s_cmp_eq_u32 s49, 40
	s_cselect_b32 s25, s5, s21
	s_cselect_b32 s24, s4, s20
	v_add_u32_e32 v138, s28, v141
	s_cselect_b32 s23, s43, s15
	s_cselect_b32 s22, s42, s14
	s_add_i32 s29, 0, 0x14000
	ds_read_b128 v[134:137], v138
	ds_read_b128 v[144:147], v138 offset:1024
	ds_read_b128 v[148:151], v138 offset:2048
	ds_read_b128 v[152:155], v138 offset:3072
	v_add_u32_e32 v138, s29, v141
	ds_read_b128 v[156:159], v138
	ds_read_b128 v[160:163], v138 offset:1024
	ds_read_b128 v[164:167], v138 offset:2048
	ds_read_b128 v[168:171], v138 offset:3072
	v_lshl_add_u64 v[138:139], s[0:1], 0, v[130:131]
	s_add_i32 m0, s26, 0xc000
	ds_read_b128 v[172:175], v143
	ds_read_b128 v[176:179], v143 offset:1024
	ds_read_b128 v[180:183], v143 offset:2048
	ds_read_b128 v[184:187], v143 offset:3072
	ds_read_b128 v[188:191], v143 offset:4096
	ds_read_b128 v[192:195], v143 offset:5120
	ds_read_b128 v[196:199], v143 offset:6144
	ds_read_b128 v[200:203], v143 offset:7168
	global_load_lds_dwordx4 v[138:139], off
	v_lshl_add_u64 v[138:139], s[0:1], 0, v[132:133]
	s_add_i32 m0, s26, 0xe000
	s_nop 0
	global_load_lds_dwordx4 v[138:139], off
	s_waitcnt vmcnt(8)
	s_waitcnt lgkmcnt(0)
	s_barrier
	v_mfma_f32_16x16x32_bf16 v[124:127], v[134:137], v[172:175], v[124:127]
	v_mfma_f32_16x16x32_bf16 v[120:123], v[148:151], v[172:175], v[120:123]
	v_mfma_f32_16x16x32_bf16 v[116:119], v[134:137], v[180:183], v[116:119]
	v_mfma_f32_16x16x32_bf16 v[112:115], v[148:151], v[180:183], v[112:115]
	v_mfma_f32_16x16x32_bf16 v[108:111], v[134:137], v[188:191], v[108:111]
	v_mfma_f32_16x16x32_bf16 v[100:103], v[148:151], v[188:191], v[100:103]
	v_mfma_f32_16x16x32_bf16 v[92:95], v[134:137], v[196:199], v[92:95]
	v_mfma_f32_16x16x32_bf16 v[80:83], v[148:151], v[196:199], v[80:83]
	v_mfma_f32_16x16x32_bf16 v[124:127], v[144:147], v[176:179], v[124:127]
	v_mfma_f32_16x16x32_bf16 v[120:123], v[152:155], v[176:179], v[120:123]
	v_mfma_f32_16x16x32_bf16 v[116:119], v[144:147], v[184:187], v[116:119]
	v_mfma_f32_16x16x32_bf16 v[112:115], v[152:155], v[184:187], v[112:115]
	v_mfma_f32_16x16x32_bf16 v[108:111], v[144:147], v[192:195], v[108:111]
	v_mfma_f32_16x16x32_bf16 v[100:103], v[152:155], v[192:195], v[100:103]
	v_mfma_f32_16x16x32_bf16 v[92:95], v[144:147], v[200:203], v[92:95]
	v_mfma_f32_16x16x32_bf16 v[80:83], v[152:155], v[200:203], v[80:83]
	v_mfma_f32_16x16x32_bf16 v[104:107], v[156:159], v[172:175], v[104:107]
	v_mfma_f32_16x16x32_bf16 v[96:99], v[164:167], v[172:175], v[96:99]
	v_mfma_f32_16x16x32_bf16 v[88:91], v[156:159], v[180:183], v[88:91]
	v_mfma_f32_16x16x32_bf16 v[84:87], v[164:167], v[180:183], v[84:87]
	v_mfma_f32_16x16x32_bf16 v[76:79], v[156:159], v[188:191], v[76:79]
	v_mfma_f32_16x16x32_bf16 v[72:75], v[164:167], v[188:191], v[72:75]
	v_mfma_f32_16x16x32_bf16 v[68:71], v[156:159], v[196:199], v[68:71]
	v_mfma_f32_16x16x32_bf16 v[64:67], v[164:167], v[196:199], v[64:67]
	v_mfma_f32_16x16x32_bf16 v[104:107], v[160:163], v[176:179], v[104:107]
	v_mfma_f32_16x16x32_bf16 v[96:99], v[168:171], v[176:179], v[96:99]
	v_mfma_f32_16x16x32_bf16 v[88:91], v[160:163], v[184:187], v[88:91]
	v_mfma_f32_16x16x32_bf16 v[84:87], v[168:171], v[184:187], v[84:87]
	v_mfma_f32_16x16x32_bf16 v[76:79], v[160:163], v[192:195], v[76:79]
	v_mfma_f32_16x16x32_bf16 v[72:75], v[168:171], v[192:195], v[72:75]
	v_mfma_f32_16x16x32_bf16 v[68:71], v[160:163], v[200:203], v[68:71]
	v_mfma_f32_16x16x32_bf16 v[64:67], v[168:171], v[200:203], v[64:67]
	s_barrier
	s_add_i32 s0, s28, s19
	v_lshl_add_u64 v[138:139], s[22:23], 0, v[208:209]
	s_mov_b32 m0, s0
	ds_read_b128 v[172:175], v143 offset:16384
	ds_read_b128 v[176:179], v143 offset:17408
	ds_read_b128 v[180:183], v143 offset:18432
	ds_read_b128 v[184:187], v143 offset:19456
	ds_read_b128 v[188:191], v143 offset:20480
	ds_read_b128 v[192:195], v143 offset:21504
	ds_read_b128 v[196:199], v143 offset:22528
	ds_read_b128 v[200:203], v143 offset:23552
	global_load_lds_dwordx4 v208, s[22:23]
	s_add_i32 m0, s0, 0x2000
	s_add_u32 s0, s22, 0xb0000
	v_lshl_add_u64 v[204:205], s[22:23], 0, v[128:129]
	s_addc_u32 s1, s23, 0
	s_add_i32 s28, s29, s19
	global_load_lds_dwordx4 v128, s[22:23]
	s_mov_b32 m0, s28
	v_lshl_add_u64 v[210:211], s[24:25], 0, v[128:129]
	global_load_lds_dwordx4 v208, s[0:1]
	s_add_i32 m0, s28, 0x2000
	s_nop 0
	global_load_lds_dwordx4 v128, s[0:1]
	v_lshl_add_u64 v[206:207], s[24:25], 0, v[208:209]
	s_mov_b32 m0, s26
	s_nop 0
	global_load_lds_dwordx4 v208, s[24:25]
	s_mov_b32 m0, s34
	s_nop 0
	global_load_lds_dwordx4 v128, s[24:25]
	s_waitcnt vmcnt(8)
	s_waitcnt lgkmcnt(0)
	s_barrier
; #define PG8_STAGE(bufoff, gbase, voff) do { _Pragma("unroll") for (int _i = 0; _i < 2; ++_i) \
;         __builtin_amdgcn_global_load_lds((const unsigned*)((const char*)(gbase) + (voff)[_i]), (PG8_LAS unsigned*)(lds + (bufoff) + ldsw + _i * 8192), 16, 0, 0); } while (0)
; #define PG8_LDA(dst, b, h) do { _Pragma("unroll") for (int m = 0; m < 4; ++m) _Pragma("unroll") for (int k = 0; k < 2; ++k) dst[m][k] = *(const PG8_LAS bf16x8*)(lds + PG8_SA(b, h) + aoff + m * 2048 + k * 1024); } while (0)
; #define PG8_LDB(dst, b, h) do { _Pragma("unroll") for (int n = 0; n < 2; ++n) _Pragma("unroll") for (int k = 0; k < 2; ++k) dst[n][k] = *(const PG8_LAS bf16x8*)(lds + PG8_SB(b, h) + boff + n * 2048 + k * 1024); } while (0)
; #define PG8_MMA(ai, bj, At, Bt) do { __builtin_amdgcn_s_setprio(1); _Pragma("unroll") for (int m = 0; m < 4; ++m) _Pragma("unroll") for (int n = 0; n < 2; ++n) _Pragma("unroll") for (int k = 0; k < 2; ++k) \
;         acc[ai][bj][m][n] = __builtin_amdgcn_mfma_f32_16x16x32_bf16(Bt[n][k], At[m][k], acc[ai][bj][m][n], 0, 0, 0); __builtin_amdgcn_s_setprio(0); } while (0)
; #define PG8_WAIT_V(n) asm volatile("s_waitcnt vmcnt(" #n ")" ::: "memory")
; #define PG8_WAIT_L(n) asm volatile("s_waitcnt lgkmcnt(" #n ")" ::: "memory")
; #define PG8_BAR __builtin_amdgcn_s_barrier()
; #define PG8_SCHED __builtin_amdgcn_sched_barrier(0)
; template <class Epi, class Sched, bool ALIGN_EPI = false, bool SP2 = false>
; __device__ __forceinline__ void gemm_phase(PG8_LAS unsigned char* lds, const Gemm g, const Sched& S, const Epi& E) {
;     ...
;             PG8_WAIT_V(8); PG8_WAIT_L(0); PG8_BAR; PG8_MMA(1, 0, At, B0); PG8_MMA(1, 1, At, B1); PG8_BAR; PG8_SCHED;
;             PG8_LDB(B0, 1, 0); PG8_LDB(B1, 1, 1); PG8_SCHED; PG8_LDA(At, 1, 0); PG8_STAGE(PG8_SA(0, 1), a2 + hstepA, voffA);
;             PG8_WAIT_V(8); PG8_WAIT_L(0); PG8_BAR; PG8_MMA(0, 0, At, B0); PG8_MMA(0, 1, At, B1); PG8_BAR; PG8_SCHED;
	v_mfma_f32_16x16x32_bf16 v[60:63], v[134:137], v[172:175], v[60:63]
	v_mfma_f32_16x16x32_bf16 v[56:59], v[148:151], v[172:175], v[56:59]
	v_mfma_f32_16x16x32_bf16 v[52:55], v[134:137], v[180:183], v[52:55]
	v_mfma_f32_16x16x32_bf16 v[48:51], v[148:151], v[180:183], v[48:51]
	v_mfma_f32_16x16x32_bf16 v[44:47], v[134:137], v[188:191], v[44:47]
	v_mfma_f32_16x16x32_bf16 v[32:35], v[148:151], v[188:191], v[32:35]
	v_mfma_f32_16x16x32_bf16 v[16:19], v[134:137], v[196:199], v[16:19]
	v_mfma_f32_16x16x32_bf16 v[8:11], v[148:151], v[196:199], v[8:11]
	v_mfma_f32_16x16x32_bf16 v[60:63], v[144:147], v[176:179], v[60:63]
	v_mfma_f32_16x16x32_bf16 v[56:59], v[152:155], v[176:179], v[56:59]
	v_mfma_f32_16x16x32_bf16 v[52:55], v[144:147], v[184:187], v[52:55]
	v_mfma_f32_16x16x32_bf16 v[48:51], v[152:155], v[184:187], v[48:51]
	v_mfma_f32_16x16x32_bf16 v[44:47], v[144:147], v[192:195], v[44:47]
	v_mfma_f32_16x16x32_bf16 v[32:35], v[152:155], v[192:195], v[32:35]
	v_mfma_f32_16x16x32_bf16 v[16:19], v[144:147], v[200:203], v[16:19]
	v_mfma_f32_16x16x32_bf16 v[8:11], v[152:155], v[200:203], v[8:11]
	v_mfma_f32_16x16x32_bf16 v[40:43], v[156:159], v[172:175], v[40:43]
	v_mfma_f32_16x16x32_bf16 v[36:39], v[164:167], v[172:175], v[36:39]
	v_mfma_f32_16x16x32_bf16 v[28:31], v[156:159], v[180:183], v[28:31]
	v_mfma_f32_16x16x32_bf16 v[24:27], v[164:167], v[180:183], v[24:27]
	v_mfma_f32_16x16x32_bf16 v[20:23], v[156:159], v[188:191], v[20:23]
	v_mfma_f32_16x16x32_bf16 v[12:15], v[164:167], v[188:191], v[12:15]
	v_mfma_f32_16x16x32_bf16 v[4:7], v[156:159], v[196:199], v[4:7]
	v_mfma_f32_16x16x32_bf16 v[0:3], v[164:167], v[196:199], v[0:3]
	v_mfma_f32_16x16x32_bf16 v[40:43], v[160:163], v[176:179], v[40:43]
	v_mfma_f32_16x16x32_bf16 v[36:39], v[168:171], v[176:179], v[36:39]
	v_mfma_f32_16x16x32_bf16 v[28:31], v[160:163], v[184:187], v[28:31]
	v_mfma_f32_16x16x32_bf16 v[24:27], v[168:171], v[184:187], v[24:27]
	v_mfma_f32_16x16x32_bf16 v[20:23], v[160:163], v[192:195], v[20:23]
	v_mfma_f32_16x16x32_bf16 v[12:15], v[168:171], v[192:195], v[12:15]
	v_mfma_f32_16x16x32_bf16 v[4:7], v[160:163], v[200:203], v[4:7]
	v_mfma_f32_16x16x32_bf16 v[0:3], v[168:171], v[200:203], v[0:3]
	s_barrier
	s_add_i32 s28, 0, 0x18000
	s_add_i32 s29, 0, 0x1c000
	v_add_u32_e32 v152, s28, v141
	v_add_u32_e32 v168, s29, v141
	ds_read_b128 v[134:137], v152
	ds_read_b128 v[144:147], v152 offset:1024
	ds_read_b128 v[148:151], v152 offset:2048
	ds_read_b128 v[152:155], v152 offset:3072
	ds_read_b128 v[156:159], v168
	ds_read_b128 v[160:163], v168 offset:1024
	ds_read_b128 v[164:167], v168 offset:2048
	ds_read_b128 v[168:171], v168 offset:3072
	s_add_u32 s0, s24, 0xb0000
	s_addc_u32 s1, s25, 0
	s_mov_b32 m0, s35
	ds_read_b128 v[172:175], v143 offset:32768
	ds_read_b128 v[176:179], v143 offset:33792
	ds_read_b128 v[180:183], v143 offset:34816
	ds_read_b128 v[184:187], v143 offset:35840
	ds_read_b128 v[188:191], v143 offset:36864
	ds_read_b128 v[192:195], v143 offset:37888
	ds_read_b128 v[196:199], v143 offset:38912
	ds_read_b128 v[200:203], v143 offset:39936
	global_load_lds_dwordx4 v208, s[0:1]
	s_mov_b32 m0, s39
	s_nop 0
	global_load_lds_dwordx4 v128, s[0:1]
	s_waitcnt vmcnt(8)
	s_waitcnt lgkmcnt(0)
	s_barrier
	v_mfma_f32_16x16x32_bf16 v[124:127], v[134:137], v[172:175], v[124:127]
	v_mfma_f32_16x16x32_bf16 v[120:123], v[148:151], v[172:175], v[120:123]
	v_mfma_f32_16x16x32_bf16 v[116:119], v[134:137], v[180:183], v[116:119]
	v_mfma_f32_16x16x32_bf16 v[112:115], v[148:151], v[180:183], v[112:115]
	v_mfma_f32_16x16x32_bf16 v[108:111], v[134:137], v[188:191], v[108:111]
	v_mfma_f32_16x16x32_bf16 v[100:103], v[148:151], v[188:191], v[100:103]
	v_mfma_f32_16x16x32_bf16 v[92:95], v[134:137], v[196:199], v[92:95]
	v_mfma_f32_16x16x32_bf16 v[80:83], v[148:151], v[196:199], v[80:83]
	v_mfma_f32_16x16x32_bf16 v[124:127], v[144:147], v[176:179], v[124:127]
	v_mfma_f32_16x16x32_bf16 v[120:123], v[152:155], v[176:179], v[120:123]
	v_mfma_f32_16x16x32_bf16 v[116:119], v[144:147], v[184:187], v[116:119]
	v_mfma_f32_16x16x32_bf16 v[112:115], v[152:155], v[184:187], v[112:115]
	v_mfma_f32_16x16x32_bf16 v[108:111], v[144:147], v[192:195], v[108:111]
	v_mfma_f32_16x16x32_bf16 v[100:103], v[152:155], v[192:195], v[100:103]
	v_mfma_f32_16x16x32_bf16 v[92:95], v[144:147], v[200:203], v[92:95]
	v_mfma_f32_16x16x32_bf16 v[80:83], v[152:155], v[200:203], v[80:83]
	v_mfma_f32_16x16x32_bf16 v[104:107], v[156:159], v[172:175], v[104:107]
	v_mfma_f32_16x16x32_bf16 v[96:99], v[164:167], v[172:175], v[96:99]
	v_mfma_f32_16x16x32_bf16 v[88:91], v[156:159], v[180:183], v[88:91]
	v_mfma_f32_16x16x32_bf16 v[84:87], v[164:167], v[180:183], v[84:87]
	v_mfma_f32_16x16x32_bf16 v[76:79], v[156:159], v[188:191], v[76:79]
	v_mfma_f32_16x16x32_bf16 v[72:75], v[164:167], v[188:191], v[72:75]
	v_mfma_f32_16x16x32_bf16 v[68:71], v[156:159], v[196:199], v[68:71]
	v_mfma_f32_16x16x32_bf16 v[64:67], v[164:167], v[196:199], v[64:67]
	v_mfma_f32_16x16x32_bf16 v[104:107], v[160:163], v[176:179], v[104:107]
	v_mfma_f32_16x16x32_bf16 v[96:99], v[168:171], v[176:179], v[96:99]
	v_mfma_f32_16x16x32_bf16 v[88:91], v[160:163], v[184:187], v[88:91]
	v_mfma_f32_16x16x32_bf16 v[84:87], v[168:171], v[184:187], v[84:87]
	v_mfma_f32_16x16x32_bf16 v[76:79], v[160:163], v[192:195], v[76:79]
	v_mfma_f32_16x16x32_bf16 v[72:75], v[168:171], v[192:195], v[72:75]
	v_mfma_f32_16x16x32_bf16 v[68:71], v[160:163], v[200:203], v[68:71]
	v_mfma_f32_16x16x32_bf16 v[64:67], v[168:171], v[200:203], v[64:67]
	s_barrier
; #define PG8_STAGE(bufoff, gbase, voff) do { _Pragma("unroll") for (int _i = 0; _i < 2; ++_i) \
;         __builtin_amdgcn_global_load_lds((const unsigned*)((const char*)(gbase) + (voff)[_i]), (PG8_LAS unsigned*)(lds + (bufoff) + ldsw + _i * 8192), 16, 0, 0); } while (0)
; #define PG8_LDA(dst, b, h) do { _Pragma("unroll") for (int m = 0; m < 4; ++m) _Pragma("unroll") for (int k = 0; k < 2; ++k) dst[m][k] = *(const PG8_LAS bf16x8*)(lds + PG8_SA(b, h) + aoff + m * 2048 + k * 1024); } while (0)
; #define PG8_MMA(ai, bj, At, Bt) do { __builtin_amdgcn_s_setprio(1); _Pragma("unroll") for (int m = 0; m < 4; ++m) _Pragma("unroll") for (int n = 0; n < 2; ++n) _Pragma("unroll") for (int k = 0; k < 2; ++k) \
;         acc[ai][bj][m][n] = __builtin_amdgcn_mfma_f32_16x16x32_bf16(Bt[n][k], At[m][k], acc[ai][bj][m][n], 0, 0, 0); __builtin_amdgcn_s_setprio(0); } while (0)
; #define PG8_WAIT_V(n) asm volatile("s_waitcnt vmcnt(" #n ")" ::: "memory")
; #define PG8_WAIT_L(n) asm volatile("s_waitcnt lgkmcnt(" #n ")" ::: "memory")
; #define PG8_BAR __builtin_amdgcn_s_barrier()
; #define PG8_SCHED __builtin_amdgcn_sched_barrier(0)
; template <class Epi, class Sched, bool ALIGN_EPI = false, bool SP2 = false>
; __device__ __forceinline__ void gemm_phase(PG8_LAS unsigned char* lds, const Gemm g, const Sched& S, const Epi& E) {
;     ...
;             PG8_LDA(At, 1, 1); PG8_STAGE(PG8_SB(1, 0), b3, voffB); PG8_STAGE(PG8_SB(1, 1), b3 + hstepB, voffB); PG8_STAGE(PG8_SA(1, 0), a3, voffA);
;             PG8_WAIT_V(8); PG8_WAIT_L(0); PG8_BAR; PG8_MMA(1, 0, At, B0); PG8_MMA(1, 1, At, B1); PG8_BAR; PG8_SCHED;
;     ...
;         if constexpr (ALIGN_EPI) { if (wr == 0) PG8_BAR; }
	s_add_i32 s0, s28, s19
	v_lshl_add_u64 v[138:139], v[138:139], 0, s[10:11]
	s_mov_b32 m0, s0
	ds_read_b128 v[172:175], v143 offset:49152
	ds_read_b128 v[176:179], v143 offset:50176
	ds_read_b128 v[180:183], v143 offset:51200
	ds_read_b128 v[184:187], v143 offset:52224
	ds_read_b128 v[188:191], v143 offset:53248
	ds_read_b128 v[192:195], v143 offset:54272
	ds_read_b128 v[196:199], v143 offset:55296
	ds_read_b128 v[200:203], v143 offset:56320
	global_load_lds_dwordx4 v[138:139], off
	s_add_i32 m0, s0, 0x2000
	s_add_u32 s0, s22, 0xb0080
	v_lshl_add_u64 v[138:139], v[204:205], 0, s[10:11]
	s_addc_u32 s1, s23, 0
	s_add_i32 s22, s29, s19
	global_load_lds_dwordx4 v[138:139], off
	s_mov_b32 m0, s22
	s_nop 0
	global_load_lds_dwordx4 v208, s[0:1]
	s_add_i32 m0, s22, 0x2000
	s_nop 0
	global_load_lds_dwordx4 v128, s[0:1]
	v_lshl_add_u64 v[138:139], v[206:207], 0, s[10:11]
	s_mov_b32 m0, s44
	s_nop 0
	global_load_lds_dwordx4 v[138:139], off
	v_lshl_add_u64 v[138:139], v[210:211], 0, s[10:11]
	s_mov_b32 m0, s45
	s_nop 0
	global_load_lds_dwordx4 v[138:139], off
	s_waitcnt vmcnt(8)
	s_waitcnt lgkmcnt(0)
	s_barrier
	v_mfma_f32_16x16x32_bf16 v[60:63], v[134:137], v[172:175], v[60:63]
	v_mfma_f32_16x16x32_bf16 v[56:59], v[148:151], v[172:175], v[56:59]
	v_mfma_f32_16x16x32_bf16 v[52:55], v[134:137], v[180:183], v[52:55]
	v_mfma_f32_16x16x32_bf16 v[48:51], v[148:151], v[180:183], v[48:51]
	v_mfma_f32_16x16x32_bf16 v[44:47], v[134:137], v[188:191], v[44:47]
	v_mfma_f32_16x16x32_bf16 v[32:35], v[148:151], v[188:191], v[32:35]
	v_mfma_f32_16x16x32_bf16 v[16:19], v[134:137], v[196:199], v[16:19]
	v_mfma_f32_16x16x32_bf16 v[8:11], v[148:151], v[196:199], v[8:11]
	v_mfma_f32_16x16x32_bf16 v[60:63], v[144:147], v[176:179], v[60:63]
	v_mfma_f32_16x16x32_bf16 v[56:59], v[152:155], v[176:179], v[56:59]
	v_mfma_f32_16x16x32_bf16 v[52:55], v[144:147], v[184:187], v[52:55]
	v_mfma_f32_16x16x32_bf16 v[48:51], v[152:155], v[184:187], v[48:51]
	v_mfma_f32_16x16x32_bf16 v[44:47], v[144:147], v[192:195], v[44:47]
	v_mfma_f32_16x16x32_bf16 v[32:35], v[152:155], v[192:195], v[32:35]
	v_mfma_f32_16x16x32_bf16 v[16:19], v[144:147], v[200:203], v[16:19]
	v_mfma_f32_16x16x32_bf16 v[8:11], v[152:155], v[200:203], v[8:11]
	v_mfma_f32_16x16x32_bf16 v[40:43], v[156:159], v[172:175], v[40:43]
	v_mfma_f32_16x16x32_bf16 v[36:39], v[164:167], v[172:175], v[36:39]
	v_mfma_f32_16x16x32_bf16 v[28:31], v[156:159], v[180:183], v[28:31]
	v_mfma_f32_16x16x32_bf16 v[24:27], v[164:167], v[180:183], v[24:27]
	v_mfma_f32_16x16x32_bf16 v[20:23], v[156:159], v[188:191], v[20:23]
	v_mfma_f32_16x16x32_bf16 v[12:15], v[164:167], v[188:191], v[12:15]
	v_mfma_f32_16x16x32_bf16 v[4:7], v[156:159], v[196:199], v[4:7]
	v_mfma_f32_16x16x32_bf16 v[0:3], v[164:167], v[196:199], v[0:3]
	v_mfma_f32_16x16x32_bf16 v[40:43], v[160:163], v[176:179], v[40:43]
	v_mfma_f32_16x16x32_bf16 v[36:39], v[168:171], v[176:179], v[36:39]
	v_mfma_f32_16x16x32_bf16 v[28:31], v[160:163], v[184:187], v[28:31]
	v_mfma_f32_16x16x32_bf16 v[24:27], v[168:171], v[184:187], v[24:27]
	v_mfma_f32_16x16x32_bf16 v[20:23], v[160:163], v[192:195], v[20:23]
	v_mfma_f32_16x16x32_bf16 v[12:15], v[168:171], v[192:195], v[12:15]
	v_mfma_f32_16x16x32_bf16 v[4:7], v[160:163], v[200:203], v[4:7]
	v_mfma_f32_16x16x32_bf16 v[0:3], v[168:171], v[200:203], v[0:3]
	s_barrier
	s_add_i32 s49, s49, 2
	s_add_u32 s14, s14, 0x100
	s_addc_u32 s15, s15, 0
	s_cmp_gt_u32 s49, 41
	s_mov_b64 s[0:1], s[20:21]
	s_cbranch_scc0 .LBB0_1000
	s_and_b64 vcc, exec, s[8:9]
	s_cbranch_vccz .LBB0_1003
	s_barrier
